# merge4_all6
# speedup vs baseline: 1.0297x; 1.0247x over previous
; #define STAGE(P, BASE, br, kt) do { const char* _gb = (const char*)(BASE) + ((size_t)(br) * K + (size_t)(kt) * BK) * 2; \
;     __builtin_amdgcn_global_load_lds((const unsigned*)(_gb + loff0), (unsigned*)((char*)(P) + tid * 16), 16, 0, 0); \
;     __builtin_amdgcn_global_load_lds((const unsigned*)(_gb + (size_t)K * 128 + loff0), (unsigned*)((char*)(P) + tid * 16 + 8192), 16, 0, 0); } while (0)
; #define LDA(dst, b, h) for (int m = 0; m < 4; ++m) { \
;     dst[m][0] = *reinterpret_cast<const bf16x8*>((char*)SA(b, h) + aoff0 + m * 2048); \
;     dst[m][1] = *reinterpret_cast<const bf16x8*>((char*)SA(b, h) + aoff1 + m * 2048); }
; #define LDB(dst, b, h) for (int n = 0; n < 2; ++n) { \
;     dst[n][0] = *reinterpret_cast<const bf16x8*>((char*)SB(b, h) + boff0 + n * 256); \
;     dst[n][1] = *reinterpret_cast<const bf16x8*>((char*)SB(b, h) + boff1 + n * 256); }
; #define MMA(ai, bj, At, Btf) do { __builtin_amdgcn_s_setprio(1); \
;     for (int m = 0; m < 4; ++m) for (int n = 0; n < 2; ++n) for (int k = 0; k < 2; ++k) \
;       acc[ai][bj][m][n] = __builtin_amdgcn_mfma_f32_16x16x32_bf16(Btf[n][k], At[m][k], acc[ai][bj][m][n], 0, 0, 0); \
;     __builtin_amdgcn_s_setprio(0); } while (0)
; #define WAIT_V(n) asm volatile("s_waitcnt vmcnt(" #n ")" ::: "memory")
; #define WAIT_L(n) asm volatile("s_waitcnt lgkmcnt(" #n ")" ::: "memory")
; #define BAR __builtin_amdgcn_s_barrier()
; #define SCHED __builtin_amdgcn_sched_barrier(0)
; template <int EPI> ...
;     ...
;   WAIT_V(4); BAR;
;   STAGE(SB(1, 0), Bt, bcol, 1); STAGE(SA(1, 0), A, brow, 1); STAGE(SB(1, 1), Bt, bcol + HALF, 1);
;   WAIT_V(6); BAR;
;   for (int t = 0; t < nt - 2; t += 2) {
;     LDB(B0, 0, 0); SCHED; LDA(At, 0, 0); STAGE(SA(1, 1), A, brow + HALF, t + 1);
;     WAIT_L(8); BAR; WAIT_L(0); MMA(0, 0, At, B0); BAR; SCHED;
;     LDB(B1, 0, 1); STAGE(SB(0, 0), Bt, bcol, t + 2);
;     BAR; WAIT_L(0); MMA(0, 1, At, B1); BAR;
;     LDA(At, 0, 1); STAGE(SA(0, 0), A, brow, t + 2);
;     BAR; WAIT_L(0); MMA(1, 0, At, B0); BAR; SCHED;
;     STAGE(SB(0, 1), Bt, bcol + HALF, t + 2);
;     WAIT_V(6); BAR; MMA(1, 1, At, B1); BAR;
.LBB0_276:
	s_or_b64 exec, exec, s[72:73]
	v_readfirstlane_b32 s67, v144
	v_lshl_add_u64 v[6:7], v[0:1], 0, s[12:13]
	s_mov_b32 m0, s67
	v_readfirstlane_b32 s67, v145
	s_waitcnt vmcnt(2)
	s_barrier
	global_load_lds_dwordx4 v[6:7], off
	v_lshl_add_u64 v[0:1], v[0:1], 0, s[16:17]
	s_mov_b32 m0, s67
	v_readfirstlane_b32 s67, v146
	global_load_lds_dwordx4 v[0:1], off
	v_lshl_add_u64 v[0:1], v[2:3], 0, s[12:13]
	s_mov_b32 m0, s67
	v_readfirstlane_b32 s67, v147
	global_load_lds_dwordx4 v[0:1], off
	v_lshl_add_u64 v[0:1], v[2:3], 0, s[16:17]
	s_mov_b32 m0, s67
	v_readfirstlane_b32 s67, v148
	global_load_lds_dwordx4 v[0:1], off
	v_lshl_add_u64 v[0:1], v[4:5], 0, s[12:13]
	s_mov_b32 m0, s67
	v_readfirstlane_b32 s67, v149
	global_load_lds_dwordx4 v[0:1], off
	v_lshl_add_u64 v[0:1], v[4:5], 0, s[16:17]
	s_mov_b32 m0, s67
	s_add_u32 s70, s6, s70
	global_load_lds_dwordx4 v[0:1], off
	v_mov_b32_e32 v0, 0
	s_addc_u32 s71, s7, s71
	s_mov_b32 s67, -2
	v_mov_b32_e32 v1, v0
	v_mov_b32_e32 v2, v0
	v_mov_b32_e32 v3, v0
	v_mov_b32_e32 v4, v0
	v_mov_b32_e32 v5, v0
	v_mov_b32_e32 v6, v0
	v_mov_b32_e32 v7, v0
	s_waitcnt vmcnt(6)
	s_barrier
.LBB0_277:
	ds_read_b128 v[162:165], v153
	ds_read_b128 v[166:169], v153 offset:256
	ds_read_b128 v[170:173], v154
	ds_read_b128 v[174:177], v154 offset:256
	v_lshl_add_u64 v[226:227], s[70:71], 0, v[130:131]
	v_readfirstlane_b32 s72, v151
	v_lshl_add_u64 v[210:211], v[226:227], 0, s[18:19]
	s_mov_b32 m0, s72
	v_readfirstlane_b32 s72, v152
	ds_read_b128 v[178:181], v150
	ds_read_b128 v[182:185], v150 offset:1024
	ds_read_b128 v[186:189], v150 offset:2048
	ds_read_b128 v[190:193], v150 offset:3072
	ds_read_b128 v[194:197], v150 offset:4096
	ds_read_b128 v[198:201], v150 offset:5120
	ds_read_b128 v[202:205], v150 offset:6144
	ds_read_b128 v[206:209], v150 offset:7168
	global_load_lds_dwordx4 v[210:211], off
	v_lshl_add_u64 v[210:211], v[226:227], 0, s[20:21]
	s_mov_b32 m0, s72
	s_nop 0
	global_load_lds_dwordx4 v[210:211], off
	s_waitcnt lgkmcnt(8)
	ds_read_b128 v[210:213], v155
	ds_read_b128 v[214:217], v155 offset:256
	ds_read_b128 v[218:221], v156
	ds_read_b128 v[222:225], v156 offset:256
	s_barrier
	s_waitcnt lgkmcnt(0)
	s_setprio 1
	s_waitcnt lgkmcnt(0)
	v_mfma_f32_16x16x32_bf16 v[124:127], v[162:165], v[178:181], v[124:127]
	v_mfma_f32_16x16x32_bf16 v[120:123], v[166:169], v[178:181], v[120:123]
	v_mfma_f32_16x16x32_bf16 v[116:119], v[162:165], v[186:189], v[116:119]
	v_mfma_f32_16x16x32_bf16 v[112:115], v[166:169], v[186:189], v[112:115]
	v_mfma_f32_16x16x32_bf16 v[108:111], v[162:165], v[194:197], v[108:111]
	v_mfma_f32_16x16x32_bf16 v[104:107], v[166:169], v[194:197], v[104:107]
	v_mfma_f32_16x16x32_bf16 v[100:103], v[162:165], v[202:205], v[100:103]
	v_mfma_f32_16x16x32_bf16 v[96:99], v[166:169], v[202:205], v[96:99]
	v_mfma_f32_16x16x32_bf16 v[124:127], v[170:173], v[182:185], v[124:127]
	v_mfma_f32_16x16x32_bf16 v[120:123], v[174:177], v[182:185], v[120:123]
	v_mfma_f32_16x16x32_bf16 v[116:119], v[170:173], v[190:193], v[116:119]
	v_mfma_f32_16x16x32_bf16 v[112:115], v[174:177], v[190:193], v[112:115]
	v_mfma_f32_16x16x32_bf16 v[108:111], v[170:173], v[198:201], v[108:111]
	v_mfma_f32_16x16x32_bf16 v[104:107], v[174:177], v[198:201], v[104:107]
	v_mfma_f32_16x16x32_bf16 v[100:103], v[170:173], v[206:209], v[100:103]
	v_mfma_f32_16x16x32_bf16 v[96:99], v[174:177], v[206:209], v[96:99]
	s_setprio 0
	s_waitcnt lgkmcnt(0)
	s_setprio 1
	s_waitcnt lgkmcnt(0)
	v_mfma_f32_16x16x32_bf16 v[92:95], v[210:213], v[178:181], v[92:95]
	v_mfma_f32_16x16x32_bf16 v[88:91], v[214:217], v[178:181], v[88:91]
	v_mfma_f32_16x16x32_bf16 v[84:87], v[210:213], v[186:189], v[84:87]
	v_mfma_f32_16x16x32_bf16 v[80:83], v[214:217], v[186:189], v[80:83]
	v_mfma_f32_16x16x32_bf16 v[76:79], v[210:213], v[194:197], v[76:79]
	v_mfma_f32_16x16x32_bf16 v[72:75], v[214:217], v[194:197], v[72:75]
	v_mfma_f32_16x16x32_bf16 v[68:71], v[210:213], v[202:205], v[68:71]
	v_mfma_f32_16x16x32_bf16 v[64:67], v[214:217], v[202:205], v[64:67]
	v_mfma_f32_16x16x32_bf16 v[92:95], v[218:221], v[182:185], v[92:95]
	v_mfma_f32_16x16x32_bf16 v[88:91], v[222:225], v[182:185], v[88:91]
	v_mfma_f32_16x16x32_bf16 v[84:87], v[218:221], v[190:193], v[84:87]
	v_mfma_f32_16x16x32_bf16 v[80:83], v[222:225], v[190:193], v[80:83]
	v_mfma_f32_16x16x32_bf16 v[76:79], v[218:221], v[198:201], v[76:79]
	v_mfma_f32_16x16x32_bf16 v[72:75], v[222:225], v[198:201], v[72:75]
	v_mfma_f32_16x16x32_bf16 v[68:71], v[218:221], v[206:209], v[68:71]
	v_mfma_f32_16x16x32_bf16 v[64:67], v[222:225], v[206:209], v[64:67]
	s_setprio 0
	s_barrier
	v_lshl_add_u64 v[228:229], s[68:69], 0, v[130:131]
	v_readfirstlane_b32 s72, v136
	v_lshl_add_u64 v[230:231], v[228:229], 0, s[22:23]
	s_mov_b32 m0, s72
	v_readfirstlane_b32 s72, v137
	global_load_lds_dwordx4 v[230:231], off
	v_lshl_add_u64 v[230:231], v[228:229], 0, s[26:27]
	s_mov_b32 m0, s72
	s_nop 0
	global_load_lds_dwordx4 v[230:231], off
	v_readfirstlane_b32 s72, v138
	v_lshl_add_u64 v[230:231], v[226:227], 0, s[28:29]
	s_mov_b32 m0, s72
	v_readfirstlane_b32 s72, v139
	ds_read_b128 v[178:181], v150 offset:16384
	ds_read_b128 v[182:185], v150 offset:17408
	ds_read_b128 v[186:189], v150 offset:18432
	ds_read_b128 v[190:193], v150 offset:19456
	ds_read_b128 v[194:197], v150 offset:20480
	ds_read_b128 v[198:201], v150 offset:21504
	ds_read_b128 v[202:205], v150 offset:22528
	ds_read_b128 v[206:209], v150 offset:23552
	global_load_lds_dwordx4 v[230:231], off
	v_lshl_add_u64 v[230:231], v[226:227], 0, s[30:31]
	s_mov_b32 m0, s72
	s_nop 0
	global_load_lds_dwordx4 v[230:231], off
	v_readfirstlane_b32 s72, v140
	v_lshl_add_u64 v[246:247], v[228:229], 0, s[36:37]
	s_mov_b32 m0, s72
	v_readfirstlane_b32 s72, v141
	global_load_lds_dwordx4 v[246:247], off
	v_lshl_add_u64 v[246:247], v[228:229], 0, s[38:39]
	s_mov_b32 m0, s72
	s_nop 0
	global_load_lds_dwordx4 v[246:247], off
	s_waitcnt vmcnt(6)
	s_barrier
; #define STAGE(P, BASE, br, kt) do { const char* _gb = (const char*)(BASE) + ((size_t)(br) * K + (size_t)(kt) * BK) * 2; \
;     __builtin_amdgcn_global_load_lds((const unsigned*)(_gb + loff0), (unsigned*)((char*)(P) + tid * 16), 16, 0, 0); \
;     __builtin_amdgcn_global_load_lds((const unsigned*)(_gb + (size_t)K * 128 + loff0), (unsigned*)((char*)(P) + tid * 16 + 8192), 16, 0, 0); } while (0)
; #define LDA(dst, b, h) for (int m = 0; m < 4; ++m) { \
;     dst[m][0] = *reinterpret_cast<const bf16x8*>((char*)SA(b, h) + aoff0 + m * 2048); \
;     dst[m][1] = *reinterpret_cast<const bf16x8*>((char*)SA(b, h) + aoff1 + m * 2048); }
; #define LDB(dst, b, h) for (int n = 0; n < 2; ++n) { \
;     dst[n][0] = *reinterpret_cast<const bf16x8*>((char*)SB(b, h) + boff0 + n * 256); \
;     dst[n][1] = *reinterpret_cast<const bf16x8*>((char*)SB(b, h) + boff1 + n * 256); }
; #define MMA(ai, bj, At, Btf) do { __builtin_amdgcn_s_setprio(1); \
;     for (int m = 0; m < 4; ++m) for (int n = 0; n < 2; ++n) for (int k = 0; k < 2; ++k) \
;       acc[ai][bj][m][n] = __builtin_amdgcn_mfma_f32_16x16x32_bf16(Btf[n][k], At[m][k], acc[ai][bj][m][n], 0, 0, 0); \
;     __builtin_amdgcn_s_setprio(0); } while (0)
; #define WAIT_V(n) asm volatile("s_waitcnt vmcnt(" #n ")" ::: "memory")
; #define WAIT_L(n) asm volatile("s_waitcnt lgkmcnt(" #n ")" ::: "memory")
; #define BAR __builtin_amdgcn_s_barrier()
; #define SCHED __builtin_amdgcn_sched_barrier(0)
; template <int EPI> ...
;     ...
;     BAR; WAIT_L(0); MMA(1, 0, At, B0); BAR; SCHED;
;     STAGE(SB(0, 1), Bt, bcol + HALF, t + 2);
;     WAIT_V(6); BAR; MMA(1, 1, At, B1); BAR;
;     LDB(B0, 1, 0); SCHED; LDA(At, 1, 0); STAGE(SA(0, 1), A, brow + HALF, t + 2);
;     WAIT_L(8); BAR; WAIT_L(0); MMA(0, 0, At, B0); BAR; SCHED;
;     LDB(B1, 1, 1); STAGE(SB(1, 0), Bt, bcol, t + 3);
;     BAR; WAIT_L(0); MMA(0, 1, At, B1); BAR;
	s_waitcnt lgkmcnt(0)
	s_setprio 1
	s_waitcnt lgkmcnt(0)
	v_mfma_f32_16x16x32_bf16 v[60:63], v[162:165], v[178:181], v[60:63]
	v_mfma_f32_16x16x32_bf16 v[56:59], v[166:169], v[178:181], v[56:59]
	v_mfma_f32_16x16x32_bf16 v[52:55], v[162:165], v[186:189], v[52:55]
	v_mfma_f32_16x16x32_bf16 v[48:51], v[166:169], v[186:189], v[48:51]
	v_mfma_f32_16x16x32_bf16 v[44:47], v[162:165], v[194:197], v[44:47]
	v_mfma_f32_16x16x32_bf16 v[40:43], v[166:169], v[194:197], v[40:43]
	v_mfma_f32_16x16x32_bf16 v[36:39], v[162:165], v[202:205], v[36:39]
	v_mfma_f32_16x16x32_bf16 v[32:35], v[166:169], v[202:205], v[32:35]
	v_mfma_f32_16x16x32_bf16 v[60:63], v[170:173], v[182:185], v[60:63]
	v_mfma_f32_16x16x32_bf16 v[56:59], v[174:177], v[182:185], v[56:59]
	v_mfma_f32_16x16x32_bf16 v[52:55], v[170:173], v[190:193], v[52:55]
	v_mfma_f32_16x16x32_bf16 v[48:51], v[174:177], v[190:193], v[48:51]
	v_mfma_f32_16x16x32_bf16 v[44:47], v[170:173], v[198:201], v[44:47]
	v_mfma_f32_16x16x32_bf16 v[40:43], v[174:177], v[198:201], v[40:43]
	v_mfma_f32_16x16x32_bf16 v[36:39], v[170:173], v[206:209], v[36:39]
	v_mfma_f32_16x16x32_bf16 v[32:35], v[174:177], v[206:209], v[32:35]
	s_setprio 0
	s_setprio 1
	v_mfma_f32_16x16x32_bf16 v[28:31], v[210:213], v[178:181], v[28:31]
	v_mfma_f32_16x16x32_bf16 v[24:27], v[214:217], v[178:181], v[24:27]
	v_mfma_f32_16x16x32_bf16 v[20:23], v[210:213], v[186:189], v[20:23]
	v_mfma_f32_16x16x32_bf16 v[16:19], v[214:217], v[186:189], v[16:19]
	v_mfma_f32_16x16x32_bf16 v[12:15], v[210:213], v[194:197], v[12:15]
	v_mfma_f32_16x16x32_bf16 v[8:11], v[214:217], v[194:197], v[8:11]
	v_mfma_f32_16x16x32_bf16 v[4:7], v[210:213], v[202:205], v[4:7]
	v_mfma_f32_16x16x32_bf16 v[0:3], v[214:217], v[202:205], v[0:3]
	v_mfma_f32_16x16x32_bf16 v[28:31], v[218:221], v[182:185], v[28:31]
	v_mfma_f32_16x16x32_bf16 v[24:27], v[222:225], v[182:185], v[24:27]
	v_mfma_f32_16x16x32_bf16 v[20:23], v[218:221], v[190:193], v[20:23]
	v_mfma_f32_16x16x32_bf16 v[16:19], v[222:225], v[190:193], v[16:19]
	v_mfma_f32_16x16x32_bf16 v[12:15], v[218:221], v[198:201], v[12:15]
	v_mfma_f32_16x16x32_bf16 v[8:11], v[222:225], v[198:201], v[8:11]
	v_mfma_f32_16x16x32_bf16 v[4:7], v[218:221], v[206:209], v[4:7]
	v_mfma_f32_16x16x32_bf16 v[0:3], v[222:225], v[206:209], v[0:3]
	s_setprio 0
	s_barrier
	ds_read_b128 v[162:165], v157
	ds_read_b128 v[166:169], v157 offset:256
	ds_read_b128 v[170:173], v158
	ds_read_b128 v[174:177], v158 offset:256
	v_readfirstlane_b32 s72, v142
	v_lshl_add_u64 v[210:211], v[226:227], 0, s[46:47]
	s_mov_b32 m0, s72
	v_readfirstlane_b32 s72, v143
	ds_read_b128 v[178:181], v150 offset:32768
	ds_read_b128 v[182:185], v150 offset:33792
	ds_read_b128 v[186:189], v150 offset:34816
	ds_read_b128 v[190:193], v150 offset:35840
	ds_read_b128 v[194:197], v150 offset:36864
	ds_read_b128 v[198:201], v150 offset:37888
	ds_read_b128 v[202:205], v150 offset:38912
	ds_read_b128 v[206:209], v150 offset:39936
	global_load_lds_dwordx4 v[210:211], off
	v_lshl_add_u64 v[210:211], v[226:227], 0, s[48:49]
	s_mov_b32 m0, s72
	s_nop 0
	global_load_lds_dwordx4 v[210:211], off
	s_waitcnt lgkmcnt(8)
	ds_read_b128 v[210:213], v159
	ds_read_b128 v[214:217], v159 offset:256
	ds_read_b128 v[218:221], v160
	ds_read_b128 v[222:225], v160 offset:256
	s_barrier
	s_waitcnt lgkmcnt(0)
	s_setprio 1
	s_waitcnt lgkmcnt(0)
	v_mfma_f32_16x16x32_bf16 v[124:127], v[162:165], v[178:181], v[124:127]
	v_mfma_f32_16x16x32_bf16 v[120:123], v[166:169], v[178:181], v[120:123]
	v_mfma_f32_16x16x32_bf16 v[116:119], v[162:165], v[186:189], v[116:119]
	v_mfma_f32_16x16x32_bf16 v[112:115], v[166:169], v[186:189], v[112:115]
	v_mfma_f32_16x16x32_bf16 v[108:111], v[162:165], v[194:197], v[108:111]
	v_mfma_f32_16x16x32_bf16 v[104:107], v[166:169], v[194:197], v[104:107]
	v_mfma_f32_16x16x32_bf16 v[100:103], v[162:165], v[202:205], v[100:103]
	v_mfma_f32_16x16x32_bf16 v[96:99], v[166:169], v[202:205], v[96:99]
	v_mfma_f32_16x16x32_bf16 v[124:127], v[170:173], v[182:185], v[124:127]
	v_mfma_f32_16x16x32_bf16 v[120:123], v[174:177], v[182:185], v[120:123]
	v_mfma_f32_16x16x32_bf16 v[116:119], v[170:173], v[190:193], v[116:119]
	v_mfma_f32_16x16x32_bf16 v[112:115], v[174:177], v[190:193], v[112:115]
	v_mfma_f32_16x16x32_bf16 v[108:111], v[170:173], v[198:201], v[108:111]
	v_mfma_f32_16x16x32_bf16 v[104:107], v[174:177], v[198:201], v[104:107]
	v_mfma_f32_16x16x32_bf16 v[100:103], v[170:173], v[206:209], v[100:103]
	v_mfma_f32_16x16x32_bf16 v[96:99], v[174:177], v[206:209], v[96:99]
	s_setprio 0
	s_waitcnt lgkmcnt(0)
	s_setprio 1
	s_waitcnt lgkmcnt(0)
	v_mfma_f32_16x16x32_bf16 v[92:95], v[210:213], v[178:181], v[92:95]
	v_mfma_f32_16x16x32_bf16 v[88:91], v[214:217], v[178:181], v[88:91]
	v_mfma_f32_16x16x32_bf16 v[84:87], v[210:213], v[186:189], v[84:87]
	v_mfma_f32_16x16x32_bf16 v[80:83], v[214:217], v[186:189], v[80:83]
	v_mfma_f32_16x16x32_bf16 v[76:79], v[210:213], v[194:197], v[76:79]
	v_mfma_f32_16x16x32_bf16 v[72:75], v[214:217], v[194:197], v[72:75]
	v_mfma_f32_16x16x32_bf16 v[68:71], v[210:213], v[202:205], v[68:71]
	v_mfma_f32_16x16x32_bf16 v[64:67], v[214:217], v[202:205], v[64:67]
	v_mfma_f32_16x16x32_bf16 v[92:95], v[218:221], v[182:185], v[92:95]
	v_mfma_f32_16x16x32_bf16 v[88:91], v[222:225], v[182:185], v[88:91]
	v_mfma_f32_16x16x32_bf16 v[84:87], v[218:221], v[190:193], v[84:87]
	v_mfma_f32_16x16x32_bf16 v[80:83], v[222:225], v[190:193], v[80:83]
	v_mfma_f32_16x16x32_bf16 v[76:79], v[218:221], v[198:201], v[76:79]
	v_mfma_f32_16x16x32_bf16 v[72:75], v[222:225], v[198:201], v[72:75]
	v_mfma_f32_16x16x32_bf16 v[68:71], v[218:221], v[206:209], v[68:71]
	v_mfma_f32_16x16x32_bf16 v[64:67], v[222:225], v[206:209], v[64:67]
	s_setprio 0
	s_barrier
; #define STAGE(P, BASE, br, kt) do { const char* _gb = (const char*)(BASE) + ((size_t)(br) * K + (size_t)(kt) * BK) * 2; \
;     __builtin_amdgcn_global_load_lds((const unsigned*)(_gb + loff0), (unsigned*)((char*)(P) + tid * 16), 16, 0, 0); \
;     __builtin_amdgcn_global_load_lds((const unsigned*)(_gb + (size_t)K * 128 + loff0), (unsigned*)((char*)(P) + tid * 16 + 8192), 16, 0, 0); } while (0)
; #define LDA(dst, b, h) for (int m = 0; m < 4; ++m) { \
;     dst[m][0] = *reinterpret_cast<const bf16x8*>((char*)SA(b, h) + aoff0 + m * 2048); \
;     dst[m][1] = *reinterpret_cast<const bf16x8*>((char*)SA(b, h) + aoff1 + m * 2048); }
; #define LDB(dst, b, h) for (int n = 0; n < 2; ++n) { \
;     dst[n][0] = *reinterpret_cast<const bf16x8*>((char*)SB(b, h) + boff0 + n * 256); \
;     dst[n][1] = *reinterpret_cast<const bf16x8*>((char*)SB(b, h) + boff1 + n * 256); }
; #define MMA(ai, bj, At, Btf) do { __builtin_amdgcn_s_setprio(1); \
;     for (int m = 0; m < 4; ++m) for (int n = 0; n < 2; ++n) for (int k = 0; k < 2; ++k) \
;       acc[ai][bj][m][n] = __builtin_amdgcn_mfma_f32_16x16x32_bf16(Btf[n][k], At[m][k], acc[ai][bj][m][n], 0, 0, 0); \
;     __builtin_amdgcn_s_setprio(0); } while (0)
; #define WAIT_V(n) asm volatile("s_waitcnt vmcnt(" #n ")" ::: "memory")
; #define WAIT_L(n) asm volatile("s_waitcnt lgkmcnt(" #n ")" ::: "memory")
; #define BAR __builtin_amdgcn_s_barrier()
; #define SCHED __builtin_amdgcn_sched_barrier(0)
; template <int EPI> ...
;     ...
;     LDB(B1, 1, 1); STAGE(SB(1, 0), Bt, bcol, t + 3);
;     BAR; WAIT_L(0); MMA(0, 1, At, B1); BAR;
;     LDA(At, 1, 1); STAGE(SA(1, 0), A, brow, t + 3);
;     BAR; WAIT_L(0); MMA(1, 0, At, B0); BAR; SCHED;
;     STAGE(SB(1, 1), Bt, bcol + HALF, t + 3);
;     WAIT_V(6); BAR; MMA(1, 1, At, B1); BAR;
;   }
;   { LDB(B0, 0, 0); LDA(At, 0, 0); STAGE(SA(1, 1), A, brow + HALF, nt - 1);
;     BAR; WAIT_L(0); MMA(0, 0, At, B0); BAR;
	v_readfirstlane_b32 s72, v144
	v_lshl_add_u64 v[230:231], v[228:229], 0, s[50:51]
	s_mov_b32 m0, s72
	v_readfirstlane_b32 s72, v145
	global_load_lds_dwordx4 v[230:231], off
	v_lshl_add_u64 v[230:231], v[228:229], 0, s[52:53]
	s_mov_b32 m0, s72
	s_nop 0
	global_load_lds_dwordx4 v[230:231], off
	v_readfirstlane_b32 s72, v146
	v_lshl_add_u64 v[230:231], v[226:227], 0, s[54:55]
	s_mov_b32 m0, s72
	v_readfirstlane_b32 s72, v147
	ds_read_b128 v[178:181], v150 offset:49152
	ds_read_b128 v[182:185], v150 offset:50176
	ds_read_b128 v[186:189], v150 offset:51200
	ds_read_b128 v[190:193], v150 offset:52224
	ds_read_b128 v[194:197], v150 offset:53248
	ds_read_b128 v[198:201], v150 offset:54272
	ds_read_b128 v[202:205], v150 offset:55296
	ds_read_b128 v[206:209], v150 offset:56320
	global_load_lds_dwordx4 v[230:231], off
	v_lshl_add_u64 v[226:227], v[226:227], 0, s[56:57]
	s_mov_b32 m0, s72
	s_nop 0
	global_load_lds_dwordx4 v[226:227], off
	v_readfirstlane_b32 s72, v148
	v_lshl_add_u64 v[246:247], v[228:229], 0, s[58:59]
	s_mov_b32 m0, s72
	v_readfirstlane_b32 s72, v149
	global_load_lds_dwordx4 v[246:247], off
	v_lshl_add_u64 v[246:247], v[228:229], 0, s[60:61]
	s_mov_b32 m0, s72
	s_nop 0
	global_load_lds_dwordx4 v[246:247], off
	s_waitcnt vmcnt(6)
	s_barrier
	s_waitcnt lgkmcnt(0)
	s_setprio 1
	s_waitcnt lgkmcnt(0)
	v_mfma_f32_16x16x32_bf16 v[60:63], v[162:165], v[178:181], v[60:63]
	v_mfma_f32_16x16x32_bf16 v[56:59], v[166:169], v[178:181], v[56:59]
	v_mfma_f32_16x16x32_bf16 v[52:55], v[162:165], v[186:189], v[52:55]
	v_mfma_f32_16x16x32_bf16 v[48:51], v[166:169], v[186:189], v[48:51]
	v_mfma_f32_16x16x32_bf16 v[44:47], v[162:165], v[194:197], v[44:47]
	v_mfma_f32_16x16x32_bf16 v[40:43], v[166:169], v[194:197], v[40:43]
	v_mfma_f32_16x16x32_bf16 v[36:39], v[162:165], v[202:205], v[36:39]
	v_mfma_f32_16x16x32_bf16 v[32:35], v[166:169], v[202:205], v[32:35]
	v_mfma_f32_16x16x32_bf16 v[60:63], v[170:173], v[182:185], v[60:63]
	v_mfma_f32_16x16x32_bf16 v[56:59], v[174:177], v[182:185], v[56:59]
	v_mfma_f32_16x16x32_bf16 v[52:55], v[170:173], v[190:193], v[52:55]
	v_mfma_f32_16x16x32_bf16 v[48:51], v[174:177], v[190:193], v[48:51]
	v_mfma_f32_16x16x32_bf16 v[44:47], v[170:173], v[198:201], v[44:47]
	v_mfma_f32_16x16x32_bf16 v[40:43], v[174:177], v[198:201], v[40:43]
	v_mfma_f32_16x16x32_bf16 v[36:39], v[170:173], v[206:209], v[36:39]
	v_mfma_f32_16x16x32_bf16 v[32:35], v[174:177], v[206:209], v[32:35]
	s_setprio 0
	s_setprio 1
	v_mfma_f32_16x16x32_bf16 v[28:31], v[210:213], v[178:181], v[28:31]
	v_mfma_f32_16x16x32_bf16 v[24:27], v[214:217], v[178:181], v[24:27]
	v_mfma_f32_16x16x32_bf16 v[20:23], v[210:213], v[186:189], v[20:23]
	v_mfma_f32_16x16x32_bf16 v[16:19], v[214:217], v[186:189], v[16:19]
	v_mfma_f32_16x16x32_bf16 v[12:15], v[210:213], v[194:197], v[12:15]
	v_mfma_f32_16x16x32_bf16 v[8:11], v[214:217], v[194:197], v[8:11]
	v_mfma_f32_16x16x32_bf16 v[4:7], v[210:213], v[202:205], v[4:7]
	v_mfma_f32_16x16x32_bf16 v[0:3], v[214:217], v[202:205], v[0:3]
	v_mfma_f32_16x16x32_bf16 v[28:31], v[218:221], v[182:185], v[28:31]
	v_mfma_f32_16x16x32_bf16 v[24:27], v[222:225], v[182:185], v[24:27]
	v_mfma_f32_16x16x32_bf16 v[20:23], v[218:221], v[190:193], v[20:23]
	v_mfma_f32_16x16x32_bf16 v[16:19], v[222:225], v[190:193], v[16:19]
	v_mfma_f32_16x16x32_bf16 v[12:15], v[218:221], v[198:201], v[12:15]
	v_mfma_f32_16x16x32_bf16 v[8:11], v[222:225], v[198:201], v[8:11]
	v_mfma_f32_16x16x32_bf16 v[4:7], v[218:221], v[206:209], v[4:7]
	v_mfma_f32_16x16x32_bf16 v[0:3], v[222:225], v[206:209], v[0:3]
	s_setprio 0
	s_add_i32 s67, s67, 2
	s_add_u32 s70, s70, 0x100
	s_addc_u32 s71, s71, 0
	s_add_u32 s68, s68, 0x100
	s_addc_u32 s69, s69, 0
	s_cmp_lt_u32 s67, 28
	s_barrier
	s_cbranch_scc1 .LBB0_277
	v_readfirstlane_b32 s67, v151
	v_lshl_add_u64 v[210:211], v[132:133], 0, s[62:63]
	s_mov_b32 m0, s67
	v_readfirstlane_b32 s67, v152
	ds_read_b128 v[162:165], v153
	ds_read_b128 v[166:169], v153 offset:256
	ds_read_b128 v[170:173], v154
	ds_read_b128 v[174:177], v154 offset:256
	ds_read_b128 v[178:181], v150
	ds_read_b128 v[182:185], v150 offset:1024
	ds_read_b128 v[186:189], v150 offset:2048
	ds_read_b128 v[190:193], v150 offset:3072
	ds_read_b128 v[194:197], v150 offset:4096
	ds_read_b128 v[198:201], v150 offset:5120
	ds_read_b128 v[202:205], v150 offset:6144
	ds_read_b128 v[206:209], v150 offset:7168
	global_load_lds_dwordx4 v[210:211], off
	v_lshl_add_u64 v[132:133], v[132:133], 0, s[64:65]
	s_mov_b32 m0, s67
	s_nop 0
	global_load_lds_dwordx4 v[132:133], off
	s_barrier
	s_waitcnt lgkmcnt(0)
	s_setprio 1
	s_waitcnt lgkmcnt(0)
	v_mfma_f32_16x16x32_bf16 v[124:127], v[162:165], v[178:181], v[124:127]
	v_mfma_f32_16x16x32_bf16 v[116:119], v[162:165], v[186:189], v[116:119]
	v_mfma_f32_16x16x32_bf16 v[108:111], v[162:165], v[194:197], v[108:111]
	v_mfma_f32_16x16x32_bf16 v[100:103], v[162:165], v[202:205], v[100:103]
	v_mfma_f32_16x16x32_bf16 v[124:127], v[170:173], v[182:185], v[124:127]
	v_mfma_f32_16x16x32_bf16 v[120:123], v[166:169], v[178:181], v[120:123]
	v_mfma_f32_16x16x32_bf16 v[116:119], v[170:173], v[190:193], v[116:119]
	v_mfma_f32_16x16x32_bf16 v[112:115], v[166:169], v[186:189], v[112:115]
	v_mfma_f32_16x16x32_bf16 v[108:111], v[170:173], v[198:201], v[108:111]
	v_mfma_f32_16x16x32_bf16 v[104:107], v[166:169], v[194:197], v[104:107]
	v_mfma_f32_16x16x32_bf16 v[100:103], v[170:173], v[206:209], v[100:103]
	v_mfma_f32_16x16x32_bf16 v[96:99], v[166:169], v[202:205], v[96:99]
	v_mfma_f32_16x16x32_bf16 v[210:213], v[174:177], v[182:185], v[120:123]
	v_mfma_f32_16x16x32_bf16 v[214:217], v[174:177], v[190:193], v[112:115]
	v_mfma_f32_16x16x32_bf16 v[218:221], v[174:177], v[198:201], v[104:107]
	v_mfma_f32_16x16x32_bf16 v[222:225], v[174:177], v[206:209], v[96:99]
	s_setprio 0
	s_barrier
; #define LDA(dst, b, h) for (int m = 0; m < 4; ++m) { \
;     dst[m][0] = *reinterpret_cast<const bf16x8*>((char*)SA(b, h) + aoff0 + m * 2048); \
;     dst[m][1] = *reinterpret_cast<const bf16x8*>((char*)SA(b, h) + aoff1 + m * 2048); }
; #define LDB(dst, b, h) for (int n = 0; n < 2; ++n) { \
;     dst[n][0] = *reinterpret_cast<const bf16x8*>((char*)SB(b, h) + boff0 + n * 256); \
;     dst[n][1] = *reinterpret_cast<const bf16x8*>((char*)SB(b, h) + boff1 + n * 256); }
; #define MMA(ai, bj, At, Btf) do { __builtin_amdgcn_s_setprio(1); \
;     for (int m = 0; m < 4; ++m) for (int n = 0; n < 2; ++n) for (int k = 0; k < 2; ++k) \
;       acc[ai][bj][m][n] = __builtin_amdgcn_mfma_f32_16x16x32_bf16(Btf[n][k], At[m][k], acc[ai][bj][m][n], 0, 0, 0); \
;     __builtin_amdgcn_s_setprio(0); } while (0)
; #define WAIT_V(n) asm volatile("s_waitcnt vmcnt(" #n ")" ::: "memory")
; #define WAIT_L(n) asm volatile("s_waitcnt lgkmcnt(" #n ")" ::: "memory")
; #define BAR __builtin_amdgcn_s_barrier()
; template <int EPI> ...
;     ...
;     LDB(B1, 0, 1); BAR; WAIT_L(0); MMA(0, 1, At, B1); BAR;
;     LDA(At, 0, 1); WAIT_V(4); BAR; WAIT_L(0); MMA(1, 0, At, B0); MMA(1, 1, At, B1); BAR; }
;   { LDB(B0, 1, 0); LDA(At, 1, 0); WAIT_V(2); BAR; WAIT_L(0); MMA(0, 0, At, B0); BAR;
	s_nop 1
	ds_read_b128 v[96:99], v155
	ds_read_b128 v[104:107], v155 offset:256
	ds_read_b128 v[112:115], v156
	ds_read_b128 v[120:123], v156 offset:256
	s_barrier
	s_waitcnt lgkmcnt(0)
	s_setprio 1
	s_waitcnt lgkmcnt(0)
	v_mfma_f32_16x16x32_bf16 v[92:95], v[96:99], v[178:181], v[92:95]
	v_mfma_f32_16x16x32_bf16 v[84:87], v[96:99], v[186:189], v[84:87]
	v_mfma_f32_16x16x32_bf16 v[76:79], v[96:99], v[194:197], v[76:79]
	v_mfma_f32_16x16x32_bf16 v[68:71], v[96:99], v[202:205], v[68:71]
	v_mfma_f32_16x16x32_bf16 v[92:95], v[112:115], v[182:185], v[92:95]
	v_mfma_f32_16x16x32_bf16 v[88:91], v[104:107], v[178:181], v[88:91]
	v_mfma_f32_16x16x32_bf16 v[84:87], v[112:115], v[190:193], v[84:87]
	v_mfma_f32_16x16x32_bf16 v[80:83], v[104:107], v[186:189], v[80:83]
	v_mfma_f32_16x16x32_bf16 v[76:79], v[112:115], v[198:201], v[76:79]
	v_mfma_f32_16x16x32_bf16 v[72:75], v[104:107], v[194:197], v[72:75]
	v_mfma_f32_16x16x32_bf16 v[68:71], v[112:115], v[206:209], v[68:71]
	v_mfma_f32_16x16x32_bf16 v[64:67], v[104:107], v[202:205], v[64:67]
	v_mfma_f32_16x16x32_bf16 v[178:181], v[120:123], v[182:185], v[88:91]
	v_mfma_f32_16x16x32_bf16 v[182:185], v[120:123], v[190:193], v[80:83]
	v_mfma_f32_16x16x32_bf16 v[186:189], v[120:123], v[198:201], v[72:75]
	v_mfma_f32_16x16x32_bf16 v[190:193], v[120:123], v[206:209], v[64:67]
	s_setprio 0
	s_barrier
	s_nop 1
	ds_read_b128 v[64:67], v150 offset:16384
	ds_read_b128 v[72:75], v150 offset:17408
	ds_read_b128 v[80:83], v150 offset:18432
	ds_read_b128 v[88:91], v150 offset:19456
	ds_read_b128 v[194:197], v150 offset:20480
	ds_read_b128 v[198:201], v150 offset:21504
	ds_read_b128 v[202:205], v150 offset:22528
	ds_read_b128 v[206:209], v150 offset:23552
	s_waitcnt vmcnt(4)
	s_barrier
	s_waitcnt lgkmcnt(0)
	s_setprio 1
	s_waitcnt lgkmcnt(0)
	v_mfma_f32_16x16x32_bf16 v[60:63], v[162:165], v[64:67], v[60:63]
	v_mfma_f32_16x16x32_bf16 v[56:59], v[166:169], v[64:67], v[56:59]
	v_mfma_f32_16x16x32_bf16 v[52:55], v[162:165], v[80:83], v[52:55]
	v_mfma_f32_16x16x32_bf16 v[40:43], v[166:169], v[194:197], v[40:43]
	v_mfma_f32_16x16x32_bf16 v[36:39], v[162:165], v[202:205], v[36:39]
	v_mfma_f32_16x16x32_bf16 v[60:63], v[170:173], v[72:75], v[60:63]
	v_mfma_f32_16x16x32_bf16 v[56:59], v[174:177], v[72:75], v[56:59]
	v_mfma_f32_16x16x32_bf16 v[52:55], v[170:173], v[88:91], v[52:55]
	v_mfma_f32_16x16x32_bf16 v[48:51], v[166:169], v[80:83], v[48:51]
	v_mfma_f32_16x16x32_bf16 v[44:47], v[162:165], v[194:197], v[44:47]
	v_mfma_f32_16x16x32_bf16 v[40:43], v[174:177], v[198:201], v[40:43]
	v_mfma_f32_16x16x32_bf16 v[36:39], v[170:173], v[206:209], v[36:39]
	v_mfma_f32_16x16x32_bf16 v[32:35], v[166:169], v[202:205], v[32:35]
	v_mfma_f32_16x16x32_bf16 v[226:229], v[174:177], v[88:91], v[48:51]
	v_mfma_f32_16x16x32_bf16 v[230:233], v[170:173], v[198:201], v[44:47]
	v_mfma_f32_16x16x32_bf16 v[162:165], v[174:177], v[206:209], v[32:35]
	s_setprio 0
	s_setprio 1
	v_mfma_f32_16x16x32_bf16 v[24:27], v[104:107], v[64:67], v[24:27]
	v_mfma_f32_16x16x32_bf16 v[20:23], v[96:99], v[80:83], v[20:23]
	v_mfma_f32_16x16x32_bf16 v[8:11], v[104:107], v[194:197], v[8:11]
	v_mfma_f32_16x16x32_bf16 v[4:7], v[96:99], v[202:205], v[4:7]
	v_mfma_f32_16x16x32_bf16 v[28:31], v[96:99], v[64:67], v[28:31]
	v_mfma_f32_16x16x32_bf16 v[24:27], v[120:123], v[72:75], v[24:27]
	v_mfma_f32_16x16x32_bf16 v[20:23], v[112:115], v[88:91], v[20:23]
	v_mfma_f32_16x16x32_bf16 v[16:19], v[104:107], v[80:83], v[16:19]
	v_mfma_f32_16x16x32_bf16 v[12:15], v[96:99], v[194:197], v[12:15]
	v_mfma_f32_16x16x32_bf16 v[8:11], v[120:123], v[198:201], v[8:11]
	v_mfma_f32_16x16x32_bf16 v[4:7], v[112:115], v[206:209], v[4:7]
	v_mfma_f32_16x16x32_bf16 v[0:3], v[104:107], v[202:205], v[0:3]
	v_mfma_f32_16x16x32_bf16 v[166:169], v[112:115], v[72:75], v[28:31]
	v_mfma_f32_16x16x32_bf16 v[170:173], v[120:123], v[88:91], v[16:19]
	v_mfma_f32_16x16x32_bf16 v[174:177], v[112:115], v[198:201], v[12:15]
	v_mfma_f32_16x16x32_bf16 v[194:197], v[120:123], v[206:209], v[0:3]
	s_setprio 0
	s_barrier
	s_nop 1
	ds_read_b128 v[0:3], v157
	ds_read_b128 v[198:201], v157 offset:256
	ds_read_b128 v[12:15], v158
	ds_read_b128 v[202:205], v158 offset:256
	ds_read_b128 v[16:19], v150 offset:32768
	ds_read_b128 v[28:31], v150 offset:33792
	ds_read_b128 v[32:35], v150 offset:34816
	ds_read_b128 v[44:47], v150 offset:35840
	ds_read_b128 v[48:51], v150 offset:36864
	ds_read_b128 v[206:209], v150 offset:37888
	ds_read_b128 v[234:237], v150 offset:38912
	ds_read_b128 v[238:241], v150 offset:39936
	s_waitcnt vmcnt(2)
	s_barrier
; #define LDA(dst, b, h) for (int m = 0; m < 4; ++m) { \
;     dst[m][0] = *reinterpret_cast<const bf16x8*>((char*)SA(b, h) + aoff0 + m * 2048); \
;     dst[m][1] = *reinterpret_cast<const bf16x8*>((char*)SA(b, h) + aoff1 + m * 2048); }
; #define LDB(dst, b, h) for (int n = 0; n < 2; ++n) { \
;     dst[n][0] = *reinterpret_cast<const bf16x8*>((char*)SB(b, h) + boff0 + n * 256); \
;     dst[n][1] = *reinterpret_cast<const bf16x8*>((char*)SB(b, h) + boff1 + n * 256); }
; #define MMA(ai, bj, At, Btf) do { __builtin_amdgcn_s_setprio(1); \
;     for (int m = 0; m < 4; ++m) for (int n = 0; n < 2; ++n) for (int k = 0; k < 2; ++k) \
;       acc[ai][bj][m][n] = __builtin_amdgcn_mfma_f32_16x16x32_bf16(Btf[n][k], At[m][k], acc[ai][bj][m][n], 0, 0, 0); \
;     __builtin_amdgcn_s_setprio(0); } while (0)
; #define WAIT_V(n) asm volatile("s_waitcnt vmcnt(" #n ")" ::: "memory")
; #define WAIT_L(n) asm volatile("s_waitcnt lgkmcnt(" #n ")" ::: "memory")
; #define BAR __builtin_amdgcn_s_barrier()
; template <int EPI> ...
;     ...
;   { LDB(B0, 1, 0); LDA(At, 1, 0); WAIT_V(2); BAR; WAIT_L(0); MMA(0, 0, At, B0); BAR;
;     LDB(B1, 1, 1); WAIT_V(0); BAR; WAIT_L(0); MMA(0, 1, At, B1); BAR;
;     LDA(At, 1, 1); BAR; WAIT_L(0); MMA(1, 0, At, B0); MMA(1, 1, At, B1); BAR; }
;   if (wr == 0) BAR;
	s_waitcnt lgkmcnt(0)
	s_setprio 1
	s_waitcnt lgkmcnt(0)
	v_mfma_f32_16x16x32_bf16 v[64:67], v[0:3], v[16:19], v[124:127]
	v_mfma_f32_16x16x32_bf16 v[120:123], v[12:15], v[28:31], v[64:67]
	v_mfma_f32_16x16x32_bf16 v[64:67], v[198:201], v[16:19], v[210:213]
	v_mfma_f32_16x16x32_bf16 v[112:115], v[202:205], v[28:31], v[64:67]
	v_mfma_f32_16x16x32_bf16 v[64:67], v[0:3], v[32:35], v[116:119]
	v_mfma_f32_16x16x32_bf16 v[104:107], v[12:15], v[44:47], v[64:67]
	v_mfma_f32_16x16x32_bf16 v[64:67], v[198:201], v[32:35], v[214:217]
	v_mfma_f32_16x16x32_bf16 v[96:99], v[202:205], v[44:47], v[64:67]
	v_mfma_f32_16x16x32_bf16 v[64:67], v[0:3], v[48:51], v[108:111]
	v_mfma_f32_16x16x32_bf16 v[88:91], v[12:15], v[206:209], v[64:67]
	v_mfma_f32_16x16x32_bf16 v[64:67], v[198:201], v[48:51], v[218:221]
	v_mfma_f32_16x16x32_bf16 v[80:83], v[202:205], v[206:209], v[64:67]
	v_mfma_f32_16x16x32_bf16 v[64:67], v[0:3], v[234:237], v[100:103]
	v_mfma_f32_16x16x32_bf16 v[72:75], v[12:15], v[238:241], v[64:67]
	v_mfma_f32_16x16x32_bf16 v[64:67], v[198:201], v[234:237], v[222:225]
	v_mfma_f32_16x16x32_bf16 v[64:67], v[202:205], v[238:241], v[64:67]
	s_setprio 0
	s_barrier
	ds_read_b128 v[210:213], v159
	ds_read_b128 v[214:217], v159 offset:256
	ds_read_b128 v[218:221], v160
	ds_read_b128 v[222:225], v160 offset:256
	s_waitcnt vmcnt(0)
	s_barrier
	s_waitcnt lgkmcnt(0)
	s_setprio 1
	s_waitcnt lgkmcnt(0)
	v_mfma_f32_16x16x32_bf16 v[92:95], v[210:213], v[16:19], v[92:95]
	v_mfma_f32_16x16x32_bf16 v[16:19], v[214:217], v[16:19], v[178:181]
	v_mfma_f32_16x16x32_bf16 v[116:119], v[222:225], v[28:31], v[16:19]
	v_mfma_f32_16x16x32_bf16 v[16:19], v[210:213], v[32:35], v[84:87]
	v_mfma_f32_16x16x32_bf16 v[108:111], v[218:221], v[44:47], v[16:19]
	v_mfma_f32_16x16x32_bf16 v[16:19], v[214:217], v[32:35], v[182:185]
	v_mfma_f32_16x16x32_bf16 v[100:103], v[222:225], v[44:47], v[16:19]
	v_mfma_f32_16x16x32_bf16 v[16:19], v[210:213], v[48:51], v[76:79]
	v_mfma_f32_16x16x32_bf16 v[124:127], v[218:221], v[28:31], v[92:95]
	v_mfma_f32_16x16x32_bf16 v[92:95], v[218:221], v[206:209], v[16:19]
	v_mfma_f32_16x16x32_bf16 v[16:19], v[214:217], v[48:51], v[186:189]
	v_mfma_f32_16x16x32_bf16 v[84:87], v[222:225], v[206:209], v[16:19]
	v_mfma_f32_16x16x32_bf16 v[16:19], v[210:213], v[234:237], v[68:71]
	v_mfma_f32_16x16x32_bf16 v[76:79], v[218:221], v[238:241], v[16:19]
	v_mfma_f32_16x16x32_bf16 v[16:19], v[214:217], v[234:237], v[190:193]
	v_mfma_f32_16x16x32_bf16 v[68:71], v[222:225], v[238:241], v[16:19]
	s_setprio 0
	s_barrier
	ds_read_b128 v[178:181], v150 offset:49152
	ds_read_b128 v[182:185], v150 offset:50176
	ds_read_b128 v[186:189], v150 offset:51200
	ds_read_b128 v[190:193], v150 offset:52224
	ds_read_b128 v[206:209], v150 offset:53248
	ds_read_b128 v[234:237], v150 offset:54272
	ds_read_b128 v[238:241], v150 offset:55296
	ds_read_b128 v[242:245], v150 offset:56320
	s_barrier
	s_waitcnt lgkmcnt(0)
	s_setprio 1
	s_waitcnt lgkmcnt(0)
	v_mfma_f32_16x16x32_bf16 v[16:19], v[0:3], v[178:181], v[60:63]
	v_mfma_f32_16x16x32_bf16 v[60:63], v[12:15], v[182:185], v[16:19]
	v_mfma_f32_16x16x32_bf16 v[16:19], v[198:201], v[178:181], v[56:59]
	v_mfma_f32_16x16x32_bf16 v[48:51], v[202:205], v[182:185], v[16:19]
	v_mfma_f32_16x16x32_bf16 v[16:19], v[0:3], v[186:189], v[52:55]
	v_mfma_f32_16x16x32_bf16 v[44:47], v[12:15], v[190:193], v[16:19]
	v_mfma_f32_16x16x32_bf16 v[16:19], v[198:201], v[186:189], v[226:229]
	v_mfma_f32_16x16x32_bf16 v[32:35], v[202:205], v[190:193], v[16:19]
	v_mfma_f32_16x16x32_bf16 v[16:19], v[0:3], v[206:209], v[230:233]
	v_mfma_f32_16x16x32_bf16 v[0:3], v[0:3], v[238:241], v[36:39]
	v_mfma_f32_16x16x32_bf16 v[28:31], v[12:15], v[234:237], v[16:19]
	v_mfma_f32_16x16x32_bf16 v[16:19], v[198:201], v[206:209], v[40:43]
	v_mfma_f32_16x16x32_bf16 v[12:15], v[12:15], v[242:245], v[0:3]
	v_mfma_f32_16x16x32_bf16 v[0:3], v[198:201], v[238:241], v[162:165]
	v_mfma_f32_16x16x32_bf16 v[16:19], v[202:205], v[234:237], v[16:19]
	v_mfma_f32_16x16x32_bf16 v[0:3], v[202:205], v[242:245], v[0:3]
	s_setprio 0
	s_setprio 1
	v_mfma_f32_16x16x32_bf16 v[20:23], v[210:213], v[186:189], v[20:23]
	v_mfma_f32_16x16x32_bf16 v[36:39], v[210:213], v[178:181], v[166:169]
	v_mfma_f32_16x16x32_bf16 v[40:43], v[218:221], v[190:193], v[20:23]
	v_mfma_f32_16x16x32_bf16 v[20:23], v[214:217], v[186:189], v[170:173]
	v_mfma_f32_16x16x32_bf16 v[56:59], v[218:221], v[182:185], v[36:39]
	v_mfma_f32_16x16x32_bf16 v[24:27], v[214:217], v[178:181], v[24:27]
	v_mfma_f32_16x16x32_bf16 v[36:39], v[222:225], v[190:193], v[20:23]
	v_mfma_f32_16x16x32_bf16 v[20:23], v[210:213], v[206:209], v[174:177]
	v_mfma_f32_16x16x32_bf16 v[8:11], v[214:217], v[206:209], v[8:11]
	v_mfma_f32_16x16x32_bf16 v[4:7], v[210:213], v[238:241], v[4:7]
	v_mfma_f32_16x16x32_bf16 v[52:55], v[222:225], v[182:185], v[24:27]
	v_mfma_f32_16x16x32_bf16 v[24:27], v[218:221], v[234:237], v[20:23]
	v_mfma_f32_16x16x32_bf16 v[20:23], v[222:225], v[234:237], v[8:11]
	v_mfma_f32_16x16x32_bf16 v[8:11], v[218:221], v[242:245], v[4:7]
	v_mfma_f32_16x16x32_bf16 v[4:7], v[214:217], v[238:241], v[194:197]
	v_mfma_f32_16x16x32_bf16 v[4:7], v[222:225], v[242:245], v[4:7]
	s_setprio 0
	s_barrier
	s_and_saveexec_b64 s[68:69], s[2:3]
	s_cbranch_execz .LBB0_271
	s_barrier
	s_branch .LBB0_271

; #define STAGE(P, BASE, br, kt) do { const char* _gb = (const char*)(BASE) + ((size_t)(br) * K + (size_t)(kt) * BK) * 2; \
;     __builtin_amdgcn_global_load_lds((const unsigned*)(_gb + loff0), (unsigned*)((char*)(P) + tid * 16), 16, 0, 0); \
;     __builtin_amdgcn_global_load_lds((const unsigned*)(_gb + (size_t)K * 128 + loff0), (unsigned*)((char*)(P) + tid * 16 + 8192), 16, 0, 0); } while (0)
; #define LDA(dst, b, h) for (int m = 0; m < 4; ++m) { \
;     dst[m][0] = *reinterpret_cast<const bf16x8*>((char*)SA(b, h) + aoff0 + m * 2048); \
;     dst[m][1] = *reinterpret_cast<const bf16x8*>((char*)SA(b, h) + aoff1 + m * 2048); }
; #define LDB(dst, b, h) for (int n = 0; n < 2; ++n) { \
;     dst[n][0] = *reinterpret_cast<const bf16x8*>((char*)SB(b, h) + boff0 + n * 256); \
;     dst[n][1] = *reinterpret_cast<const bf16x8*>((char*)SB(b, h) + boff1 + n * 256); }
; #define MMA(ai, bj, At, Btf) do { __builtin_amdgcn_s_setprio(1); \
;     for (int m = 0; m < 4; ++m) for (int n = 0; n < 2; ++n) for (int k = 0; k < 2; ++k) \
;       acc[ai][bj][m][n] = __builtin_amdgcn_mfma_f32_16x16x32_bf16(Btf[n][k], At[m][k], acc[ai][bj][m][n], 0, 0, 0); \
;     __builtin_amdgcn_s_setprio(0); } while (0)
; #define WAIT_V(n) asm volatile("s_waitcnt vmcnt(" #n ")" ::: "memory")
; #define WAIT_L(n) asm volatile("s_waitcnt lgkmcnt(" #n ")" ::: "memory")
; #define BAR __builtin_amdgcn_s_barrier()
; #define SCHED __builtin_amdgcn_sched_barrier(0)
; template <int EPI> ...
;     ...
;   WAIT_V(4); BAR;
;   STAGE(SB(1, 0), Bt, bcol, 1); STAGE(SA(1, 0), A, brow, 1); STAGE(SB(1, 1), Bt, bcol + HALF, 1);
;   WAIT_V(6); BAR;
;   for (int t = 0; t < nt - 2; t += 2) {
;     LDB(B0, 0, 0); SCHED; LDA(At, 0, 0); STAGE(SA(1, 1), A, brow + HALF, t + 1);
;     WAIT_L(8); BAR; WAIT_L(0); MMA(0, 0, At, B0); BAR; SCHED;
;     LDB(B1, 0, 1); STAGE(SB(0, 0), Bt, bcol, t + 2);
;     BAR; WAIT_L(0); MMA(0, 1, At, B1); BAR;
;     LDA(At, 0, 1); STAGE(SA(0, 0), A, brow, t + 2);
;     BAR; WAIT_L(0); MMA(1, 0, At, B0); BAR; SCHED;
;     STAGE(SB(0, 1), Bt, bcol + HALF, t + 2);
;     WAIT_V(6); BAR; MMA(1, 1, At, B1); BAR;
.LBB0_323:
	s_or_b64 exec, exec, s[64:65]
	v_readfirstlane_b32 s64, v143
	v_lshl_add_u64 v[6:7], v[0:1], 0, s[10:11]
	s_mov_b32 m0, s64
	v_readfirstlane_b32 s64, v144
	s_waitcnt vmcnt(2)
	s_barrier
	global_load_lds_dwordx4 v[6:7], off
	v_lshl_add_u64 v[0:1], v[0:1], 0, s[12:13]
	s_mov_b32 m0, s64
	v_readfirstlane_b32 s64, v145
	global_load_lds_dwordx4 v[0:1], off
	v_lshl_add_u64 v[0:1], v[2:3], 0, s[10:11]
	s_mov_b32 m0, s64
	v_readfirstlane_b32 s64, v146
	global_load_lds_dwordx4 v[0:1], off
	v_lshl_add_u64 v[0:1], v[2:3], 0, s[12:13]
	s_mov_b32 m0, s64
	v_readfirstlane_b32 s64, v147
	global_load_lds_dwordx4 v[0:1], off
	v_lshl_add_u64 v[0:1], v[4:5], 0, s[10:11]
	s_mov_b32 m0, s64
	v_readfirstlane_b32 s64, v148
	global_load_lds_dwordx4 v[0:1], off
	v_lshl_add_u64 v[0:1], v[4:5], 0, s[12:13]
	s_mov_b32 m0, s64
	s_ashr_i32 s61, s60, 31
	global_load_lds_dwordx4 v[0:1], off
	s_add_u32 s62, s6, s62
	s_addc_u32 s63, s7, s63
	s_add_u32 s64, s6, s77
	s_addc_u32 s65, s7, s76
	s_add_u32 s66, s6, s66
	v_mov_b32_e32 v0, 0
	s_addc_u32 s67, s7, s67
	s_mov_b32 s76, -2
	v_mov_b32_e32 v1, v0
	v_mov_b32_e32 v2, v0
	v_mov_b32_e32 v3, v0
	v_mov_b32_e32 v4, v0
	v_mov_b32_e32 v5, v0
	v_mov_b32_e32 v6, v0
	v_mov_b32_e32 v7, v0
	s_waitcnt vmcnt(6)
	s_barrier
.LBB0_324:
	ds_read_b128 v[160:163], v152
	ds_read_b128 v[164:167], v152 offset:256
	ds_read_b128 v[168:171], v153
	ds_read_b128 v[172:175], v153 offset:256
	v_lshl_add_u64 v[224:225], s[64:65], 0, v[132:133]
	v_readfirstlane_b32 s77, v150
	v_lshl_add_u64 v[208:209], v[224:225], 0, s[16:17]
	s_mov_b32 m0, s77
	v_readfirstlane_b32 s77, v151
	ds_read_b128 v[176:179], v149
	ds_read_b128 v[180:183], v149 offset:1024
	ds_read_b128 v[184:187], v149 offset:2048
	ds_read_b128 v[188:191], v149 offset:3072
	ds_read_b128 v[192:195], v149 offset:4096
	ds_read_b128 v[196:199], v149 offset:5120
	ds_read_b128 v[200:203], v149 offset:6144
	ds_read_b128 v[204:207], v149 offset:7168
	global_load_lds_dwordx4 v[208:209], off
	v_lshl_add_u64 v[208:209], v[224:225], 0, s[18:19]
	s_mov_b32 m0, s77
	s_nop 0
	global_load_lds_dwordx4 v[208:209], off
	s_waitcnt lgkmcnt(8)
	ds_read_b128 v[208:211], v154
	ds_read_b128 v[212:215], v154 offset:256
	ds_read_b128 v[216:219], v155
	ds_read_b128 v[220:223], v155 offset:256
	s_barrier
	s_waitcnt lgkmcnt(0)
	s_setprio 1
	s_waitcnt lgkmcnt(0)
	v_mfma_f32_16x16x32_bf16 v[124:127], v[160:163], v[176:179], v[124:127]
	v_mfma_f32_16x16x32_bf16 v[120:123], v[164:167], v[176:179], v[120:123]
	v_mfma_f32_16x16x32_bf16 v[116:119], v[160:163], v[184:187], v[116:119]
	v_mfma_f32_16x16x32_bf16 v[112:115], v[164:167], v[184:187], v[112:115]
	v_mfma_f32_16x16x32_bf16 v[108:111], v[160:163], v[192:195], v[108:111]
	v_mfma_f32_16x16x32_bf16 v[104:107], v[164:167], v[192:195], v[104:107]
	v_mfma_f32_16x16x32_bf16 v[100:103], v[160:163], v[200:203], v[100:103]
	v_mfma_f32_16x16x32_bf16 v[96:99], v[164:167], v[200:203], v[96:99]
	v_mfma_f32_16x16x32_bf16 v[124:127], v[168:171], v[180:183], v[124:127]
	v_mfma_f32_16x16x32_bf16 v[120:123], v[172:175], v[180:183], v[120:123]
	v_mfma_f32_16x16x32_bf16 v[116:119], v[168:171], v[188:191], v[116:119]
	v_mfma_f32_16x16x32_bf16 v[112:115], v[172:175], v[188:191], v[112:115]
	v_mfma_f32_16x16x32_bf16 v[108:111], v[168:171], v[196:199], v[108:111]
	v_mfma_f32_16x16x32_bf16 v[104:107], v[172:175], v[196:199], v[104:107]
	v_mfma_f32_16x16x32_bf16 v[100:103], v[168:171], v[204:207], v[100:103]
	v_mfma_f32_16x16x32_bf16 v[96:99], v[172:175], v[204:207], v[96:99]
	s_setprio 0
	s_waitcnt lgkmcnt(0)
	s_setprio 1
	s_waitcnt lgkmcnt(0)
	v_mfma_f32_16x16x32_bf16 v[92:95], v[208:211], v[176:179], v[92:95]
	v_mfma_f32_16x16x32_bf16 v[88:91], v[212:215], v[176:179], v[88:91]
	v_mfma_f32_16x16x32_bf16 v[84:87], v[208:211], v[184:187], v[84:87]
	v_mfma_f32_16x16x32_bf16 v[80:83], v[212:215], v[184:187], v[80:83]
	v_mfma_f32_16x16x32_bf16 v[76:79], v[208:211], v[192:195], v[76:79]
	v_mfma_f32_16x16x32_bf16 v[72:75], v[212:215], v[192:195], v[72:75]
	v_mfma_f32_16x16x32_bf16 v[68:71], v[208:211], v[200:203], v[68:71]
	v_mfma_f32_16x16x32_bf16 v[64:67], v[212:215], v[200:203], v[64:67]
	v_mfma_f32_16x16x32_bf16 v[92:95], v[216:219], v[180:183], v[92:95]
	v_mfma_f32_16x16x32_bf16 v[88:91], v[220:223], v[180:183], v[88:91]
	v_mfma_f32_16x16x32_bf16 v[84:87], v[216:219], v[188:191], v[84:87]
	v_mfma_f32_16x16x32_bf16 v[80:83], v[220:223], v[188:191], v[80:83]
	v_mfma_f32_16x16x32_bf16 v[76:79], v[216:219], v[196:199], v[76:79]
	v_mfma_f32_16x16x32_bf16 v[72:75], v[220:223], v[196:199], v[72:75]
	v_mfma_f32_16x16x32_bf16 v[68:71], v[216:219], v[204:207], v[68:71]
	v_mfma_f32_16x16x32_bf16 v[64:67], v[220:223], v[204:207], v[64:67]
	s_setprio 0
	s_barrier
	v_lshl_add_u64 v[226:227], s[66:67], 0, v[132:133]
	v_readfirstlane_b32 s77, v135
	v_lshl_add_u64 v[228:229], v[226:227], 0, s[20:21]
	s_mov_b32 m0, s77
	v_readfirstlane_b32 s77, v136
	global_load_lds_dwordx4 v[228:229], off
	v_lshl_add_u64 v[228:229], v[226:227], 0, s[22:23]
	s_mov_b32 m0, s77
	s_nop 0
	global_load_lds_dwordx4 v[228:229], off
	v_readfirstlane_b32 s77, v137
	v_lshl_add_u64 v[228:229], v[224:225], 0, s[26:27]
	s_mov_b32 m0, s77
	v_readfirstlane_b32 s77, v138
	ds_read_b128 v[176:179], v149 offset:16384
	ds_read_b128 v[180:183], v149 offset:17408
	ds_read_b128 v[184:187], v149 offset:18432
	ds_read_b128 v[188:191], v149 offset:19456
	ds_read_b128 v[192:195], v149 offset:20480
	ds_read_b128 v[196:199], v149 offset:21504
	ds_read_b128 v[200:203], v149 offset:22528
	ds_read_b128 v[204:207], v149 offset:23552
	global_load_lds_dwordx4 v[228:229], off
	v_lshl_add_u64 v[228:229], v[224:225], 0, s[28:29]
	s_mov_b32 m0, s77
	s_nop 0
	global_load_lds_dwordx4 v[228:229], off
	v_lshl_add_u64 v[228:229], s[62:63], 0, v[132:133]
	v_readfirstlane_b32 s77, v139
	v_lshl_add_u64 v[246:247], v[228:229], 0, s[30:31]
	s_mov_b32 m0, s77
	v_readfirstlane_b32 s77, v140
	global_load_lds_dwordx4 v[246:247], off
	v_lshl_add_u64 v[246:247], v[228:229], 0, s[36:37]
	s_mov_b32 m0, s77
	s_nop 0
	global_load_lds_dwordx4 v[246:247], off
	s_waitcnt vmcnt(6)
	s_barrier
; #define STAGE(P, BASE, br, kt) do { const char* _gb = (const char*)(BASE) + ((size_t)(br) * K + (size_t)(kt) * BK) * 2; \
;     __builtin_amdgcn_global_load_lds((const unsigned*)(_gb + loff0), (unsigned*)((char*)(P) + tid * 16), 16, 0, 0); \
;     __builtin_amdgcn_global_load_lds((const unsigned*)(_gb + (size_t)K * 128 + loff0), (unsigned*)((char*)(P) + tid * 16 + 8192), 16, 0, 0); } while (0)
; #define LDA(dst, b, h) for (int m = 0; m < 4; ++m) { \
;     dst[m][0] = *reinterpret_cast<const bf16x8*>((char*)SA(b, h) + aoff0 + m * 2048); \
;     dst[m][1] = *reinterpret_cast<const bf16x8*>((char*)SA(b, h) + aoff1 + m * 2048); }
; #define LDB(dst, b, h) for (int n = 0; n < 2; ++n) { \
;     dst[n][0] = *reinterpret_cast<const bf16x8*>((char*)SB(b, h) + boff0 + n * 256); \
;     dst[n][1] = *reinterpret_cast<const bf16x8*>((char*)SB(b, h) + boff1 + n * 256); }
; #define MMA(ai, bj, At, Btf) do { __builtin_amdgcn_s_setprio(1); \
;     for (int m = 0; m < 4; ++m) for (int n = 0; n < 2; ++n) for (int k = 0; k < 2; ++k) \
;       acc[ai][bj][m][n] = __builtin_amdgcn_mfma_f32_16x16x32_bf16(Btf[n][k], At[m][k], acc[ai][bj][m][n], 0, 0, 0); \
;     __builtin_amdgcn_s_setprio(0); } while (0)
; #define WAIT_V(n) asm volatile("s_waitcnt vmcnt(" #n ")" ::: "memory")
; #define WAIT_L(n) asm volatile("s_waitcnt lgkmcnt(" #n ")" ::: "memory")
; #define BAR __builtin_amdgcn_s_barrier()
; #define SCHED __builtin_amdgcn_sched_barrier(0)
; template <int EPI> ...
;     ...
;     BAR; WAIT_L(0); MMA(1, 0, At, B0); BAR; SCHED;
;     STAGE(SB(0, 1), Bt, bcol + HALF, t + 2);
;     WAIT_V(6); BAR; MMA(1, 1, At, B1); BAR;
;     LDB(B0, 1, 0); SCHED; LDA(At, 1, 0); STAGE(SA(0, 1), A, brow + HALF, t + 2);
;     WAIT_L(8); BAR; WAIT_L(0); MMA(0, 0, At, B0); BAR; SCHED;
;     LDB(B1, 1, 1); STAGE(SB(1, 0), Bt, bcol, t + 3);
;     BAR; WAIT_L(0); MMA(0, 1, At, B1); BAR;
	s_waitcnt lgkmcnt(0)
	s_setprio 1
	s_waitcnt lgkmcnt(0)
	v_mfma_f32_16x16x32_bf16 v[60:63], v[160:163], v[176:179], v[60:63]
	v_mfma_f32_16x16x32_bf16 v[56:59], v[164:167], v[176:179], v[56:59]
	v_mfma_f32_16x16x32_bf16 v[52:55], v[160:163], v[184:187], v[52:55]
	v_mfma_f32_16x16x32_bf16 v[48:51], v[164:167], v[184:187], v[48:51]
	v_mfma_f32_16x16x32_bf16 v[44:47], v[160:163], v[192:195], v[44:47]
	v_mfma_f32_16x16x32_bf16 v[40:43], v[164:167], v[192:195], v[40:43]
	v_mfma_f32_16x16x32_bf16 v[36:39], v[160:163], v[200:203], v[36:39]
	v_mfma_f32_16x16x32_bf16 v[32:35], v[164:167], v[200:203], v[32:35]
	v_mfma_f32_16x16x32_bf16 v[60:63], v[168:171], v[180:183], v[60:63]
	v_mfma_f32_16x16x32_bf16 v[56:59], v[172:175], v[180:183], v[56:59]
	v_mfma_f32_16x16x32_bf16 v[52:55], v[168:171], v[188:191], v[52:55]
	v_mfma_f32_16x16x32_bf16 v[48:51], v[172:175], v[188:191], v[48:51]
	v_mfma_f32_16x16x32_bf16 v[44:47], v[168:171], v[196:199], v[44:47]
	v_mfma_f32_16x16x32_bf16 v[40:43], v[172:175], v[196:199], v[40:43]
	v_mfma_f32_16x16x32_bf16 v[36:39], v[168:171], v[204:207], v[36:39]
	v_mfma_f32_16x16x32_bf16 v[32:35], v[172:175], v[204:207], v[32:35]
	s_setprio 0
	s_setprio 1
	v_mfma_f32_16x16x32_bf16 v[28:31], v[208:211], v[176:179], v[28:31]
	v_mfma_f32_16x16x32_bf16 v[24:27], v[212:215], v[176:179], v[24:27]
	v_mfma_f32_16x16x32_bf16 v[20:23], v[208:211], v[184:187], v[20:23]
	v_mfma_f32_16x16x32_bf16 v[16:19], v[212:215], v[184:187], v[16:19]
	v_mfma_f32_16x16x32_bf16 v[12:15], v[208:211], v[192:195], v[12:15]
	v_mfma_f32_16x16x32_bf16 v[8:11], v[212:215], v[192:195], v[8:11]
	v_mfma_f32_16x16x32_bf16 v[4:7], v[208:211], v[200:203], v[4:7]
	v_mfma_f32_16x16x32_bf16 v[0:3], v[212:215], v[200:203], v[0:3]
	v_mfma_f32_16x16x32_bf16 v[28:31], v[216:219], v[180:183], v[28:31]
	v_mfma_f32_16x16x32_bf16 v[24:27], v[220:223], v[180:183], v[24:27]
	v_mfma_f32_16x16x32_bf16 v[20:23], v[216:219], v[188:191], v[20:23]
	v_mfma_f32_16x16x32_bf16 v[16:19], v[220:223], v[188:191], v[16:19]
	v_mfma_f32_16x16x32_bf16 v[12:15], v[216:219], v[196:199], v[12:15]
	v_mfma_f32_16x16x32_bf16 v[8:11], v[220:223], v[196:199], v[8:11]
	v_mfma_f32_16x16x32_bf16 v[4:7], v[216:219], v[204:207], v[4:7]
	v_mfma_f32_16x16x32_bf16 v[0:3], v[220:223], v[204:207], v[0:3]
	s_setprio 0
	s_barrier
	ds_read_b128 v[160:163], v156
	ds_read_b128 v[164:167], v156 offset:256
	ds_read_b128 v[168:171], v157
	ds_read_b128 v[172:175], v157 offset:256
	v_readfirstlane_b32 s77, v141
	v_lshl_add_u64 v[208:209], v[224:225], 0, s[38:39]
	s_mov_b32 m0, s77
	v_readfirstlane_b32 s77, v142
	ds_read_b128 v[176:179], v149 offset:32768
	ds_read_b128 v[180:183], v149 offset:33792
	ds_read_b128 v[184:187], v149 offset:34816
	ds_read_b128 v[188:191], v149 offset:35840
	ds_read_b128 v[192:195], v149 offset:36864
	ds_read_b128 v[196:199], v149 offset:37888
	ds_read_b128 v[200:203], v149 offset:38912
	ds_read_b128 v[204:207], v149 offset:39936
	global_load_lds_dwordx4 v[208:209], off
	v_lshl_add_u64 v[208:209], v[224:225], 0, s[46:47]
	s_mov_b32 m0, s77
	s_nop 0
	global_load_lds_dwordx4 v[208:209], off
	s_waitcnt lgkmcnt(8)
	ds_read_b128 v[208:211], v158
	ds_read_b128 v[212:215], v158 offset:256
	ds_read_b128 v[216:219], v159
	ds_read_b128 v[220:223], v159 offset:256
	s_barrier
	s_waitcnt lgkmcnt(0)
	s_setprio 1
	s_waitcnt lgkmcnt(0)
	v_mfma_f32_16x16x32_bf16 v[124:127], v[160:163], v[176:179], v[124:127]
	v_mfma_f32_16x16x32_bf16 v[120:123], v[164:167], v[176:179], v[120:123]
	v_mfma_f32_16x16x32_bf16 v[116:119], v[160:163], v[184:187], v[116:119]
	v_mfma_f32_16x16x32_bf16 v[112:115], v[164:167], v[184:187], v[112:115]
	v_mfma_f32_16x16x32_bf16 v[108:111], v[160:163], v[192:195], v[108:111]
	v_mfma_f32_16x16x32_bf16 v[104:107], v[164:167], v[192:195], v[104:107]
	v_mfma_f32_16x16x32_bf16 v[100:103], v[160:163], v[200:203], v[100:103]
	v_mfma_f32_16x16x32_bf16 v[96:99], v[164:167], v[200:203], v[96:99]
	v_mfma_f32_16x16x32_bf16 v[124:127], v[168:171], v[180:183], v[124:127]
	v_mfma_f32_16x16x32_bf16 v[120:123], v[172:175], v[180:183], v[120:123]
	v_mfma_f32_16x16x32_bf16 v[116:119], v[168:171], v[188:191], v[116:119]
	v_mfma_f32_16x16x32_bf16 v[112:115], v[172:175], v[188:191], v[112:115]
	v_mfma_f32_16x16x32_bf16 v[108:111], v[168:171], v[196:199], v[108:111]
	v_mfma_f32_16x16x32_bf16 v[104:107], v[172:175], v[196:199], v[104:107]
	v_mfma_f32_16x16x32_bf16 v[100:103], v[168:171], v[204:207], v[100:103]
	v_mfma_f32_16x16x32_bf16 v[96:99], v[172:175], v[204:207], v[96:99]
	s_setprio 0
	s_waitcnt lgkmcnt(0)
	s_setprio 1
	s_waitcnt lgkmcnt(0)
	v_mfma_f32_16x16x32_bf16 v[92:95], v[208:211], v[176:179], v[92:95]
	v_mfma_f32_16x16x32_bf16 v[88:91], v[212:215], v[176:179], v[88:91]
	v_mfma_f32_16x16x32_bf16 v[84:87], v[208:211], v[184:187], v[84:87]
	v_mfma_f32_16x16x32_bf16 v[80:83], v[212:215], v[184:187], v[80:83]
	v_mfma_f32_16x16x32_bf16 v[76:79], v[208:211], v[192:195], v[76:79]
	v_mfma_f32_16x16x32_bf16 v[72:75], v[212:215], v[192:195], v[72:75]
	v_mfma_f32_16x16x32_bf16 v[68:71], v[208:211], v[200:203], v[68:71]
	v_mfma_f32_16x16x32_bf16 v[64:67], v[212:215], v[200:203], v[64:67]
	v_mfma_f32_16x16x32_bf16 v[92:95], v[216:219], v[180:183], v[92:95]
	v_mfma_f32_16x16x32_bf16 v[88:91], v[220:223], v[180:183], v[88:91]
	v_mfma_f32_16x16x32_bf16 v[84:87], v[216:219], v[188:191], v[84:87]
	v_mfma_f32_16x16x32_bf16 v[80:83], v[220:223], v[188:191], v[80:83]
	v_mfma_f32_16x16x32_bf16 v[76:79], v[216:219], v[196:199], v[76:79]
	v_mfma_f32_16x16x32_bf16 v[72:75], v[220:223], v[196:199], v[72:75]
	v_mfma_f32_16x16x32_bf16 v[68:71], v[216:219], v[204:207], v[68:71]
	v_mfma_f32_16x16x32_bf16 v[64:67], v[220:223], v[204:207], v[64:67]
	s_setprio 0
	s_barrier
; #define STAGE(P, BASE, br, kt) do { const char* _gb = (const char*)(BASE) + ((size_t)(br) * K + (size_t)(kt) * BK) * 2; \
;     __builtin_amdgcn_global_load_lds((const unsigned*)(_gb + loff0), (unsigned*)((char*)(P) + tid * 16), 16, 0, 0); \
;     __builtin_amdgcn_global_load_lds((const unsigned*)(_gb + (size_t)K * 128 + loff0), (unsigned*)((char*)(P) + tid * 16 + 8192), 16, 0, 0); } while (0)
; #define LDA(dst, b, h) for (int m = 0; m < 4; ++m) { \
;     dst[m][0] = *reinterpret_cast<const bf16x8*>((char*)SA(b, h) + aoff0 + m * 2048); \
;     dst[m][1] = *reinterpret_cast<const bf16x8*>((char*)SA(b, h) + aoff1 + m * 2048); }
; #define LDB(dst, b, h) for (int n = 0; n < 2; ++n) { \
;     dst[n][0] = *reinterpret_cast<const bf16x8*>((char*)SB(b, h) + boff0 + n * 256); \
;     dst[n][1] = *reinterpret_cast<const bf16x8*>((char*)SB(b, h) + boff1 + n * 256); }
; #define MMA(ai, bj, At, Btf) do { __builtin_amdgcn_s_setprio(1); \
;     for (int m = 0; m < 4; ++m) for (int n = 0; n < 2; ++n) for (int k = 0; k < 2; ++k) \
;       acc[ai][bj][m][n] = __builtin_amdgcn_mfma_f32_16x16x32_bf16(Btf[n][k], At[m][k], acc[ai][bj][m][n], 0, 0, 0); \
;     __builtin_amdgcn_s_setprio(0); } while (0)
; #define WAIT_V(n) asm volatile("s_waitcnt vmcnt(" #n ")" ::: "memory")
; #define WAIT_L(n) asm volatile("s_waitcnt lgkmcnt(" #n ")" ::: "memory")
; #define BAR __builtin_amdgcn_s_barrier()
; #define SCHED __builtin_amdgcn_sched_barrier(0)
; template <int EPI> ...
;     ...
;     LDB(B1, 1, 1); STAGE(SB(1, 0), Bt, bcol, t + 3);
;     BAR; WAIT_L(0); MMA(0, 1, At, B1); BAR;
;     LDA(At, 1, 1); STAGE(SA(1, 0), A, brow, t + 3);
;     BAR; WAIT_L(0); MMA(1, 0, At, B0); BAR; SCHED;
;     STAGE(SB(1, 1), Bt, bcol + HALF, t + 3);
;     WAIT_V(6); BAR; MMA(1, 1, At, B1); BAR;
;   }
;   { LDB(B0, 0, 0); LDA(At, 0, 0); STAGE(SA(1, 1), A, brow + HALF, nt - 1);
;     BAR; WAIT_L(0); MMA(0, 0, At, B0); BAR;
	v_readfirstlane_b32 s77, v143
	v_lshl_add_u64 v[230:231], v[226:227], 0, s[48:49]
	s_mov_b32 m0, s77
	v_readfirstlane_b32 s77, v144
	global_load_lds_dwordx4 v[230:231], off
	v_lshl_add_u64 v[226:227], v[226:227], 0, s[50:51]
	s_mov_b32 m0, s77
	s_nop 0
	global_load_lds_dwordx4 v[226:227], off
	v_readfirstlane_b32 s77, v145
	v_lshl_add_u64 v[226:227], v[224:225], 0, s[52:53]
	s_mov_b32 m0, s77
	v_readfirstlane_b32 s77, v146
	ds_read_b128 v[176:179], v149 offset:49152
	ds_read_b128 v[180:183], v149 offset:50176
	ds_read_b128 v[184:187], v149 offset:51200
	ds_read_b128 v[188:191], v149 offset:52224
	ds_read_b128 v[192:195], v149 offset:53248
	ds_read_b128 v[196:199], v149 offset:54272
	ds_read_b128 v[200:203], v149 offset:55296
	ds_read_b128 v[204:207], v149 offset:56320
	global_load_lds_dwordx4 v[226:227], off
	v_lshl_add_u64 v[224:225], v[224:225], 0, s[54:55]
	s_mov_b32 m0, s77
	s_nop 0
	global_load_lds_dwordx4 v[224:225], off
	v_readfirstlane_b32 s77, v147
	v_lshl_add_u64 v[246:247], v[228:229], 0, s[56:57]
	s_mov_b32 m0, s77
	v_readfirstlane_b32 s77, v148
	global_load_lds_dwordx4 v[246:247], off
	v_lshl_add_u64 v[246:247], v[228:229], 0, s[58:59]
	s_mov_b32 m0, s77
	s_nop 0
	global_load_lds_dwordx4 v[246:247], off
	s_waitcnt vmcnt(6)
	s_barrier
	s_waitcnt lgkmcnt(0)
	s_setprio 1
	s_waitcnt lgkmcnt(0)
	v_mfma_f32_16x16x32_bf16 v[60:63], v[160:163], v[176:179], v[60:63]
	v_mfma_f32_16x16x32_bf16 v[56:59], v[164:167], v[176:179], v[56:59]
	v_mfma_f32_16x16x32_bf16 v[52:55], v[160:163], v[184:187], v[52:55]
	v_mfma_f32_16x16x32_bf16 v[48:51], v[164:167], v[184:187], v[48:51]
	v_mfma_f32_16x16x32_bf16 v[44:47], v[160:163], v[192:195], v[44:47]
	v_mfma_f32_16x16x32_bf16 v[40:43], v[164:167], v[192:195], v[40:43]
	v_mfma_f32_16x16x32_bf16 v[36:39], v[160:163], v[200:203], v[36:39]
	v_mfma_f32_16x16x32_bf16 v[32:35], v[164:167], v[200:203], v[32:35]
	v_mfma_f32_16x16x32_bf16 v[60:63], v[168:171], v[180:183], v[60:63]
	v_mfma_f32_16x16x32_bf16 v[56:59], v[172:175], v[180:183], v[56:59]
	v_mfma_f32_16x16x32_bf16 v[52:55], v[168:171], v[188:191], v[52:55]
	v_mfma_f32_16x16x32_bf16 v[48:51], v[172:175], v[188:191], v[48:51]
	v_mfma_f32_16x16x32_bf16 v[44:47], v[168:171], v[196:199], v[44:47]
	v_mfma_f32_16x16x32_bf16 v[40:43], v[172:175], v[196:199], v[40:43]
	v_mfma_f32_16x16x32_bf16 v[36:39], v[168:171], v[204:207], v[36:39]
	v_mfma_f32_16x16x32_bf16 v[32:35], v[172:175], v[204:207], v[32:35]
	s_setprio 0
	s_setprio 1
	v_mfma_f32_16x16x32_bf16 v[28:31], v[208:211], v[176:179], v[28:31]
	v_mfma_f32_16x16x32_bf16 v[24:27], v[212:215], v[176:179], v[24:27]
	v_mfma_f32_16x16x32_bf16 v[20:23], v[208:211], v[184:187], v[20:23]
	v_mfma_f32_16x16x32_bf16 v[16:19], v[212:215], v[184:187], v[16:19]
	v_mfma_f32_16x16x32_bf16 v[12:15], v[208:211], v[192:195], v[12:15]
	v_mfma_f32_16x16x32_bf16 v[8:11], v[212:215], v[192:195], v[8:11]
	v_mfma_f32_16x16x32_bf16 v[4:7], v[208:211], v[200:203], v[4:7]
	v_mfma_f32_16x16x32_bf16 v[0:3], v[212:215], v[200:203], v[0:3]
	v_mfma_f32_16x16x32_bf16 v[28:31], v[216:219], v[180:183], v[28:31]
	v_mfma_f32_16x16x32_bf16 v[24:27], v[220:223], v[180:183], v[24:27]
	v_mfma_f32_16x16x32_bf16 v[20:23], v[216:219], v[188:191], v[20:23]
	v_mfma_f32_16x16x32_bf16 v[16:19], v[220:223], v[188:191], v[16:19]
	v_mfma_f32_16x16x32_bf16 v[12:15], v[216:219], v[196:199], v[12:15]
	v_mfma_f32_16x16x32_bf16 v[8:11], v[220:223], v[196:199], v[8:11]
	v_mfma_f32_16x16x32_bf16 v[4:7], v[216:219], v[204:207], v[4:7]
	v_mfma_f32_16x16x32_bf16 v[0:3], v[220:223], v[204:207], v[0:3]
	s_setprio 0
	s_add_i32 s76, s76, 2
	s_add_u32 s62, s62, 0x100
	s_addc_u32 s63, s63, 0
	s_add_u32 s64, s64, 0x100
	s_addc_u32 s65, s65, 0
	s_add_u32 s66, s66, 0x100
	s_addc_u32 s67, s67, 0
	s_cmpk_lt_u32 s76, 0x54
	s_barrier
	s_cbranch_scc1 .LBB0_324
	s_add_u32 s62, s70, s75
	s_addc_u32 s63, s71, s74
	v_lshl_add_u64 v[208:209], s[62:63], 0, v[128:129]
	v_readfirstlane_b32 s62, v150
	s_mov_b32 m0, s62
	v_readfirstlane_b32 s62, v151
	ds_read_b128 v[160:163], v152
	ds_read_b128 v[164:167], v152 offset:256
	ds_read_b128 v[168:171], v153
	ds_read_b128 v[172:175], v153 offset:256
	ds_read_b128 v[176:179], v149
	ds_read_b128 v[180:183], v149 offset:1024
	ds_read_b128 v[184:187], v149 offset:2048
	ds_read_b128 v[188:191], v149 offset:3072
	ds_read_b128 v[192:195], v149 offset:4096
	ds_read_b128 v[196:199], v149 offset:5120
	ds_read_b128 v[200:203], v149 offset:6144
	ds_read_b128 v[204:207], v149 offset:7168
	global_load_lds_dwordx4 v[208:209], off
	v_lshl_add_u64 v[208:209], v[208:209], 0, s[8:9]
	s_mov_b32 m0, s62
	s_nop 0
	global_load_lds_dwordx4 v[208:209], off
	s_barrier
	s_waitcnt lgkmcnt(0)
	s_setprio 1
	s_waitcnt lgkmcnt(0)
	v_mfma_f32_16x16x32_bf16 v[124:127], v[160:163], v[176:179], v[124:127]
	v_mfma_f32_16x16x32_bf16 v[116:119], v[160:163], v[184:187], v[116:119]
	v_mfma_f32_16x16x32_bf16 v[108:111], v[160:163], v[192:195], v[108:111]
	v_mfma_f32_16x16x32_bf16 v[100:103], v[160:163], v[200:203], v[100:103]
	v_mfma_f32_16x16x32_bf16 v[96:99], v[164:167], v[200:203], v[96:99]
	v_mfma_f32_16x16x32_bf16 v[124:127], v[168:171], v[180:183], v[124:127]
	v_mfma_f32_16x16x32_bf16 v[120:123], v[164:167], v[176:179], v[120:123]
	v_mfma_f32_16x16x32_bf16 v[116:119], v[168:171], v[188:191], v[116:119]
	v_mfma_f32_16x16x32_bf16 v[112:115], v[164:167], v[184:187], v[112:115]
	v_mfma_f32_16x16x32_bf16 v[108:111], v[168:171], v[196:199], v[108:111]
	v_mfma_f32_16x16x32_bf16 v[104:107], v[164:167], v[192:195], v[104:107]
	v_mfma_f32_16x16x32_bf16 v[100:103], v[168:171], v[204:207], v[100:103]
	v_mfma_f32_16x16x32_bf16 v[96:99], v[172:175], v[204:207], v[96:99]
	v_mfma_f32_16x16x32_bf16 v[208:211], v[172:175], v[180:183], v[120:123]
	v_mfma_f32_16x16x32_bf16 v[212:215], v[172:175], v[188:191], v[112:115]
	v_mfma_f32_16x16x32_bf16 v[216:219], v[172:175], v[196:199], v[104:107]
	s_setprio 0
	s_barrier
; #define LDA(dst, b, h) for (int m = 0; m < 4; ++m) { \
;     dst[m][0] = *reinterpret_cast<const bf16x8*>((char*)SA(b, h) + aoff0 + m * 2048); \
;     dst[m][1] = *reinterpret_cast<const bf16x8*>((char*)SA(b, h) + aoff1 + m * 2048); }
; #define LDB(dst, b, h) for (int n = 0; n < 2; ++n) { \
;     dst[n][0] = *reinterpret_cast<const bf16x8*>((char*)SB(b, h) + boff0 + n * 256); \
;     dst[n][1] = *reinterpret_cast<const bf16x8*>((char*)SB(b, h) + boff1 + n * 256); }
; #define MMA(ai, bj, At, Btf) do { __builtin_amdgcn_s_setprio(1); \
;     for (int m = 0; m < 4; ++m) for (int n = 0; n < 2; ++n) for (int k = 0; k < 2; ++k) \
;       acc[ai][bj][m][n] = __builtin_amdgcn_mfma_f32_16x16x32_bf16(Btf[n][k], At[m][k], acc[ai][bj][m][n], 0, 0, 0); \
;     __builtin_amdgcn_s_setprio(0); } while (0)
; #define WAIT_V(n) asm volatile("s_waitcnt vmcnt(" #n ")" ::: "memory")
; #define WAIT_L(n) asm volatile("s_waitcnt lgkmcnt(" #n ")" ::: "memory")
; #define BAR __builtin_amdgcn_s_barrier()
; template <int EPI> ...
;     ...
;     LDB(B1, 0, 1); BAR; WAIT_L(0); MMA(0, 1, At, B1); BAR;
;     LDA(At, 0, 1); WAIT_V(4); BAR; WAIT_L(0); MMA(1, 0, At, B0); MMA(1, 1, At, B1); BAR; }
;   { LDB(B0, 1, 0); LDA(At, 1, 0); WAIT_V(2); BAR; WAIT_L(0); MMA(0, 0, At, B0); BAR;
	s_nop 0
	ds_read_b128 v[104:107], v154
	ds_read_b128 v[112:115], v154 offset:256
	ds_read_b128 v[120:123], v155
	ds_read_b128 v[220:223], v155 offset:256
	s_barrier
	s_waitcnt lgkmcnt(0)
	s_setprio 1
	s_waitcnt lgkmcnt(0)
	v_mfma_f32_16x16x32_bf16 v[84:87], v[104:107], v[184:187], v[84:87]
	v_mfma_f32_16x16x32_bf16 v[76:79], v[104:107], v[192:195], v[76:79]
	v_mfma_f32_16x16x32_bf16 v[72:75], v[112:115], v[192:195], v[72:75]
	v_mfma_f32_16x16x32_bf16 v[92:95], v[104:107], v[176:179], v[92:95]
	v_mfma_f32_16x16x32_bf16 v[88:91], v[112:115], v[176:179], v[88:91]
	v_mfma_f32_16x16x32_bf16 v[84:87], v[120:123], v[188:191], v[84:87]
	v_mfma_f32_16x16x32_bf16 v[80:83], v[112:115], v[184:187], v[80:83]
	v_mfma_f32_16x16x32_bf16 v[76:79], v[120:123], v[196:199], v[76:79]
	v_mfma_f32_16x16x32_bf16 v[72:75], v[220:223], v[196:199], v[72:75]
	v_mfma_f32_16x16x32_bf16 v[68:71], v[104:107], v[200:203], v[68:71]
	v_mfma_f32_16x16x32_bf16 v[64:67], v[112:115], v[200:203], v[64:67]
	v_mfma_f32_16x16x32_bf16 v[224:227], v[120:123], v[180:183], v[92:95]
	v_mfma_f32_16x16x32_bf16 v[176:179], v[220:223], v[180:183], v[88:91]
	v_mfma_f32_16x16x32_bf16 v[180:183], v[220:223], v[188:191], v[80:83]
	v_mfma_f32_16x16x32_bf16 v[184:187], v[120:123], v[204:207], v[68:71]
	v_mfma_f32_16x16x32_bf16 v[188:191], v[220:223], v[204:207], v[64:67]
	s_setprio 0
	s_barrier
	s_nop 0
	ds_read_b128 v[64:67], v149 offset:16384
	ds_read_b128 v[68:71], v149 offset:17408
	ds_read_b128 v[80:83], v149 offset:18432
	ds_read_b128 v[88:91], v149 offset:19456
	ds_read_b128 v[92:95], v149 offset:20480
	ds_read_b128 v[192:195], v149 offset:21504
	ds_read_b128 v[196:199], v149 offset:22528
	ds_read_b128 v[200:203], v149 offset:23552
	s_waitcnt vmcnt(4)
	s_barrier
	s_waitcnt lgkmcnt(0)
	s_setprio 1
	s_waitcnt lgkmcnt(0)
	v_mfma_f32_16x16x32_bf16 v[52:55], v[160:163], v[80:83], v[52:55]
	v_mfma_f32_16x16x32_bf16 v[44:47], v[160:163], v[92:95], v[44:47]
	v_mfma_f32_16x16x32_bf16 v[36:39], v[160:163], v[196:199], v[36:39]
	v_mfma_f32_16x16x32_bf16 v[60:63], v[160:163], v[64:67], v[60:63]
	v_mfma_f32_16x16x32_bf16 v[56:59], v[164:167], v[64:67], v[56:59]
	v_mfma_f32_16x16x32_bf16 v[52:55], v[168:171], v[88:91], v[52:55]
	v_mfma_f32_16x16x32_bf16 v[48:51], v[164:167], v[80:83], v[48:51]
	v_mfma_f32_16x16x32_bf16 v[44:47], v[168:171], v[192:195], v[44:47]
	v_mfma_f32_16x16x32_bf16 v[40:43], v[164:167], v[92:95], v[40:43]
	v_mfma_f32_16x16x32_bf16 v[36:39], v[168:171], v[200:203], v[36:39]
	v_mfma_f32_16x16x32_bf16 v[32:35], v[164:167], v[196:199], v[32:35]
	v_mfma_f32_16x16x32_bf16 v[204:207], v[168:171], v[68:71], v[60:63]
	v_mfma_f32_16x16x32_bf16 v[228:231], v[172:175], v[68:71], v[56:59]
	v_mfma_f32_16x16x32_bf16 v[232:235], v[172:175], v[88:91], v[48:51]
	v_mfma_f32_16x16x32_bf16 v[236:239], v[172:175], v[192:195], v[40:43]
	v_mfma_f32_16x16x32_bf16 v[160:163], v[172:175], v[200:203], v[32:35]
	s_setprio 0
	s_setprio 1
	v_mfma_f32_16x16x32_bf16 v[28:31], v[104:107], v[64:67], v[28:31]
	v_mfma_f32_16x16x32_bf16 v[20:23], v[104:107], v[80:83], v[20:23]
	v_mfma_f32_16x16x32_bf16 v[12:15], v[104:107], v[92:95], v[12:15]
	v_mfma_f32_16x16x32_bf16 v[4:7], v[104:107], v[196:199], v[4:7]
	v_mfma_f32_16x16x32_bf16 v[28:31], v[120:123], v[68:71], v[28:31]
	v_mfma_f32_16x16x32_bf16 v[24:27], v[112:115], v[64:67], v[24:27]
	v_mfma_f32_16x16x32_bf16 v[20:23], v[120:123], v[88:91], v[20:23]
	v_mfma_f32_16x16x32_bf16 v[16:19], v[112:115], v[80:83], v[16:19]
	v_mfma_f32_16x16x32_bf16 v[12:15], v[120:123], v[192:195], v[12:15]
	v_mfma_f32_16x16x32_bf16 v[8:11], v[112:115], v[92:95], v[8:11]
	v_mfma_f32_16x16x32_bf16 v[4:7], v[120:123], v[200:203], v[4:7]
	v_mfma_f32_16x16x32_bf16 v[0:3], v[112:115], v[196:199], v[0:3]
	v_mfma_f32_16x16x32_bf16 v[164:167], v[220:223], v[68:71], v[24:27]
	v_mfma_f32_16x16x32_bf16 v[168:171], v[220:223], v[88:91], v[16:19]
	v_mfma_f32_16x16x32_bf16 v[172:175], v[220:223], v[192:195], v[8:11]
	v_mfma_f32_16x16x32_bf16 v[192:195], v[220:223], v[200:203], v[0:3]
	s_setprio 0
	s_barrier
	s_nop 1
	ds_read_b128 v[0:3], v156
	ds_read_b128 v[8:11], v156 offset:256
	ds_read_b128 v[16:19], v157
	ds_read_b128 v[24:27], v157 offset:256
	ds_read_b128 v[32:35], v149 offset:32768
	ds_read_b128 v[40:43], v149 offset:33792
	ds_read_b128 v[48:51], v149 offset:34816
	ds_read_b128 v[56:59], v149 offset:35840
	ds_read_b128 v[60:63], v149 offset:36864
	ds_read_b128 v[68:71], v149 offset:37888
	ds_read_b128 v[196:199], v149 offset:38912
	ds_read_b128 v[200:203], v149 offset:39936
	s_waitcnt vmcnt(2)
	s_barrier
; #define LDA(dst, b, h) for (int m = 0; m < 4; ++m) { \
;     dst[m][0] = *reinterpret_cast<const bf16x8*>((char*)SA(b, h) + aoff0 + m * 2048); \
;     dst[m][1] = *reinterpret_cast<const bf16x8*>((char*)SA(b, h) + aoff1 + m * 2048); }
; #define LDB(dst, b, h) for (int n = 0; n < 2; ++n) { \
;     dst[n][0] = *reinterpret_cast<const bf16x8*>((char*)SB(b, h) + boff0 + n * 256); \
;     dst[n][1] = *reinterpret_cast<const bf16x8*>((char*)SB(b, h) + boff1 + n * 256); }
; #define MMA(ai, bj, At, Btf) do { __builtin_amdgcn_s_setprio(1); \
;     for (int m = 0; m < 4; ++m) for (int n = 0; n < 2; ++n) for (int k = 0; k < 2; ++k) \
;       acc[ai][bj][m][n] = __builtin_amdgcn_mfma_f32_16x16x32_bf16(Btf[n][k], At[m][k], acc[ai][bj][m][n], 0, 0, 0); \
;     __builtin_amdgcn_s_setprio(0); } while (0)
; #define WAIT_V(n) asm volatile("s_waitcnt vmcnt(" #n ")" ::: "memory")
; #define WAIT_L(n) asm volatile("s_waitcnt lgkmcnt(" #n ")" ::: "memory")
; #define BAR __builtin_amdgcn_s_barrier()
; template <int EPI> ...
;     ...
;   { LDB(B0, 1, 0); LDA(At, 1, 0); WAIT_V(2); BAR; WAIT_L(0); MMA(0, 0, At, B0); BAR;
;     LDB(B1, 1, 1); WAIT_V(0); BAR; WAIT_L(0); MMA(0, 1, At, B1); BAR;
;     LDA(At, 1, 1); BAR; WAIT_L(0); MMA(1, 0, At, B0); MMA(1, 1, At, B1); BAR; }
;   if (wr == 0) BAR;
	s_waitcnt lgkmcnt(0)
	s_setprio 1
	s_waitcnt lgkmcnt(0)
	v_mfma_f32_16x16x32_bf16 v[64:67], v[0:3], v[32:35], v[124:127]
	v_mfma_f32_16x16x32_bf16 v[120:123], v[16:19], v[40:43], v[64:67]
	v_mfma_f32_16x16x32_bf16 v[64:67], v[8:11], v[32:35], v[208:211]
	v_mfma_f32_16x16x32_bf16 v[124:127], v[24:27], v[40:43], v[64:67]
	v_mfma_f32_16x16x32_bf16 v[64:67], v[0:3], v[48:51], v[116:119]
	v_mfma_f32_16x16x32_bf16 v[112:115], v[16:19], v[56:59], v[64:67]
	v_mfma_f32_16x16x32_bf16 v[64:67], v[8:11], v[48:51], v[212:215]
	v_mfma_f32_16x16x32_bf16 v[116:119], v[24:27], v[56:59], v[64:67]
	v_mfma_f32_16x16x32_bf16 v[64:67], v[0:3], v[60:63], v[108:111]
	v_mfma_f32_16x16x32_bf16 v[104:107], v[16:19], v[68:71], v[64:67]
	v_mfma_f32_16x16x32_bf16 v[64:67], v[8:11], v[60:63], v[216:219]
	v_mfma_f32_16x16x32_bf16 v[108:111], v[24:27], v[68:71], v[64:67]
	v_mfma_f32_16x16x32_bf16 v[64:67], v[0:3], v[196:199], v[100:103]
	v_mfma_f32_16x16x32_bf16 v[88:91], v[16:19], v[200:203], v[64:67]
	v_mfma_f32_16x16x32_bf16 v[64:67], v[8:11], v[196:199], v[96:99]
	v_mfma_f32_16x16x32_bf16 v[92:95], v[24:27], v[200:203], v[64:67]
	s_setprio 0
	s_barrier
	ds_read_b128 v[208:211], v158
	ds_read_b128 v[212:215], v158 offset:256
	ds_read_b128 v[216:219], v159
	ds_read_b128 v[220:223], v159 offset:256
	s_waitcnt vmcnt(0)
	s_barrier
	s_waitcnt lgkmcnt(0)
	s_setprio 1
	s_waitcnt lgkmcnt(0)
	v_mfma_f32_16x16x32_bf16 v[64:67], v[208:211], v[32:35], v[224:227]
	v_mfma_f32_16x16x32_bf16 v[32:35], v[212:215], v[32:35], v[176:179]
	v_mfma_f32_16x16x32_bf16 v[100:103], v[220:223], v[40:43], v[32:35]
	v_mfma_f32_16x16x32_bf16 v[32:35], v[208:211], v[48:51], v[84:87]
	v_mfma_f32_16x16x32_bf16 v[80:83], v[216:219], v[56:59], v[32:35]
	v_mfma_f32_16x16x32_bf16 v[32:35], v[212:215], v[48:51], v[180:183]
	v_mfma_f32_16x16x32_bf16 v[84:87], v[220:223], v[56:59], v[32:35]
	v_mfma_f32_16x16x32_bf16 v[32:35], v[208:211], v[60:63], v[76:79]
	v_mfma_f32_16x16x32_bf16 v[96:99], v[216:219], v[40:43], v[64:67]
	v_mfma_f32_16x16x32_bf16 v[64:67], v[216:219], v[68:71], v[32:35]
	v_mfma_f32_16x16x32_bf16 v[32:35], v[212:215], v[60:63], v[72:75]
	v_mfma_f32_16x16x32_bf16 v[68:71], v[220:223], v[68:71], v[32:35]
	v_mfma_f32_16x16x32_bf16 v[32:35], v[208:211], v[196:199], v[184:187]
	v_mfma_f32_16x16x32_bf16 v[56:59], v[216:219], v[200:203], v[32:35]
	v_mfma_f32_16x16x32_bf16 v[32:35], v[212:215], v[196:199], v[188:191]
	v_mfma_f32_16x16x32_bf16 v[60:63], v[220:223], v[200:203], v[32:35]
	s_setprio 0
	s_barrier
	ds_read_b128 v[176:179], v149 offset:49152
	ds_read_b128 v[180:183], v149 offset:50176
	ds_read_b128 v[184:187], v149 offset:51200
	ds_read_b128 v[188:191], v149 offset:52224
	ds_read_b128 v[196:199], v149 offset:53248
	ds_read_b128 v[200:203], v149 offset:54272
	ds_read_b128 v[224:227], v149 offset:55296
	ds_read_b128 v[240:243], v149 offset:56320
	s_barrier
	s_waitcnt lgkmcnt(0)
	s_setprio 1
	s_waitcnt lgkmcnt(0)
	v_mfma_f32_16x16x32_bf16 v[32:35], v[0:3], v[176:179], v[204:207]
	v_mfma_f32_16x16x32_bf16 v[72:75], v[16:19], v[180:183], v[32:35]
	v_mfma_f32_16x16x32_bf16 v[32:35], v[8:11], v[176:179], v[228:231]
	v_mfma_f32_16x16x32_bf16 v[76:79], v[24:27], v[180:183], v[32:35]
	v_mfma_f32_16x16x32_bf16 v[32:35], v[0:3], v[184:187], v[52:55]
	v_mfma_f32_16x16x32_bf16 v[48:51], v[16:19], v[188:191], v[32:35]
	v_mfma_f32_16x16x32_bf16 v[32:35], v[8:11], v[184:187], v[232:235]
	v_mfma_f32_16x16x32_bf16 v[52:55], v[24:27], v[188:191], v[32:35]
	v_mfma_f32_16x16x32_bf16 v[32:35], v[0:3], v[196:199], v[44:47]
	v_mfma_f32_16x16x32_bf16 v[40:43], v[16:19], v[200:203], v[32:35]
	v_mfma_f32_16x16x32_bf16 v[32:35], v[8:11], v[196:199], v[236:239]
	v_mfma_f32_16x16x32_bf16 v[0:3], v[0:3], v[224:227], v[36:39]
	v_mfma_f32_16x16x32_bf16 v[44:47], v[24:27], v[200:203], v[32:35]
	v_mfma_f32_16x16x32_bf16 v[32:35], v[16:19], v[240:243], v[0:3]
	v_mfma_f32_16x16x32_bf16 v[0:3], v[8:11], v[224:227], v[160:163]
	v_mfma_f32_16x16x32_bf16 v[36:39], v[24:27], v[240:243], v[0:3]
	s_setprio 0
	s_setprio 1
	v_mfma_f32_16x16x32_bf16 v[0:3], v[208:211], v[176:179], v[28:31]
	v_mfma_f32_16x16x32_bf16 v[24:27], v[216:219], v[180:183], v[0:3]
	v_mfma_f32_16x16x32_bf16 v[0:3], v[212:215], v[176:179], v[164:167]
	v_mfma_f32_16x16x32_bf16 v[28:31], v[220:223], v[180:183], v[0:3]
	v_mfma_f32_16x16x32_bf16 v[0:3], v[208:211], v[184:187], v[20:23]
	v_mfma_f32_16x16x32_bf16 v[16:19], v[216:219], v[188:191], v[0:3]
	v_mfma_f32_16x16x32_bf16 v[0:3], v[212:215], v[184:187], v[168:171]
	v_mfma_f32_16x16x32_bf16 v[20:23], v[220:223], v[188:191], v[0:3]
	v_mfma_f32_16x16x32_bf16 v[0:3], v[208:211], v[196:199], v[12:15]
	v_mfma_f32_16x16x32_bf16 v[8:11], v[216:219], v[200:203], v[0:3]
	v_mfma_f32_16x16x32_bf16 v[0:3], v[212:215], v[196:199], v[172:175]
	v_mfma_f32_16x16x32_bf16 v[12:15], v[220:223], v[200:203], v[0:3]
	v_mfma_f32_16x16x32_bf16 v[0:3], v[208:211], v[224:227], v[4:7]
	v_mfma_f32_16x16x32_bf16 v[4:7], v[212:215], v[224:227], v[192:195]
	v_mfma_f32_16x16x32_bf16 v[0:3], v[216:219], v[240:243], v[0:3]
	v_mfma_f32_16x16x32_bf16 v[4:7], v[220:223], v[240:243], v[4:7]
	s_setprio 0
	s_barrier
	s_and_saveexec_b64 s[62:63], s[2:3]
	s_cbranch_execz .LBB0_318
	s_barrier
	s_branch .LBB0_318

; #define STAGE(P, BASE, br, kt) do { const char* _gb = (const char*)(BASE) + ((size_t)(br) * K + (size_t)(kt) * BK) * 2; \
;     __builtin_amdgcn_global_load_lds((const unsigned*)(_gb + loff0), (unsigned*)((char*)(P) + tid * 16), 16, 0, 0); \
;     __builtin_amdgcn_global_load_lds((const unsigned*)(_gb + (size_t)K * 128 + loff0), (unsigned*)((char*)(P) + tid * 16 + 8192), 16, 0, 0); } while (0)
; #define LDA(dst, b, h) for (int m = 0; m < 4; ++m) { \
;     dst[m][0] = *reinterpret_cast<const bf16x8*>((char*)SA(b, h) + aoff0 + m * 2048); \
;     dst[m][1] = *reinterpret_cast<const bf16x8*>((char*)SA(b, h) + aoff1 + m * 2048); }
; #define LDB(dst, b, h) for (int n = 0; n < 2; ++n) { \
;     dst[n][0] = *reinterpret_cast<const bf16x8*>((char*)SB(b, h) + boff0 + n * 256); \
;     dst[n][1] = *reinterpret_cast<const bf16x8*>((char*)SB(b, h) + boff1 + n * 256); }
; #define MMA(ai, bj, At, Btf) do { __builtin_amdgcn_s_setprio(1); \
;     for (int m = 0; m < 4; ++m) for (int n = 0; n < 2; ++n) for (int k = 0; k < 2; ++k) \
;       acc[ai][bj][m][n] = __builtin_amdgcn_mfma_f32_16x16x32_bf16(Btf[n][k], At[m][k], acc[ai][bj][m][n], 0, 0, 0); \
;     __builtin_amdgcn_s_setprio(0); } while (0)
; #define WAIT_V(n) asm volatile("s_waitcnt vmcnt(" #n ")" ::: "memory")
; #define WAIT_L(n) asm volatile("s_waitcnt lgkmcnt(" #n ")" ::: "memory")
; #define BAR __builtin_amdgcn_s_barrier()
; #define SCHED __builtin_amdgcn_sched_barrier(0)
; template <int EPI> ...
;     ...
;   WAIT_V(4); BAR;
;   STAGE(SB(1, 0), Bt, bcol, 1); STAGE(SA(1, 0), A, brow, 1); STAGE(SB(1, 1), Bt, bcol + HALF, 1);
;   WAIT_V(6); BAR;
;   for (int t = 0; t < nt - 2; t += 2) {
;     LDB(B0, 0, 0); SCHED; LDA(At, 0, 0); STAGE(SA(1, 1), A, brow + HALF, t + 1);
;     WAIT_L(8); BAR; WAIT_L(0); MMA(0, 0, At, B0); BAR; SCHED;
;     LDB(B1, 0, 1); STAGE(SB(0, 0), Bt, bcol, t + 2);
;     BAR; WAIT_L(0); MMA(0, 1, At, B1); BAR;
;     LDA(At, 0, 1); STAGE(SA(0, 0), A, brow, t + 2);
;     BAR; WAIT_L(0); MMA(1, 0, At, B0); BAR; SCHED;
;     STAGE(SB(0, 1), Bt, bcol + HALF, t + 2);
;     WAIT_V(6); BAR; MMA(1, 1, At, B1); BAR;
.LBB0_410:
	s_or_b64 exec, exec, s[70:71]
	v_readfirstlane_b32 s61, v143
	v_lshl_add_u64 v[6:7], v[0:1], 0, s[10:11]
	s_mov_b32 m0, s61
	v_readfirstlane_b32 s61, v144
	s_waitcnt vmcnt(2)
	s_barrier
	global_load_lds_dwordx4 v[6:7], off
	v_lshl_add_u64 v[0:1], v[0:1], 0, s[12:13]
	s_mov_b32 m0, s61
	v_readfirstlane_b32 s61, v145
	global_load_lds_dwordx4 v[0:1], off
	v_lshl_add_u64 v[0:1], v[2:3], 0, s[10:11]
	s_mov_b32 m0, s61
	v_readfirstlane_b32 s61, v146
	global_load_lds_dwordx4 v[0:1], off
	v_lshl_add_u64 v[0:1], v[2:3], 0, s[12:13]
	s_mov_b32 m0, s61
	v_readfirstlane_b32 s61, v147
	global_load_lds_dwordx4 v[0:1], off
	v_lshl_add_u64 v[0:1], v[4:5], 0, s[10:11]
	s_mov_b32 m0, s61
	v_readfirstlane_b32 s61, v148
	global_load_lds_dwordx4 v[0:1], off
	v_lshl_add_u64 v[0:1], v[4:5], 0, s[12:13]
	s_mov_b32 m0, s61
	s_add_u32 s66, s6, s66
	global_load_lds_dwordx4 v[0:1], off
	s_addc_u32 s67, s7, s67
	s_add_u32 s68, s6, s68
	v_mov_b32_e32 v0, 0
	s_addc_u32 s69, s7, s69
	s_mov_b32 s61, -2
	v_mov_b32_e32 v1, v0
	v_mov_b32_e32 v2, v0
	v_mov_b32_e32 v3, v0
	v_mov_b32_e32 v4, v0
	v_mov_b32_e32 v5, v0
	v_mov_b32_e32 v6, v0
	v_mov_b32_e32 v7, v0
	s_waitcnt vmcnt(6)
	s_barrier
.LBB0_411:
	ds_read_b128 v[160:163], v152
	ds_read_b128 v[164:167], v152 offset:256
	ds_read_b128 v[168:171], v153
	ds_read_b128 v[172:175], v153 offset:256
	v_lshl_add_u64 v[224:225], s[68:69], 0, v[132:133]
	v_readfirstlane_b32 s70, v150
	v_lshl_add_u64 v[208:209], v[224:225], 0, s[16:17]
	s_mov_b32 m0, s70
	v_readfirstlane_b32 s70, v151
	ds_read_b128 v[176:179], v149
	ds_read_b128 v[180:183], v149 offset:1024
	ds_read_b128 v[184:187], v149 offset:2048
	ds_read_b128 v[188:191], v149 offset:3072
	ds_read_b128 v[192:195], v149 offset:4096
	ds_read_b128 v[196:199], v149 offset:5120
	ds_read_b128 v[200:203], v149 offset:6144
	ds_read_b128 v[204:207], v149 offset:7168
	global_load_lds_dwordx4 v[208:209], off
	v_lshl_add_u64 v[208:209], v[224:225], 0, s[18:19]
	s_mov_b32 m0, s70
	s_nop 0
	global_load_lds_dwordx4 v[208:209], off
	s_waitcnt lgkmcnt(8)
	ds_read_b128 v[208:211], v154
	ds_read_b128 v[212:215], v154 offset:256
	ds_read_b128 v[216:219], v155
	ds_read_b128 v[220:223], v155 offset:256
	s_barrier
	s_waitcnt lgkmcnt(0)
	s_setprio 1
	s_waitcnt lgkmcnt(0)
	v_mfma_f32_16x16x32_bf16 v[124:127], v[160:163], v[176:179], v[124:127]
	v_mfma_f32_16x16x32_bf16 v[120:123], v[164:167], v[176:179], v[120:123]
	v_mfma_f32_16x16x32_bf16 v[116:119], v[160:163], v[184:187], v[116:119]
	v_mfma_f32_16x16x32_bf16 v[112:115], v[164:167], v[184:187], v[112:115]
	v_mfma_f32_16x16x32_bf16 v[108:111], v[160:163], v[192:195], v[108:111]
	v_mfma_f32_16x16x32_bf16 v[104:107], v[164:167], v[192:195], v[104:107]
	v_mfma_f32_16x16x32_bf16 v[100:103], v[160:163], v[200:203], v[100:103]
	v_mfma_f32_16x16x32_bf16 v[96:99], v[164:167], v[200:203], v[96:99]
	v_mfma_f32_16x16x32_bf16 v[124:127], v[168:171], v[180:183], v[124:127]
	v_mfma_f32_16x16x32_bf16 v[120:123], v[172:175], v[180:183], v[120:123]
	v_mfma_f32_16x16x32_bf16 v[116:119], v[168:171], v[188:191], v[116:119]
	v_mfma_f32_16x16x32_bf16 v[112:115], v[172:175], v[188:191], v[112:115]
	v_mfma_f32_16x16x32_bf16 v[108:111], v[168:171], v[196:199], v[108:111]
	v_mfma_f32_16x16x32_bf16 v[104:107], v[172:175], v[196:199], v[104:107]
	v_mfma_f32_16x16x32_bf16 v[100:103], v[168:171], v[204:207], v[100:103]
	v_mfma_f32_16x16x32_bf16 v[96:99], v[172:175], v[204:207], v[96:99]
	s_setprio 0
	s_waitcnt lgkmcnt(0)
	s_setprio 1
	s_waitcnt lgkmcnt(0)
	v_mfma_f32_16x16x32_bf16 v[92:95], v[208:211], v[176:179], v[92:95]
	v_mfma_f32_16x16x32_bf16 v[88:91], v[212:215], v[176:179], v[88:91]
	v_mfma_f32_16x16x32_bf16 v[84:87], v[208:211], v[184:187], v[84:87]
	v_mfma_f32_16x16x32_bf16 v[80:83], v[212:215], v[184:187], v[80:83]
	v_mfma_f32_16x16x32_bf16 v[76:79], v[208:211], v[192:195], v[76:79]
	v_mfma_f32_16x16x32_bf16 v[72:75], v[212:215], v[192:195], v[72:75]
	v_mfma_f32_16x16x32_bf16 v[68:71], v[208:211], v[200:203], v[68:71]
	v_mfma_f32_16x16x32_bf16 v[64:67], v[212:215], v[200:203], v[64:67]
	v_mfma_f32_16x16x32_bf16 v[92:95], v[216:219], v[180:183], v[92:95]
	v_mfma_f32_16x16x32_bf16 v[88:91], v[220:223], v[180:183], v[88:91]
	v_mfma_f32_16x16x32_bf16 v[84:87], v[216:219], v[188:191], v[84:87]
	v_mfma_f32_16x16x32_bf16 v[80:83], v[220:223], v[188:191], v[80:83]
	v_mfma_f32_16x16x32_bf16 v[76:79], v[216:219], v[196:199], v[76:79]
	v_mfma_f32_16x16x32_bf16 v[72:75], v[220:223], v[196:199], v[72:75]
	v_mfma_f32_16x16x32_bf16 v[68:71], v[216:219], v[204:207], v[68:71]
	v_mfma_f32_16x16x32_bf16 v[64:67], v[220:223], v[204:207], v[64:67]
	s_setprio 0
	s_barrier
	v_lshl_add_u64 v[226:227], s[66:67], 0, v[132:133]
	v_readfirstlane_b32 s70, v135
	v_lshl_add_u64 v[228:229], v[226:227], 0, s[20:21]
	s_mov_b32 m0, s70
	v_readfirstlane_b32 s70, v136
	global_load_lds_dwordx4 v[228:229], off
	v_lshl_add_u64 v[228:229], v[226:227], 0, s[22:23]
	s_mov_b32 m0, s70
	s_nop 0
	global_load_lds_dwordx4 v[228:229], off
	v_readfirstlane_b32 s70, v137
	v_lshl_add_u64 v[228:229], v[224:225], 0, s[26:27]
	s_mov_b32 m0, s70
	v_readfirstlane_b32 s70, v138
	ds_read_b128 v[176:179], v149 offset:16384
	ds_read_b128 v[180:183], v149 offset:17408
	ds_read_b128 v[184:187], v149 offset:18432
	ds_read_b128 v[188:191], v149 offset:19456
	ds_read_b128 v[192:195], v149 offset:20480
	ds_read_b128 v[196:199], v149 offset:21504
	ds_read_b128 v[200:203], v149 offset:22528
	ds_read_b128 v[204:207], v149 offset:23552
	global_load_lds_dwordx4 v[228:229], off
	v_lshl_add_u64 v[228:229], v[224:225], 0, s[28:29]
	s_mov_b32 m0, s70
	s_nop 0
	global_load_lds_dwordx4 v[228:229], off
	v_readfirstlane_b32 s70, v139
	v_lshl_add_u64 v[246:247], v[226:227], 0, s[30:31]
	s_mov_b32 m0, s70
	v_readfirstlane_b32 s70, v140
	global_load_lds_dwordx4 v[246:247], off
	v_lshl_add_u64 v[246:247], v[226:227], 0, s[36:37]
	s_mov_b32 m0, s70
	s_nop 0
	global_load_lds_dwordx4 v[246:247], off
	s_waitcnt vmcnt(6)
	s_barrier
; #define STAGE(P, BASE, br, kt) do { const char* _gb = (const char*)(BASE) + ((size_t)(br) * K + (size_t)(kt) * BK) * 2; \
;     __builtin_amdgcn_global_load_lds((const unsigned*)(_gb + loff0), (unsigned*)((char*)(P) + tid * 16), 16, 0, 0); \
;     __builtin_amdgcn_global_load_lds((const unsigned*)(_gb + (size_t)K * 128 + loff0), (unsigned*)((char*)(P) + tid * 16 + 8192), 16, 0, 0); } while (0)
; #define LDA(dst, b, h) for (int m = 0; m < 4; ++m) { \
;     dst[m][0] = *reinterpret_cast<const bf16x8*>((char*)SA(b, h) + aoff0 + m * 2048); \
;     dst[m][1] = *reinterpret_cast<const bf16x8*>((char*)SA(b, h) + aoff1 + m * 2048); }
; #define LDB(dst, b, h) for (int n = 0; n < 2; ++n) { \
;     dst[n][0] = *reinterpret_cast<const bf16x8*>((char*)SB(b, h) + boff0 + n * 256); \
;     dst[n][1] = *reinterpret_cast<const bf16x8*>((char*)SB(b, h) + boff1 + n * 256); }
; #define MMA(ai, bj, At, Btf) do { __builtin_amdgcn_s_setprio(1); \
;     for (int m = 0; m < 4; ++m) for (int n = 0; n < 2; ++n) for (int k = 0; k < 2; ++k) \
;       acc[ai][bj][m][n] = __builtin_amdgcn_mfma_f32_16x16x32_bf16(Btf[n][k], At[m][k], acc[ai][bj][m][n], 0, 0, 0); \
;     __builtin_amdgcn_s_setprio(0); } while (0)
; #define WAIT_V(n) asm volatile("s_waitcnt vmcnt(" #n ")" ::: "memory")
; #define WAIT_L(n) asm volatile("s_waitcnt lgkmcnt(" #n ")" ::: "memory")
; #define BAR __builtin_amdgcn_s_barrier()
; #define SCHED __builtin_amdgcn_sched_barrier(0)
; template <int EPI> ...
;     ...
;     BAR; WAIT_L(0); MMA(1, 0, At, B0); BAR; SCHED;
;     STAGE(SB(0, 1), Bt, bcol + HALF, t + 2);
;     WAIT_V(6); BAR; MMA(1, 1, At, B1); BAR;
;     LDB(B0, 1, 0); SCHED; LDA(At, 1, 0); STAGE(SA(0, 1), A, brow + HALF, t + 2);
;     WAIT_L(8); BAR; WAIT_L(0); MMA(0, 0, At, B0); BAR; SCHED;
;     LDB(B1, 1, 1); STAGE(SB(1, 0), Bt, bcol, t + 3);
;     BAR; WAIT_L(0); MMA(0, 1, At, B1); BAR;
	s_waitcnt lgkmcnt(0)
	s_setprio 1
	s_waitcnt lgkmcnt(0)
	v_mfma_f32_16x16x32_bf16 v[60:63], v[160:163], v[176:179], v[60:63]
	v_mfma_f32_16x16x32_bf16 v[56:59], v[164:167], v[176:179], v[56:59]
	v_mfma_f32_16x16x32_bf16 v[52:55], v[160:163], v[184:187], v[52:55]
	v_mfma_f32_16x16x32_bf16 v[48:51], v[164:167], v[184:187], v[48:51]
	v_mfma_f32_16x16x32_bf16 v[44:47], v[160:163], v[192:195], v[44:47]
	v_mfma_f32_16x16x32_bf16 v[40:43], v[164:167], v[192:195], v[40:43]
	v_mfma_f32_16x16x32_bf16 v[36:39], v[160:163], v[200:203], v[36:39]
	v_mfma_f32_16x16x32_bf16 v[32:35], v[164:167], v[200:203], v[32:35]
	v_mfma_f32_16x16x32_bf16 v[60:63], v[168:171], v[180:183], v[60:63]
	v_mfma_f32_16x16x32_bf16 v[56:59], v[172:175], v[180:183], v[56:59]
	v_mfma_f32_16x16x32_bf16 v[52:55], v[168:171], v[188:191], v[52:55]
	v_mfma_f32_16x16x32_bf16 v[48:51], v[172:175], v[188:191], v[48:51]
	v_mfma_f32_16x16x32_bf16 v[44:47], v[168:171], v[196:199], v[44:47]
	v_mfma_f32_16x16x32_bf16 v[40:43], v[172:175], v[196:199], v[40:43]
	v_mfma_f32_16x16x32_bf16 v[36:39], v[168:171], v[204:207], v[36:39]
	v_mfma_f32_16x16x32_bf16 v[32:35], v[172:175], v[204:207], v[32:35]
	s_setprio 0
	s_setprio 1
	v_mfma_f32_16x16x32_bf16 v[28:31], v[208:211], v[176:179], v[28:31]
	v_mfma_f32_16x16x32_bf16 v[24:27], v[212:215], v[176:179], v[24:27]
	v_mfma_f32_16x16x32_bf16 v[20:23], v[208:211], v[184:187], v[20:23]
	v_mfma_f32_16x16x32_bf16 v[16:19], v[212:215], v[184:187], v[16:19]
	v_mfma_f32_16x16x32_bf16 v[12:15], v[208:211], v[192:195], v[12:15]
	v_mfma_f32_16x16x32_bf16 v[8:11], v[212:215], v[192:195], v[8:11]
	v_mfma_f32_16x16x32_bf16 v[4:7], v[208:211], v[200:203], v[4:7]
	v_mfma_f32_16x16x32_bf16 v[0:3], v[212:215], v[200:203], v[0:3]
	v_mfma_f32_16x16x32_bf16 v[28:31], v[216:219], v[180:183], v[28:31]
	v_mfma_f32_16x16x32_bf16 v[24:27], v[220:223], v[180:183], v[24:27]
	v_mfma_f32_16x16x32_bf16 v[20:23], v[216:219], v[188:191], v[20:23]
	v_mfma_f32_16x16x32_bf16 v[16:19], v[220:223], v[188:191], v[16:19]
	v_mfma_f32_16x16x32_bf16 v[12:15], v[216:219], v[196:199], v[12:15]
	v_mfma_f32_16x16x32_bf16 v[8:11], v[220:223], v[196:199], v[8:11]
	v_mfma_f32_16x16x32_bf16 v[4:7], v[216:219], v[204:207], v[4:7]
	v_mfma_f32_16x16x32_bf16 v[0:3], v[220:223], v[204:207], v[0:3]
	s_setprio 0
	s_barrier
	ds_read_b128 v[160:163], v156
	ds_read_b128 v[164:167], v156 offset:256
	ds_read_b128 v[168:171], v157
	ds_read_b128 v[172:175], v157 offset:256
	v_readfirstlane_b32 s70, v141
	v_lshl_add_u64 v[208:209], v[224:225], 0, s[38:39]
	s_mov_b32 m0, s70
	v_readfirstlane_b32 s70, v142
	ds_read_b128 v[176:179], v149 offset:32768
	ds_read_b128 v[180:183], v149 offset:33792
	ds_read_b128 v[184:187], v149 offset:34816
	ds_read_b128 v[188:191], v149 offset:35840
	ds_read_b128 v[192:195], v149 offset:36864
	ds_read_b128 v[196:199], v149 offset:37888
	ds_read_b128 v[200:203], v149 offset:38912
	ds_read_b128 v[204:207], v149 offset:39936
	global_load_lds_dwordx4 v[208:209], off
	v_lshl_add_u64 v[208:209], v[224:225], 0, s[46:47]
	s_mov_b32 m0, s70
	s_nop 0
	global_load_lds_dwordx4 v[208:209], off
	s_waitcnt lgkmcnt(8)
	ds_read_b128 v[208:211], v158
	ds_read_b128 v[212:215], v158 offset:256
	ds_read_b128 v[216:219], v159
	ds_read_b128 v[220:223], v159 offset:256
	s_barrier
	s_waitcnt lgkmcnt(0)
	s_setprio 1
	s_waitcnt lgkmcnt(0)
	v_mfma_f32_16x16x32_bf16 v[124:127], v[160:163], v[176:179], v[124:127]
	v_mfma_f32_16x16x32_bf16 v[120:123], v[164:167], v[176:179], v[120:123]
	v_mfma_f32_16x16x32_bf16 v[116:119], v[160:163], v[184:187], v[116:119]
	v_mfma_f32_16x16x32_bf16 v[112:115], v[164:167], v[184:187], v[112:115]
	v_mfma_f32_16x16x32_bf16 v[108:111], v[160:163], v[192:195], v[108:111]
	v_mfma_f32_16x16x32_bf16 v[104:107], v[164:167], v[192:195], v[104:107]
	v_mfma_f32_16x16x32_bf16 v[100:103], v[160:163], v[200:203], v[100:103]
	v_mfma_f32_16x16x32_bf16 v[96:99], v[164:167], v[200:203], v[96:99]
	v_mfma_f32_16x16x32_bf16 v[124:127], v[168:171], v[180:183], v[124:127]
	v_mfma_f32_16x16x32_bf16 v[120:123], v[172:175], v[180:183], v[120:123]
	v_mfma_f32_16x16x32_bf16 v[116:119], v[168:171], v[188:191], v[116:119]
	v_mfma_f32_16x16x32_bf16 v[112:115], v[172:175], v[188:191], v[112:115]
	v_mfma_f32_16x16x32_bf16 v[108:111], v[168:171], v[196:199], v[108:111]
	v_mfma_f32_16x16x32_bf16 v[104:107], v[172:175], v[196:199], v[104:107]
	v_mfma_f32_16x16x32_bf16 v[100:103], v[168:171], v[204:207], v[100:103]
	v_mfma_f32_16x16x32_bf16 v[96:99], v[172:175], v[204:207], v[96:99]
	s_setprio 0
	s_waitcnt lgkmcnt(0)
	s_setprio 1
	s_waitcnt lgkmcnt(0)
	v_mfma_f32_16x16x32_bf16 v[92:95], v[208:211], v[176:179], v[92:95]
	v_mfma_f32_16x16x32_bf16 v[88:91], v[212:215], v[176:179], v[88:91]
	v_mfma_f32_16x16x32_bf16 v[84:87], v[208:211], v[184:187], v[84:87]
	v_mfma_f32_16x16x32_bf16 v[80:83], v[212:215], v[184:187], v[80:83]
	v_mfma_f32_16x16x32_bf16 v[76:79], v[208:211], v[192:195], v[76:79]
	v_mfma_f32_16x16x32_bf16 v[72:75], v[212:215], v[192:195], v[72:75]
	v_mfma_f32_16x16x32_bf16 v[68:71], v[208:211], v[200:203], v[68:71]
	v_mfma_f32_16x16x32_bf16 v[64:67], v[212:215], v[200:203], v[64:67]
	v_mfma_f32_16x16x32_bf16 v[92:95], v[216:219], v[180:183], v[92:95]
	v_mfma_f32_16x16x32_bf16 v[88:91], v[220:223], v[180:183], v[88:91]
	v_mfma_f32_16x16x32_bf16 v[84:87], v[216:219], v[188:191], v[84:87]
	v_mfma_f32_16x16x32_bf16 v[80:83], v[220:223], v[188:191], v[80:83]
	v_mfma_f32_16x16x32_bf16 v[76:79], v[216:219], v[196:199], v[76:79]
	v_mfma_f32_16x16x32_bf16 v[72:75], v[220:223], v[196:199], v[72:75]
	v_mfma_f32_16x16x32_bf16 v[68:71], v[216:219], v[204:207], v[68:71]
	v_mfma_f32_16x16x32_bf16 v[64:67], v[220:223], v[204:207], v[64:67]
	s_setprio 0
	s_barrier
; #define STAGE(P, BASE, br, kt) do { const char* _gb = (const char*)(BASE) + ((size_t)(br) * K + (size_t)(kt) * BK) * 2; \
;     __builtin_amdgcn_global_load_lds((const unsigned*)(_gb + loff0), (unsigned*)((char*)(P) + tid * 16), 16, 0, 0); \
;     __builtin_amdgcn_global_load_lds((const unsigned*)(_gb + (size_t)K * 128 + loff0), (unsigned*)((char*)(P) + tid * 16 + 8192), 16, 0, 0); } while (0)
; #define LDA(dst, b, h) for (int m = 0; m < 4; ++m) { \
;     dst[m][0] = *reinterpret_cast<const bf16x8*>((char*)SA(b, h) + aoff0 + m * 2048); \
;     dst[m][1] = *reinterpret_cast<const bf16x8*>((char*)SA(b, h) + aoff1 + m * 2048); }
; #define LDB(dst, b, h) for (int n = 0; n < 2; ++n) { \
;     dst[n][0] = *reinterpret_cast<const bf16x8*>((char*)SB(b, h) + boff0 + n * 256); \
;     dst[n][1] = *reinterpret_cast<const bf16x8*>((char*)SB(b, h) + boff1 + n * 256); }
; #define MMA(ai, bj, At, Btf) do { __builtin_amdgcn_s_setprio(1); \
;     for (int m = 0; m < 4; ++m) for (int n = 0; n < 2; ++n) for (int k = 0; k < 2; ++k) \
;       acc[ai][bj][m][n] = __builtin_amdgcn_mfma_f32_16x16x32_bf16(Btf[n][k], At[m][k], acc[ai][bj][m][n], 0, 0, 0); \
;     __builtin_amdgcn_s_setprio(0); } while (0)
; #define WAIT_V(n) asm volatile("s_waitcnt vmcnt(" #n ")" ::: "memory")
; #define WAIT_L(n) asm volatile("s_waitcnt lgkmcnt(" #n ")" ::: "memory")
; #define BAR __builtin_amdgcn_s_barrier()
; #define SCHED __builtin_amdgcn_sched_barrier(0)
; template <int EPI> ...
;     ...
;     LDB(B1, 1, 1); STAGE(SB(1, 0), Bt, bcol, t + 3);
;     BAR; WAIT_L(0); MMA(0, 1, At, B1); BAR;
;     LDA(At, 1, 1); STAGE(SA(1, 0), A, brow, t + 3);
;     BAR; WAIT_L(0); MMA(1, 0, At, B0); BAR; SCHED;
;     STAGE(SB(1, 1), Bt, bcol + HALF, t + 3);
;     WAIT_V(6); BAR; MMA(1, 1, At, B1); BAR;
;   }
;   { LDB(B0, 0, 0); LDA(At, 0, 0); STAGE(SA(1, 1), A, brow + HALF, nt - 1);
;     BAR; WAIT_L(0); MMA(0, 0, At, B0); BAR;
	v_readfirstlane_b32 s70, v143
	v_lshl_add_u64 v[228:229], v[226:227], 0, s[48:49]
	s_mov_b32 m0, s70
	v_readfirstlane_b32 s70, v144
	global_load_lds_dwordx4 v[228:229], off
	v_lshl_add_u64 v[228:229], v[226:227], 0, s[50:51]
	s_mov_b32 m0, s70
	s_nop 0
	global_load_lds_dwordx4 v[228:229], off
	v_readfirstlane_b32 s70, v145
	v_lshl_add_u64 v[228:229], v[224:225], 0, s[52:53]
	s_mov_b32 m0, s70
	v_readfirstlane_b32 s70, v146
	ds_read_b128 v[176:179], v149 offset:49152
	ds_read_b128 v[180:183], v149 offset:50176
	ds_read_b128 v[184:187], v149 offset:51200
	ds_read_b128 v[188:191], v149 offset:52224
	ds_read_b128 v[192:195], v149 offset:53248
	ds_read_b128 v[196:199], v149 offset:54272
	ds_read_b128 v[200:203], v149 offset:55296
	ds_read_b128 v[204:207], v149 offset:56320
	global_load_lds_dwordx4 v[228:229], off
	v_lshl_add_u64 v[224:225], v[224:225], 0, s[54:55]
	s_mov_b32 m0, s70
	s_nop 0
	global_load_lds_dwordx4 v[224:225], off
	v_readfirstlane_b32 s70, v147
	v_lshl_add_u64 v[246:247], v[226:227], 0, s[56:57]
	s_mov_b32 m0, s70
	v_readfirstlane_b32 s70, v148
	global_load_lds_dwordx4 v[246:247], off
	v_lshl_add_u64 v[246:247], v[226:227], 0, s[58:59]
	s_mov_b32 m0, s70
	s_nop 0
	global_load_lds_dwordx4 v[246:247], off
	s_waitcnt vmcnt(6)
	s_barrier
	s_waitcnt lgkmcnt(0)
	s_setprio 1
	s_waitcnt lgkmcnt(0)
	v_mfma_f32_16x16x32_bf16 v[60:63], v[160:163], v[176:179], v[60:63]
	v_mfma_f32_16x16x32_bf16 v[56:59], v[164:167], v[176:179], v[56:59]
	v_mfma_f32_16x16x32_bf16 v[52:55], v[160:163], v[184:187], v[52:55]
	v_mfma_f32_16x16x32_bf16 v[48:51], v[164:167], v[184:187], v[48:51]
	v_mfma_f32_16x16x32_bf16 v[44:47], v[160:163], v[192:195], v[44:47]
	v_mfma_f32_16x16x32_bf16 v[40:43], v[164:167], v[192:195], v[40:43]
	v_mfma_f32_16x16x32_bf16 v[36:39], v[160:163], v[200:203], v[36:39]
	v_mfma_f32_16x16x32_bf16 v[32:35], v[164:167], v[200:203], v[32:35]
	v_mfma_f32_16x16x32_bf16 v[60:63], v[168:171], v[180:183], v[60:63]
	v_mfma_f32_16x16x32_bf16 v[56:59], v[172:175], v[180:183], v[56:59]
	v_mfma_f32_16x16x32_bf16 v[52:55], v[168:171], v[188:191], v[52:55]
	v_mfma_f32_16x16x32_bf16 v[48:51], v[172:175], v[188:191], v[48:51]
	v_mfma_f32_16x16x32_bf16 v[44:47], v[168:171], v[196:199], v[44:47]
	v_mfma_f32_16x16x32_bf16 v[40:43], v[172:175], v[196:199], v[40:43]
	v_mfma_f32_16x16x32_bf16 v[36:39], v[168:171], v[204:207], v[36:39]
	v_mfma_f32_16x16x32_bf16 v[32:35], v[172:175], v[204:207], v[32:35]
	s_setprio 0
	s_setprio 1
	v_mfma_f32_16x16x32_bf16 v[28:31], v[208:211], v[176:179], v[28:31]
	v_mfma_f32_16x16x32_bf16 v[24:27], v[212:215], v[176:179], v[24:27]
	v_mfma_f32_16x16x32_bf16 v[20:23], v[208:211], v[184:187], v[20:23]
	v_mfma_f32_16x16x32_bf16 v[16:19], v[212:215], v[184:187], v[16:19]
	v_mfma_f32_16x16x32_bf16 v[12:15], v[208:211], v[192:195], v[12:15]
	v_mfma_f32_16x16x32_bf16 v[8:11], v[212:215], v[192:195], v[8:11]
	v_mfma_f32_16x16x32_bf16 v[4:7], v[208:211], v[200:203], v[4:7]
	v_mfma_f32_16x16x32_bf16 v[0:3], v[212:215], v[200:203], v[0:3]
	v_mfma_f32_16x16x32_bf16 v[28:31], v[216:219], v[180:183], v[28:31]
	v_mfma_f32_16x16x32_bf16 v[24:27], v[220:223], v[180:183], v[24:27]
	v_mfma_f32_16x16x32_bf16 v[20:23], v[216:219], v[188:191], v[20:23]
	v_mfma_f32_16x16x32_bf16 v[16:19], v[220:223], v[188:191], v[16:19]
	v_mfma_f32_16x16x32_bf16 v[12:15], v[216:219], v[196:199], v[12:15]
	v_mfma_f32_16x16x32_bf16 v[8:11], v[220:223], v[196:199], v[8:11]
	v_mfma_f32_16x16x32_bf16 v[4:7], v[216:219], v[204:207], v[4:7]
	v_mfma_f32_16x16x32_bf16 v[0:3], v[220:223], v[204:207], v[0:3]
	s_setprio 0
	s_add_i32 s61, s61, 2
	s_add_u32 s66, s66, 0x100
	s_addc_u32 s67, s67, 0
	s_add_u32 s68, s68, 0x100
	s_addc_u32 s69, s69, 0
	s_cmp_lt_u32 s61, 28
	s_barrier
	s_cbranch_scc1 .LBB0_411
	s_add_u32 s64, s74, s64
	s_addc_u32 s65, s75, s65
	v_readfirstlane_b32 s61, v150
	v_lshl_add_u64 v[208:209], s[64:65], 0, v[128:129]
	s_mov_b32 m0, s61
	v_readfirstlane_b32 s61, v151
	ds_read_b128 v[160:163], v152
	ds_read_b128 v[164:167], v152 offset:256
	ds_read_b128 v[168:171], v153
	ds_read_b128 v[172:175], v153 offset:256
	ds_read_b128 v[176:179], v149
	ds_read_b128 v[180:183], v149 offset:1024
	ds_read_b128 v[184:187], v149 offset:2048
	ds_read_b128 v[188:191], v149 offset:3072
	ds_read_b128 v[192:195], v149 offset:4096
	ds_read_b128 v[196:199], v149 offset:5120
	ds_read_b128 v[200:203], v149 offset:6144
	ds_read_b128 v[204:207], v149 offset:7168
	global_load_lds_dwordx4 v[208:209], off
	v_lshl_add_u64 v[208:209], v[208:209], 0, s[8:9]
	s_mov_b32 m0, s61
	s_nop 0
	global_load_lds_dwordx4 v[208:209], off
	s_barrier
	s_waitcnt lgkmcnt(0)
	s_setprio 1
	s_waitcnt lgkmcnt(0)
	v_mfma_f32_16x16x32_bf16 v[124:127], v[160:163], v[176:179], v[124:127]
	v_mfma_f32_16x16x32_bf16 v[116:119], v[160:163], v[184:187], v[116:119]
	v_mfma_f32_16x16x32_bf16 v[108:111], v[160:163], v[192:195], v[108:111]
	v_mfma_f32_16x16x32_bf16 v[100:103], v[160:163], v[200:203], v[100:103]
	v_mfma_f32_16x16x32_bf16 v[96:99], v[164:167], v[200:203], v[96:99]
	v_mfma_f32_16x16x32_bf16 v[124:127], v[168:171], v[180:183], v[124:127]
	v_mfma_f32_16x16x32_bf16 v[120:123], v[164:167], v[176:179], v[120:123]
	v_mfma_f32_16x16x32_bf16 v[116:119], v[168:171], v[188:191], v[116:119]
	v_mfma_f32_16x16x32_bf16 v[112:115], v[164:167], v[184:187], v[112:115]
	v_mfma_f32_16x16x32_bf16 v[108:111], v[168:171], v[196:199], v[108:111]
	v_mfma_f32_16x16x32_bf16 v[104:107], v[164:167], v[192:195], v[104:107]
	v_mfma_f32_16x16x32_bf16 v[100:103], v[168:171], v[204:207], v[100:103]
	v_mfma_f32_16x16x32_bf16 v[96:99], v[172:175], v[204:207], v[96:99]
	v_mfma_f32_16x16x32_bf16 v[208:211], v[172:175], v[180:183], v[120:123]
	v_mfma_f32_16x16x32_bf16 v[212:215], v[172:175], v[188:191], v[112:115]
	v_mfma_f32_16x16x32_bf16 v[216:219], v[172:175], v[196:199], v[104:107]
	s_setprio 0
	s_barrier
; #define LDA(dst, b, h) for (int m = 0; m < 4; ++m) { \
;     dst[m][0] = *reinterpret_cast<const bf16x8*>((char*)SA(b, h) + aoff0 + m * 2048); \
;     dst[m][1] = *reinterpret_cast<const bf16x8*>((char*)SA(b, h) + aoff1 + m * 2048); }
; #define LDB(dst, b, h) for (int n = 0; n < 2; ++n) { \
;     dst[n][0] = *reinterpret_cast<const bf16x8*>((char*)SB(b, h) + boff0 + n * 256); \
;     dst[n][1] = *reinterpret_cast<const bf16x8*>((char*)SB(b, h) + boff1 + n * 256); }
; #define MMA(ai, bj, At, Btf) do { __builtin_amdgcn_s_setprio(1); \
;     for (int m = 0; m < 4; ++m) for (int n = 0; n < 2; ++n) for (int k = 0; k < 2; ++k) \
;       acc[ai][bj][m][n] = __builtin_amdgcn_mfma_f32_16x16x32_bf16(Btf[n][k], At[m][k], acc[ai][bj][m][n], 0, 0, 0); \
;     __builtin_amdgcn_s_setprio(0); } while (0)
; #define WAIT_V(n) asm volatile("s_waitcnt vmcnt(" #n ")" ::: "memory")
; #define WAIT_L(n) asm volatile("s_waitcnt lgkmcnt(" #n ")" ::: "memory")
; #define BAR __builtin_amdgcn_s_barrier()
; template <int EPI> ...
;     ...
;     LDB(B1, 0, 1); BAR; WAIT_L(0); MMA(0, 1, At, B1); BAR;
;     LDA(At, 0, 1); WAIT_V(4); BAR; WAIT_L(0); MMA(1, 0, At, B0); MMA(1, 1, At, B1); BAR; }
;   { LDB(B0, 1, 0); LDA(At, 1, 0); WAIT_V(2); BAR; WAIT_L(0); MMA(0, 0, At, B0); BAR;
	s_nop 0
	ds_read_b128 v[104:107], v154
	ds_read_b128 v[112:115], v154 offset:256
	ds_read_b128 v[120:123], v155
	ds_read_b128 v[220:223], v155 offset:256
	s_barrier
	s_waitcnt lgkmcnt(0)
	s_setprio 1
	s_waitcnt lgkmcnt(0)
	v_mfma_f32_16x16x32_bf16 v[92:95], v[104:107], v[176:179], v[92:95]
	v_mfma_f32_16x16x32_bf16 v[88:91], v[112:115], v[176:179], v[88:91]
	v_mfma_f32_16x16x32_bf16 v[76:79], v[104:107], v[192:195], v[76:79]
	v_mfma_f32_16x16x32_bf16 v[72:75], v[112:115], v[192:195], v[72:75]
	v_mfma_f32_16x16x32_bf16 v[92:95], v[120:123], v[180:183], v[92:95]
	v_mfma_f32_16x16x32_bf16 v[88:91], v[220:223], v[180:183], v[88:91]
	v_mfma_f32_16x16x32_bf16 v[84:87], v[104:107], v[184:187], v[84:87]
	v_mfma_f32_16x16x32_bf16 v[80:83], v[112:115], v[184:187], v[80:83]
	v_mfma_f32_16x16x32_bf16 v[76:79], v[120:123], v[196:199], v[76:79]
	v_mfma_f32_16x16x32_bf16 v[72:75], v[220:223], v[196:199], v[72:75]
	v_mfma_f32_16x16x32_bf16 v[68:71], v[104:107], v[200:203], v[68:71]
	v_mfma_f32_16x16x32_bf16 v[64:67], v[112:115], v[200:203], v[64:67]
	v_mfma_f32_16x16x32_bf16 v[176:179], v[120:123], v[188:191], v[84:87]
	v_mfma_f32_16x16x32_bf16 v[180:183], v[220:223], v[188:191], v[80:83]
	v_mfma_f32_16x16x32_bf16 v[184:187], v[120:123], v[204:207], v[68:71]
	v_mfma_f32_16x16x32_bf16 v[188:191], v[220:223], v[204:207], v[64:67]
	s_setprio 0
	s_barrier
	s_nop 1
	ds_read_b128 v[64:67], v149 offset:16384
	ds_read_b128 v[68:71], v149 offset:17408
	ds_read_b128 v[80:83], v149 offset:18432
	ds_read_b128 v[84:87], v149 offset:19456
	ds_read_b128 v[192:195], v149 offset:20480
	ds_read_b128 v[196:199], v149 offset:21504
	ds_read_b128 v[200:203], v149 offset:22528
	ds_read_b128 v[204:207], v149 offset:23552
	s_waitcnt vmcnt(4)
	s_barrier
	s_waitcnt lgkmcnt(0)
	s_setprio 1
	s_waitcnt lgkmcnt(0)
	v_mfma_f32_16x16x32_bf16 v[60:63], v[160:163], v[64:67], v[60:63]
	v_mfma_f32_16x16x32_bf16 v[56:59], v[164:167], v[64:67], v[56:59]
	v_mfma_f32_16x16x32_bf16 v[44:47], v[160:163], v[192:195], v[44:47]
	v_mfma_f32_16x16x32_bf16 v[36:39], v[160:163], v[200:203], v[36:39]
	v_mfma_f32_16x16x32_bf16 v[60:63], v[168:171], v[68:71], v[60:63]
	v_mfma_f32_16x16x32_bf16 v[56:59], v[172:175], v[68:71], v[56:59]
	v_mfma_f32_16x16x32_bf16 v[52:55], v[160:163], v[80:83], v[52:55]
	v_mfma_f32_16x16x32_bf16 v[48:51], v[164:167], v[80:83], v[48:51]
	v_mfma_f32_16x16x32_bf16 v[44:47], v[168:171], v[196:199], v[44:47]
	v_mfma_f32_16x16x32_bf16 v[40:43], v[164:167], v[192:195], v[40:43]
	v_mfma_f32_16x16x32_bf16 v[36:39], v[168:171], v[204:207], v[36:39]
	v_mfma_f32_16x16x32_bf16 v[32:35], v[164:167], v[200:203], v[32:35]
	v_mfma_f32_16x16x32_bf16 v[224:227], v[168:171], v[84:87], v[52:55]
	v_mfma_f32_16x16x32_bf16 v[228:231], v[172:175], v[84:87], v[48:51]
	v_mfma_f32_16x16x32_bf16 v[232:235], v[172:175], v[196:199], v[40:43]
	v_mfma_f32_16x16x32_bf16 v[160:163], v[172:175], v[204:207], v[32:35]
	s_setprio 0
	s_setprio 1
	v_mfma_f32_16x16x32_bf16 v[28:31], v[104:107], v[64:67], v[28:31]
	v_mfma_f32_16x16x32_bf16 v[20:23], v[104:107], v[80:83], v[20:23]
	v_mfma_f32_16x16x32_bf16 v[12:15], v[104:107], v[192:195], v[12:15]
	v_mfma_f32_16x16x32_bf16 v[4:7], v[104:107], v[200:203], v[4:7]
	v_mfma_f32_16x16x32_bf16 v[28:31], v[120:123], v[68:71], v[28:31]
	v_mfma_f32_16x16x32_bf16 v[24:27], v[112:115], v[64:67], v[24:27]
	v_mfma_f32_16x16x32_bf16 v[20:23], v[120:123], v[84:87], v[20:23]
	v_mfma_f32_16x16x32_bf16 v[16:19], v[112:115], v[80:83], v[16:19]
	v_mfma_f32_16x16x32_bf16 v[12:15], v[120:123], v[196:199], v[12:15]
	v_mfma_f32_16x16x32_bf16 v[8:11], v[112:115], v[192:195], v[8:11]
	v_mfma_f32_16x16x32_bf16 v[4:7], v[120:123], v[204:207], v[4:7]
	v_mfma_f32_16x16x32_bf16 v[0:3], v[112:115], v[200:203], v[0:3]
	v_mfma_f32_16x16x32_bf16 v[164:167], v[220:223], v[68:71], v[24:27]
	v_mfma_f32_16x16x32_bf16 v[168:171], v[220:223], v[84:87], v[16:19]
	v_mfma_f32_16x16x32_bf16 v[172:175], v[220:223], v[196:199], v[8:11]
	v_mfma_f32_16x16x32_bf16 v[192:195], v[220:223], v[204:207], v[0:3]
	s_setprio 0
	s_barrier
	s_nop 1
	ds_read_b128 v[0:3], v156
	ds_read_b128 v[8:11], v156 offset:256
	ds_read_b128 v[16:19], v157
	ds_read_b128 v[24:27], v157 offset:256
	ds_read_b128 v[32:35], v149 offset:32768
	ds_read_b128 v[40:43], v149 offset:33792
	ds_read_b128 v[48:51], v149 offset:34816
	ds_read_b128 v[52:55], v149 offset:35840
	ds_read_b128 v[68:71], v149 offset:36864
	ds_read_b128 v[196:199], v149 offset:37888
	ds_read_b128 v[200:203], v149 offset:38912
	ds_read_b128 v[204:207], v149 offset:39936
	s_waitcnt vmcnt(2)
	s_barrier
; #define LDA(dst, b, h) for (int m = 0; m < 4; ++m) { \
;     dst[m][0] = *reinterpret_cast<const bf16x8*>((char*)SA(b, h) + aoff0 + m * 2048); \
;     dst[m][1] = *reinterpret_cast<const bf16x8*>((char*)SA(b, h) + aoff1 + m * 2048); }
; #define LDB(dst, b, h) for (int n = 0; n < 2; ++n) { \
;     dst[n][0] = *reinterpret_cast<const bf16x8*>((char*)SB(b, h) + boff0 + n * 256); \
;     dst[n][1] = *reinterpret_cast<const bf16x8*>((char*)SB(b, h) + boff1 + n * 256); }
; #define MMA(ai, bj, At, Btf) do { __builtin_amdgcn_s_setprio(1); \
;     for (int m = 0; m < 4; ++m) for (int n = 0; n < 2; ++n) for (int k = 0; k < 2; ++k) \
;       acc[ai][bj][m][n] = __builtin_amdgcn_mfma_f32_16x16x32_bf16(Btf[n][k], At[m][k], acc[ai][bj][m][n], 0, 0, 0); \
;     __builtin_amdgcn_s_setprio(0); } while (0)
; #define WAIT_V(n) asm volatile("s_waitcnt vmcnt(" #n ")" ::: "memory")
; #define WAIT_L(n) asm volatile("s_waitcnt lgkmcnt(" #n ")" ::: "memory")
; #define BAR __builtin_amdgcn_s_barrier()
; template <int EPI> ...
;     ...
;   { LDB(B0, 1, 0); LDA(At, 1, 0); WAIT_V(2); BAR; WAIT_L(0); MMA(0, 0, At, B0); BAR;
;     LDB(B1, 1, 1); WAIT_V(0); BAR; WAIT_L(0); MMA(0, 1, At, B1); BAR;
;     LDA(At, 1, 1); BAR; WAIT_L(0); MMA(1, 0, At, B0); MMA(1, 1, At, B1); BAR; }
;   if (wr == 0) BAR;
	s_waitcnt lgkmcnt(0)
	s_setprio 1
	s_waitcnt lgkmcnt(0)
	v_mfma_f32_16x16x32_bf16 v[64:67], v[0:3], v[32:35], v[124:127]
	v_mfma_f32_16x16x32_bf16 v[120:123], v[16:19], v[40:43], v[64:67]
	v_mfma_f32_16x16x32_bf16 v[64:67], v[8:11], v[32:35], v[208:211]
	v_mfma_f32_16x16x32_bf16 v[124:127], v[24:27], v[40:43], v[64:67]
	v_mfma_f32_16x16x32_bf16 v[64:67], v[0:3], v[48:51], v[116:119]
	v_mfma_f32_16x16x32_bf16 v[112:115], v[16:19], v[52:55], v[64:67]
	v_mfma_f32_16x16x32_bf16 v[64:67], v[8:11], v[48:51], v[212:215]
	v_mfma_f32_16x16x32_bf16 v[116:119], v[24:27], v[52:55], v[64:67]
	v_mfma_f32_16x16x32_bf16 v[64:67], v[0:3], v[68:71], v[108:111]
	v_mfma_f32_16x16x32_bf16 v[104:107], v[16:19], v[196:199], v[64:67]
	v_mfma_f32_16x16x32_bf16 v[64:67], v[8:11], v[68:71], v[216:219]
	v_mfma_f32_16x16x32_bf16 v[108:111], v[24:27], v[196:199], v[64:67]
	v_mfma_f32_16x16x32_bf16 v[64:67], v[0:3], v[200:203], v[100:103]
	v_mfma_f32_16x16x32_bf16 v[80:83], v[16:19], v[204:207], v[64:67]
	v_mfma_f32_16x16x32_bf16 v[64:67], v[8:11], v[200:203], v[96:99]
	v_mfma_f32_16x16x32_bf16 v[84:87], v[24:27], v[204:207], v[64:67]
	s_setprio 0
	s_barrier
	ds_read_b128 v[208:211], v158
	ds_read_b128 v[212:215], v158 offset:256
	ds_read_b128 v[216:219], v159
	ds_read_b128 v[220:223], v159 offset:256
	s_waitcnt vmcnt(0)
	s_barrier
	s_waitcnt lgkmcnt(0)
	s_setprio 1
	s_waitcnt lgkmcnt(0)
	v_mfma_f32_16x16x32_bf16 v[64:67], v[208:211], v[32:35], v[92:95]
	v_mfma_f32_16x16x32_bf16 v[32:35], v[212:215], v[32:35], v[88:91]
	v_mfma_f32_16x16x32_bf16 v[100:103], v[220:223], v[40:43], v[32:35]
	v_mfma_f32_16x16x32_bf16 v[32:35], v[208:211], v[48:51], v[176:179]
	v_mfma_f32_16x16x32_bf16 v[88:91], v[216:219], v[52:55], v[32:35]
	v_mfma_f32_16x16x32_bf16 v[32:35], v[212:215], v[48:51], v[180:183]
	v_mfma_f32_16x16x32_bf16 v[92:95], v[220:223], v[52:55], v[32:35]
	v_mfma_f32_16x16x32_bf16 v[32:35], v[208:211], v[68:71], v[76:79]
	v_mfma_f32_16x16x32_bf16 v[96:99], v[216:219], v[40:43], v[64:67]
	v_mfma_f32_16x16x32_bf16 v[64:67], v[216:219], v[196:199], v[32:35]
	v_mfma_f32_16x16x32_bf16 v[32:35], v[212:215], v[68:71], v[72:75]
	v_mfma_f32_16x16x32_bf16 v[68:71], v[220:223], v[196:199], v[32:35]
	v_mfma_f32_16x16x32_bf16 v[32:35], v[208:211], v[200:203], v[184:187]
	v_mfma_f32_16x16x32_bf16 v[48:51], v[216:219], v[204:207], v[32:35]
	v_mfma_f32_16x16x32_bf16 v[32:35], v[212:215], v[200:203], v[188:191]
	v_mfma_f32_16x16x32_bf16 v[52:55], v[220:223], v[204:207], v[32:35]
	s_setprio 0
	s_barrier
	ds_read_b128 v[176:179], v149 offset:49152
	ds_read_b128 v[180:183], v149 offset:50176
	ds_read_b128 v[184:187], v149 offset:51200
	ds_read_b128 v[188:191], v149 offset:52224
	ds_read_b128 v[196:199], v149 offset:53248
	ds_read_b128 v[200:203], v149 offset:54272
	ds_read_b128 v[204:207], v149 offset:55296
	ds_read_b128 v[236:239], v149 offset:56320
	s_barrier
	s_waitcnt lgkmcnt(0)
	s_setprio 1
	s_waitcnt lgkmcnt(0)
	v_mfma_f32_16x16x32_bf16 v[32:35], v[0:3], v[176:179], v[60:63]
	v_mfma_f32_16x16x32_bf16 v[72:75], v[16:19], v[180:183], v[32:35]
	v_mfma_f32_16x16x32_bf16 v[32:35], v[8:11], v[176:179], v[56:59]
	v_mfma_f32_16x16x32_bf16 v[76:79], v[24:27], v[180:183], v[32:35]
	v_mfma_f32_16x16x32_bf16 v[32:35], v[0:3], v[184:187], v[224:227]
	v_mfma_f32_16x16x32_bf16 v[56:59], v[16:19], v[188:191], v[32:35]
	v_mfma_f32_16x16x32_bf16 v[32:35], v[8:11], v[184:187], v[228:231]
	v_mfma_f32_16x16x32_bf16 v[60:63], v[24:27], v[188:191], v[32:35]
	v_mfma_f32_16x16x32_bf16 v[32:35], v[0:3], v[196:199], v[44:47]
	v_mfma_f32_16x16x32_bf16 v[40:43], v[16:19], v[200:203], v[32:35]
	v_mfma_f32_16x16x32_bf16 v[32:35], v[8:11], v[196:199], v[232:235]
	v_mfma_f32_16x16x32_bf16 v[0:3], v[0:3], v[204:207], v[36:39]
	v_mfma_f32_16x16x32_bf16 v[44:47], v[24:27], v[200:203], v[32:35]
	v_mfma_f32_16x16x32_bf16 v[32:35], v[16:19], v[236:239], v[0:3]
	v_mfma_f32_16x16x32_bf16 v[0:3], v[8:11], v[204:207], v[160:163]
	v_mfma_f32_16x16x32_bf16 v[36:39], v[24:27], v[236:239], v[0:3]
	s_setprio 0
	s_setprio 1
	v_mfma_f32_16x16x32_bf16 v[0:3], v[208:211], v[176:179], v[28:31]
	v_mfma_f32_16x16x32_bf16 v[24:27], v[216:219], v[180:183], v[0:3]
	v_mfma_f32_16x16x32_bf16 v[0:3], v[212:215], v[176:179], v[164:167]
	v_mfma_f32_16x16x32_bf16 v[28:31], v[220:223], v[180:183], v[0:3]
	v_mfma_f32_16x16x32_bf16 v[0:3], v[208:211], v[184:187], v[20:23]
	v_mfma_f32_16x16x32_bf16 v[16:19], v[216:219], v[188:191], v[0:3]
	v_mfma_f32_16x16x32_bf16 v[0:3], v[212:215], v[184:187], v[168:171]
	v_mfma_f32_16x16x32_bf16 v[20:23], v[220:223], v[188:191], v[0:3]
	v_mfma_f32_16x16x32_bf16 v[0:3], v[208:211], v[196:199], v[12:15]
	v_mfma_f32_16x16x32_bf16 v[8:11], v[216:219], v[200:203], v[0:3]
	v_mfma_f32_16x16x32_bf16 v[0:3], v[212:215], v[196:199], v[172:175]
	v_mfma_f32_16x16x32_bf16 v[12:15], v[220:223], v[200:203], v[0:3]
	v_mfma_f32_16x16x32_bf16 v[0:3], v[208:211], v[204:207], v[4:7]
	v_mfma_f32_16x16x32_bf16 v[4:7], v[212:215], v[204:207], v[192:195]
	v_mfma_f32_16x16x32_bf16 v[0:3], v[216:219], v[236:239], v[0:3]
	v_mfma_f32_16x16x32_bf16 v[4:7], v[220:223], v[236:239], v[4:7]
	s_setprio 0
	s_barrier
	s_and_saveexec_b64 s[64:65], s[2:3]
	s_cbranch_execz .LBB0_405
	s_barrier
	s_branch .LBB0_405

; #define STAGE(P, BASE, br, kt) do { const char* _gb = (const char*)(BASE) + ((size_t)(br) * K + (size_t)(kt) * BK) * 2; \
;     __builtin_amdgcn_global_load_lds((const unsigned*)(_gb + loff0), (unsigned*)((char*)(P) + tid * 16), 16, 0, 0); \
;     __builtin_amdgcn_global_load_lds((const unsigned*)(_gb + (size_t)K * 128 + loff0), (unsigned*)((char*)(P) + tid * 16 + 8192), 16, 0, 0); } while (0)
; #define LDA(dst, b, h) for (int m = 0; m < 4; ++m) { \
;     dst[m][0] = *reinterpret_cast<const bf16x8*>((char*)SA(b, h) + aoff0 + m * 2048); \
;     dst[m][1] = *reinterpret_cast<const bf16x8*>((char*)SA(b, h) + aoff1 + m * 2048); }
; #define LDB(dst, b, h) for (int n = 0; n < 2; ++n) { \
;     dst[n][0] = *reinterpret_cast<const bf16x8*>((char*)SB(b, h) + boff0 + n * 256); \
;     dst[n][1] = *reinterpret_cast<const bf16x8*>((char*)SB(b, h) + boff1 + n * 256); }
; #define MMA(ai, bj, At, Btf) do { __builtin_amdgcn_s_setprio(1); \
;     for (int m = 0; m < 4; ++m) for (int n = 0; n < 2; ++n) for (int k = 0; k < 2; ++k) \
;       acc[ai][bj][m][n] = __builtin_amdgcn_mfma_f32_16x16x32_bf16(Btf[n][k], At[m][k], acc[ai][bj][m][n], 0, 0, 0); \
;     __builtin_amdgcn_s_setprio(0); } while (0)
; #define WAIT_V(n) asm volatile("s_waitcnt vmcnt(" #n ")" ::: "memory")
; #define WAIT_L(n) asm volatile("s_waitcnt lgkmcnt(" #n ")" ::: "memory")
; #define BAR __builtin_amdgcn_s_barrier()
; #define SCHED __builtin_amdgcn_sched_barrier(0)
; template <int EPI> ...
;     ...
;   WAIT_V(4); BAR;
;   STAGE(SB(1, 0), Bt, bcol, 1); STAGE(SA(1, 0), A, brow, 1); STAGE(SB(1, 1), Bt, bcol + HALF, 1);
;   WAIT_V(6); BAR;
;   for (int t = 0; t < nt - 2; t += 2) {
;     LDB(B0, 0, 0); SCHED; LDA(At, 0, 0); STAGE(SA(1, 1), A, brow + HALF, t + 1);
;     WAIT_L(8); BAR; WAIT_L(0); MMA(0, 0, At, B0); BAR; SCHED;
;     LDB(B1, 0, 1); STAGE(SB(0, 0), Bt, bcol, t + 2);
;     BAR; WAIT_L(0); MMA(0, 1, At, B1); BAR;
;     LDA(At, 0, 1); STAGE(SA(0, 0), A, brow, t + 2);
;     BAR; WAIT_L(0); MMA(1, 0, At, B0); BAR; SCHED;
;     STAGE(SB(0, 1), Bt, bcol + HALF, t + 2);
;     WAIT_V(6); BAR; MMA(1, 1, At, B1); BAR;
.LBB0_1017:
	s_or_b64 exec, exec, s[68:69]
	v_readfirstlane_b32 s59, v143
	v_lshl_add_u64 v[6:7], v[0:1], 0, s[10:11]
	s_mov_b32 m0, s59
	v_readfirstlane_b32 s59, v144
	s_waitcnt vmcnt(2)
	s_barrier
	global_load_lds_dwordx4 v[6:7], off
	v_lshl_add_u64 v[0:1], v[0:1], 0, s[12:13]
	s_mov_b32 m0, s59
	v_readfirstlane_b32 s59, v145
	global_load_lds_dwordx4 v[0:1], off
	v_lshl_add_u64 v[0:1], v[2:3], 0, s[10:11]
	s_mov_b32 m0, s59
	v_readfirstlane_b32 s59, v146
	global_load_lds_dwordx4 v[0:1], off
	v_lshl_add_u64 v[0:1], v[2:3], 0, s[12:13]
	s_mov_b32 m0, s59
	v_readfirstlane_b32 s59, v147
	global_load_lds_dwordx4 v[0:1], off
	v_lshl_add_u64 v[0:1], v[4:5], 0, s[10:11]
	s_mov_b32 m0, s59
	v_readfirstlane_b32 s59, v148
	global_load_lds_dwordx4 v[0:1], off
	v_lshl_add_u64 v[0:1], v[4:5], 0, s[12:13]
	s_mov_b32 m0, s59
	s_add_u32 s64, s6, s64
	global_load_lds_dwordx4 v[0:1], off
	s_addc_u32 s65, s7, s65
	s_add_u32 s66, s6, s66
	v_mov_b32_e32 v0, 0
	s_addc_u32 s67, s7, s67
	s_mov_b32 s59, -2
	v_mov_b32_e32 v1, v0
	v_mov_b32_e32 v2, v0
	v_mov_b32_e32 v3, v0
	v_mov_b32_e32 v4, v0
	v_mov_b32_e32 v5, v0
	v_mov_b32_e32 v6, v0
	v_mov_b32_e32 v7, v0
	s_waitcnt vmcnt(6)
	s_barrier
.LBB0_1018:
	ds_read_b128 v[160:163], v152
	ds_read_b128 v[164:167], v152 offset:256
	ds_read_b128 v[168:171], v153
	ds_read_b128 v[172:175], v153 offset:256
	v_lshl_add_u64 v[224:225], s[66:67], 0, v[132:133]
	v_readfirstlane_b32 s68, v150
	v_lshl_add_u64 v[208:209], v[224:225], 0, s[16:17]
	s_mov_b32 m0, s68
	v_readfirstlane_b32 s68, v151
	ds_read_b128 v[176:179], v149
	ds_read_b128 v[180:183], v149 offset:1024
	ds_read_b128 v[184:187], v149 offset:2048
	ds_read_b128 v[188:191], v149 offset:3072
	ds_read_b128 v[192:195], v149 offset:4096
	ds_read_b128 v[196:199], v149 offset:5120
	ds_read_b128 v[200:203], v149 offset:6144
	ds_read_b128 v[204:207], v149 offset:7168
	global_load_lds_dwordx4 v[208:209], off
	v_lshl_add_u64 v[208:209], v[224:225], 0, s[18:19]
	s_mov_b32 m0, s68
	s_nop 0
	global_load_lds_dwordx4 v[208:209], off
	s_waitcnt lgkmcnt(8)
	ds_read_b128 v[208:211], v154
	ds_read_b128 v[212:215], v154 offset:256
	ds_read_b128 v[216:219], v155
	ds_read_b128 v[220:223], v155 offset:256
	s_barrier
	s_waitcnt lgkmcnt(0)
	s_setprio 1
	s_waitcnt lgkmcnt(0)
	v_mfma_f32_16x16x32_bf16 v[124:127], v[160:163], v[176:179], v[124:127]
	v_mfma_f32_16x16x32_bf16 v[120:123], v[164:167], v[176:179], v[120:123]
	v_mfma_f32_16x16x32_bf16 v[116:119], v[160:163], v[184:187], v[116:119]
	v_mfma_f32_16x16x32_bf16 v[112:115], v[164:167], v[184:187], v[112:115]
	v_mfma_f32_16x16x32_bf16 v[108:111], v[160:163], v[192:195], v[108:111]
	v_mfma_f32_16x16x32_bf16 v[104:107], v[164:167], v[192:195], v[104:107]
	v_mfma_f32_16x16x32_bf16 v[100:103], v[160:163], v[200:203], v[100:103]
	v_mfma_f32_16x16x32_bf16 v[96:99], v[164:167], v[200:203], v[96:99]
	v_mfma_f32_16x16x32_bf16 v[124:127], v[168:171], v[180:183], v[124:127]
	v_mfma_f32_16x16x32_bf16 v[120:123], v[172:175], v[180:183], v[120:123]
	v_mfma_f32_16x16x32_bf16 v[116:119], v[168:171], v[188:191], v[116:119]
	v_mfma_f32_16x16x32_bf16 v[112:115], v[172:175], v[188:191], v[112:115]
	v_mfma_f32_16x16x32_bf16 v[108:111], v[168:171], v[196:199], v[108:111]
	v_mfma_f32_16x16x32_bf16 v[104:107], v[172:175], v[196:199], v[104:107]
	v_mfma_f32_16x16x32_bf16 v[100:103], v[168:171], v[204:207], v[100:103]
	v_mfma_f32_16x16x32_bf16 v[96:99], v[172:175], v[204:207], v[96:99]
	s_setprio 0
	s_waitcnt lgkmcnt(0)
	s_setprio 1
	s_waitcnt lgkmcnt(0)
	v_mfma_f32_16x16x32_bf16 v[92:95], v[208:211], v[176:179], v[92:95]
	v_mfma_f32_16x16x32_bf16 v[88:91], v[212:215], v[176:179], v[88:91]
	v_mfma_f32_16x16x32_bf16 v[84:87], v[208:211], v[184:187], v[84:87]
	v_mfma_f32_16x16x32_bf16 v[80:83], v[212:215], v[184:187], v[80:83]
	v_mfma_f32_16x16x32_bf16 v[76:79], v[208:211], v[192:195], v[76:79]
	v_mfma_f32_16x16x32_bf16 v[72:75], v[212:215], v[192:195], v[72:75]
	v_mfma_f32_16x16x32_bf16 v[68:71], v[208:211], v[200:203], v[68:71]
	v_mfma_f32_16x16x32_bf16 v[64:67], v[212:215], v[200:203], v[64:67]
	v_mfma_f32_16x16x32_bf16 v[92:95], v[216:219], v[180:183], v[92:95]
	v_mfma_f32_16x16x32_bf16 v[88:91], v[220:223], v[180:183], v[88:91]
	v_mfma_f32_16x16x32_bf16 v[84:87], v[216:219], v[188:191], v[84:87]
	v_mfma_f32_16x16x32_bf16 v[80:83], v[220:223], v[188:191], v[80:83]
	v_mfma_f32_16x16x32_bf16 v[76:79], v[216:219], v[196:199], v[76:79]
	v_mfma_f32_16x16x32_bf16 v[72:75], v[220:223], v[196:199], v[72:75]
	v_mfma_f32_16x16x32_bf16 v[68:71], v[216:219], v[204:207], v[68:71]
	v_mfma_f32_16x16x32_bf16 v[64:67], v[220:223], v[204:207], v[64:67]
	s_setprio 0
	s_barrier
	v_lshl_add_u64 v[226:227], s[64:65], 0, v[132:133]
	v_readfirstlane_b32 s68, v135
	v_lshl_add_u64 v[228:229], v[226:227], 0, s[20:21]
	s_mov_b32 m0, s68
	v_readfirstlane_b32 s68, v136
	global_load_lds_dwordx4 v[228:229], off
	v_lshl_add_u64 v[228:229], v[226:227], 0, s[22:23]
	s_mov_b32 m0, s68
	s_nop 0
	global_load_lds_dwordx4 v[228:229], off
	v_readfirstlane_b32 s68, v137
	v_lshl_add_u64 v[228:229], v[224:225], 0, s[24:25]
	s_mov_b32 m0, s68
	v_readfirstlane_b32 s68, v138
	ds_read_b128 v[176:179], v149 offset:16384
	ds_read_b128 v[180:183], v149 offset:17408
	ds_read_b128 v[184:187], v149 offset:18432
	ds_read_b128 v[188:191], v149 offset:19456
	ds_read_b128 v[192:195], v149 offset:20480
	ds_read_b128 v[196:199], v149 offset:21504
	ds_read_b128 v[200:203], v149 offset:22528
	ds_read_b128 v[204:207], v149 offset:23552
	global_load_lds_dwordx4 v[228:229], off
	v_lshl_add_u64 v[228:229], v[224:225], 0, s[26:27]
	s_mov_b32 m0, s68
	s_nop 0
	global_load_lds_dwordx4 v[228:229], off
	v_readfirstlane_b32 s68, v139
	v_lshl_add_u64 v[246:247], v[226:227], 0, s[28:29]
	s_mov_b32 m0, s68
	v_readfirstlane_b32 s68, v140
	global_load_lds_dwordx4 v[246:247], off
	v_lshl_add_u64 v[246:247], v[226:227], 0, s[30:31]
	s_mov_b32 m0, s68
	s_nop 0
	global_load_lds_dwordx4 v[246:247], off
	s_waitcnt vmcnt(6)
	s_barrier
; #define STAGE(P, BASE, br, kt) do { const char* _gb = (const char*)(BASE) + ((size_t)(br) * K + (size_t)(kt) * BK) * 2; \
;     __builtin_amdgcn_global_load_lds((const unsigned*)(_gb + loff0), (unsigned*)((char*)(P) + tid * 16), 16, 0, 0); \
;     __builtin_amdgcn_global_load_lds((const unsigned*)(_gb + (size_t)K * 128 + loff0), (unsigned*)((char*)(P) + tid * 16 + 8192), 16, 0, 0); } while (0)
; #define LDA(dst, b, h) for (int m = 0; m < 4; ++m) { \
;     dst[m][0] = *reinterpret_cast<const bf16x8*>((char*)SA(b, h) + aoff0 + m * 2048); \
;     dst[m][1] = *reinterpret_cast<const bf16x8*>((char*)SA(b, h) + aoff1 + m * 2048); }
; #define LDB(dst, b, h) for (int n = 0; n < 2; ++n) { \
;     dst[n][0] = *reinterpret_cast<const bf16x8*>((char*)SB(b, h) + boff0 + n * 256); \
;     dst[n][1] = *reinterpret_cast<const bf16x8*>((char*)SB(b, h) + boff1 + n * 256); }
; #define MMA(ai, bj, At, Btf) do { __builtin_amdgcn_s_setprio(1); \
;     for (int m = 0; m < 4; ++m) for (int n = 0; n < 2; ++n) for (int k = 0; k < 2; ++k) \
;       acc[ai][bj][m][n] = __builtin_amdgcn_mfma_f32_16x16x32_bf16(Btf[n][k], At[m][k], acc[ai][bj][m][n], 0, 0, 0); \
;     __builtin_amdgcn_s_setprio(0); } while (0)
; #define WAIT_V(n) asm volatile("s_waitcnt vmcnt(" #n ")" ::: "memory")
; #define WAIT_L(n) asm volatile("s_waitcnt lgkmcnt(" #n ")" ::: "memory")
; #define BAR __builtin_amdgcn_s_barrier()
; #define SCHED __builtin_amdgcn_sched_barrier(0)
; template <int EPI> ...
;     ...
;     BAR; WAIT_L(0); MMA(1, 0, At, B0); BAR; SCHED;
;     STAGE(SB(0, 1), Bt, bcol + HALF, t + 2);
;     WAIT_V(6); BAR; MMA(1, 1, At, B1); BAR;
;     LDB(B0, 1, 0); SCHED; LDA(At, 1, 0); STAGE(SA(0, 1), A, brow + HALF, t + 2);
;     WAIT_L(8); BAR; WAIT_L(0); MMA(0, 0, At, B0); BAR; SCHED;
;     LDB(B1, 1, 1); STAGE(SB(1, 0), Bt, bcol, t + 3);
;     BAR; WAIT_L(0); MMA(0, 1, At, B1); BAR;
	s_waitcnt lgkmcnt(0)
	s_setprio 1
	s_waitcnt lgkmcnt(0)
	v_mfma_f32_16x16x32_bf16 v[60:63], v[160:163], v[176:179], v[60:63]
	v_mfma_f32_16x16x32_bf16 v[56:59], v[164:167], v[176:179], v[56:59]
	v_mfma_f32_16x16x32_bf16 v[52:55], v[160:163], v[184:187], v[52:55]
	v_mfma_f32_16x16x32_bf16 v[48:51], v[164:167], v[184:187], v[48:51]
	v_mfma_f32_16x16x32_bf16 v[44:47], v[160:163], v[192:195], v[44:47]
	v_mfma_f32_16x16x32_bf16 v[40:43], v[164:167], v[192:195], v[40:43]
	v_mfma_f32_16x16x32_bf16 v[36:39], v[160:163], v[200:203], v[36:39]
	v_mfma_f32_16x16x32_bf16 v[32:35], v[164:167], v[200:203], v[32:35]
	v_mfma_f32_16x16x32_bf16 v[60:63], v[168:171], v[180:183], v[60:63]
	v_mfma_f32_16x16x32_bf16 v[56:59], v[172:175], v[180:183], v[56:59]
	v_mfma_f32_16x16x32_bf16 v[52:55], v[168:171], v[188:191], v[52:55]
	v_mfma_f32_16x16x32_bf16 v[48:51], v[172:175], v[188:191], v[48:51]
	v_mfma_f32_16x16x32_bf16 v[44:47], v[168:171], v[196:199], v[44:47]
	v_mfma_f32_16x16x32_bf16 v[40:43], v[172:175], v[196:199], v[40:43]
	v_mfma_f32_16x16x32_bf16 v[36:39], v[168:171], v[204:207], v[36:39]
	v_mfma_f32_16x16x32_bf16 v[32:35], v[172:175], v[204:207], v[32:35]
	s_setprio 0
	s_setprio 1
	v_mfma_f32_16x16x32_bf16 v[28:31], v[208:211], v[176:179], v[28:31]
	v_mfma_f32_16x16x32_bf16 v[24:27], v[212:215], v[176:179], v[24:27]
	v_mfma_f32_16x16x32_bf16 v[20:23], v[208:211], v[184:187], v[20:23]
	v_mfma_f32_16x16x32_bf16 v[16:19], v[212:215], v[184:187], v[16:19]
	v_mfma_f32_16x16x32_bf16 v[12:15], v[208:211], v[192:195], v[12:15]
	v_mfma_f32_16x16x32_bf16 v[8:11], v[212:215], v[192:195], v[8:11]
	v_mfma_f32_16x16x32_bf16 v[4:7], v[208:211], v[200:203], v[4:7]
	v_mfma_f32_16x16x32_bf16 v[0:3], v[212:215], v[200:203], v[0:3]
	v_mfma_f32_16x16x32_bf16 v[28:31], v[216:219], v[180:183], v[28:31]
	v_mfma_f32_16x16x32_bf16 v[24:27], v[220:223], v[180:183], v[24:27]
	v_mfma_f32_16x16x32_bf16 v[20:23], v[216:219], v[188:191], v[20:23]
	v_mfma_f32_16x16x32_bf16 v[16:19], v[220:223], v[188:191], v[16:19]
	v_mfma_f32_16x16x32_bf16 v[12:15], v[216:219], v[196:199], v[12:15]
	v_mfma_f32_16x16x32_bf16 v[8:11], v[220:223], v[196:199], v[8:11]
	v_mfma_f32_16x16x32_bf16 v[4:7], v[216:219], v[204:207], v[4:7]
	v_mfma_f32_16x16x32_bf16 v[0:3], v[220:223], v[204:207], v[0:3]
	s_setprio 0
	s_barrier
	ds_read_b128 v[160:163], v156
	ds_read_b128 v[164:167], v156 offset:256
	ds_read_b128 v[168:171], v157
	ds_read_b128 v[172:175], v157 offset:256
	v_readfirstlane_b32 s68, v141
	v_lshl_add_u64 v[208:209], v[224:225], 0, s[36:37]
	s_mov_b32 m0, s68
	v_readfirstlane_b32 s68, v142
	ds_read_b128 v[176:179], v149 offset:32768
	ds_read_b128 v[180:183], v149 offset:33792
	ds_read_b128 v[184:187], v149 offset:34816
	ds_read_b128 v[188:191], v149 offset:35840
	ds_read_b128 v[192:195], v149 offset:36864
	ds_read_b128 v[196:199], v149 offset:37888
	ds_read_b128 v[200:203], v149 offset:38912
	ds_read_b128 v[204:207], v149 offset:39936
	global_load_lds_dwordx4 v[208:209], off
	v_lshl_add_u64 v[208:209], v[224:225], 0, s[38:39]
	s_mov_b32 m0, s68
	s_nop 0
	global_load_lds_dwordx4 v[208:209], off
	s_waitcnt lgkmcnt(8)
	ds_read_b128 v[208:211], v158
	ds_read_b128 v[212:215], v158 offset:256
	ds_read_b128 v[216:219], v159
	ds_read_b128 v[220:223], v159 offset:256
	s_barrier
	s_waitcnt lgkmcnt(0)
	s_setprio 1
	s_waitcnt lgkmcnt(0)
	v_mfma_f32_16x16x32_bf16 v[124:127], v[160:163], v[176:179], v[124:127]
	v_mfma_f32_16x16x32_bf16 v[120:123], v[164:167], v[176:179], v[120:123]
	v_mfma_f32_16x16x32_bf16 v[116:119], v[160:163], v[184:187], v[116:119]
	v_mfma_f32_16x16x32_bf16 v[112:115], v[164:167], v[184:187], v[112:115]
	v_mfma_f32_16x16x32_bf16 v[108:111], v[160:163], v[192:195], v[108:111]
	v_mfma_f32_16x16x32_bf16 v[104:107], v[164:167], v[192:195], v[104:107]
	v_mfma_f32_16x16x32_bf16 v[100:103], v[160:163], v[200:203], v[100:103]
	v_mfma_f32_16x16x32_bf16 v[96:99], v[164:167], v[200:203], v[96:99]
	v_mfma_f32_16x16x32_bf16 v[124:127], v[168:171], v[180:183], v[124:127]
	v_mfma_f32_16x16x32_bf16 v[120:123], v[172:175], v[180:183], v[120:123]
	v_mfma_f32_16x16x32_bf16 v[116:119], v[168:171], v[188:191], v[116:119]
	v_mfma_f32_16x16x32_bf16 v[112:115], v[172:175], v[188:191], v[112:115]
	v_mfma_f32_16x16x32_bf16 v[108:111], v[168:171], v[196:199], v[108:111]
	v_mfma_f32_16x16x32_bf16 v[104:107], v[172:175], v[196:199], v[104:107]
	v_mfma_f32_16x16x32_bf16 v[100:103], v[168:171], v[204:207], v[100:103]
	v_mfma_f32_16x16x32_bf16 v[96:99], v[172:175], v[204:207], v[96:99]
	s_setprio 0
	s_waitcnt lgkmcnt(0)
	s_setprio 1
	s_waitcnt lgkmcnt(0)
	v_mfma_f32_16x16x32_bf16 v[92:95], v[208:211], v[176:179], v[92:95]
	v_mfma_f32_16x16x32_bf16 v[88:91], v[212:215], v[176:179], v[88:91]
	v_mfma_f32_16x16x32_bf16 v[84:87], v[208:211], v[184:187], v[84:87]
	v_mfma_f32_16x16x32_bf16 v[80:83], v[212:215], v[184:187], v[80:83]
	v_mfma_f32_16x16x32_bf16 v[76:79], v[208:211], v[192:195], v[76:79]
	v_mfma_f32_16x16x32_bf16 v[72:75], v[212:215], v[192:195], v[72:75]
	v_mfma_f32_16x16x32_bf16 v[68:71], v[208:211], v[200:203], v[68:71]
	v_mfma_f32_16x16x32_bf16 v[64:67], v[212:215], v[200:203], v[64:67]
	v_mfma_f32_16x16x32_bf16 v[92:95], v[216:219], v[180:183], v[92:95]
	v_mfma_f32_16x16x32_bf16 v[88:91], v[220:223], v[180:183], v[88:91]
	v_mfma_f32_16x16x32_bf16 v[84:87], v[216:219], v[188:191], v[84:87]
	v_mfma_f32_16x16x32_bf16 v[80:83], v[220:223], v[188:191], v[80:83]
	v_mfma_f32_16x16x32_bf16 v[76:79], v[216:219], v[196:199], v[76:79]
	v_mfma_f32_16x16x32_bf16 v[72:75], v[220:223], v[196:199], v[72:75]
	v_mfma_f32_16x16x32_bf16 v[68:71], v[216:219], v[204:207], v[68:71]
	v_mfma_f32_16x16x32_bf16 v[64:67], v[220:223], v[204:207], v[64:67]
	s_setprio 0
	s_barrier
; #define STAGE(P, BASE, br, kt) do { const char* _gb = (const char*)(BASE) + ((size_t)(br) * K + (size_t)(kt) * BK) * 2; \
;     __builtin_amdgcn_global_load_lds((const unsigned*)(_gb + loff0), (unsigned*)((char*)(P) + tid * 16), 16, 0, 0); \
;     __builtin_amdgcn_global_load_lds((const unsigned*)(_gb + (size_t)K * 128 + loff0), (unsigned*)((char*)(P) + tid * 16 + 8192), 16, 0, 0); } while (0)
; #define LDA(dst, b, h) for (int m = 0; m < 4; ++m) { \
;     dst[m][0] = *reinterpret_cast<const bf16x8*>((char*)SA(b, h) + aoff0 + m * 2048); \
;     dst[m][1] = *reinterpret_cast<const bf16x8*>((char*)SA(b, h) + aoff1 + m * 2048); }
; #define LDB(dst, b, h) for (int n = 0; n < 2; ++n) { \
;     dst[n][0] = *reinterpret_cast<const bf16x8*>((char*)SB(b, h) + boff0 + n * 256); \
;     dst[n][1] = *reinterpret_cast<const bf16x8*>((char*)SB(b, h) + boff1 + n * 256); }
; #define MMA(ai, bj, At, Btf) do { __builtin_amdgcn_s_setprio(1); \
;     for (int m = 0; m < 4; ++m) for (int n = 0; n < 2; ++n) for (int k = 0; k < 2; ++k) \
;       acc[ai][bj][m][n] = __builtin_amdgcn_mfma_f32_16x16x32_bf16(Btf[n][k], At[m][k], acc[ai][bj][m][n], 0, 0, 0); \
;     __builtin_amdgcn_s_setprio(0); } while (0)
; #define WAIT_V(n) asm volatile("s_waitcnt vmcnt(" #n ")" ::: "memory")
; #define WAIT_L(n) asm volatile("s_waitcnt lgkmcnt(" #n ")" ::: "memory")
; #define BAR __builtin_amdgcn_s_barrier()
; #define SCHED __builtin_amdgcn_sched_barrier(0)
; template <int EPI> ...
;     ...
;     LDB(B1, 1, 1); STAGE(SB(1, 0), Bt, bcol, t + 3);
;     BAR; WAIT_L(0); MMA(0, 1, At, B1); BAR;
;     LDA(At, 1, 1); STAGE(SA(1, 0), A, brow, t + 3);
;     BAR; WAIT_L(0); MMA(1, 0, At, B0); BAR; SCHED;
;     STAGE(SB(1, 1), Bt, bcol + HALF, t + 3);
;     WAIT_V(6); BAR; MMA(1, 1, At, B1); BAR;
;   }
;   { LDB(B0, 0, 0); LDA(At, 0, 0); STAGE(SA(1, 1), A, brow + HALF, nt - 1);
;     BAR; WAIT_L(0); MMA(0, 0, At, B0); BAR;
	v_readfirstlane_b32 s68, v143
	v_lshl_add_u64 v[228:229], v[226:227], 0, s[46:47]
	s_mov_b32 m0, s68
	v_readfirstlane_b32 s68, v144
	global_load_lds_dwordx4 v[228:229], off
	v_lshl_add_u64 v[228:229], v[226:227], 0, s[48:49]
	s_mov_b32 m0, s68
	s_nop 0
	global_load_lds_dwordx4 v[228:229], off
	v_readfirstlane_b32 s68, v145
	v_lshl_add_u64 v[228:229], v[224:225], 0, s[50:51]
	s_mov_b32 m0, s68
	v_readfirstlane_b32 s68, v146
	ds_read_b128 v[176:179], v149 offset:49152
	ds_read_b128 v[180:183], v149 offset:50176
	ds_read_b128 v[184:187], v149 offset:51200
	ds_read_b128 v[188:191], v149 offset:52224
	ds_read_b128 v[192:195], v149 offset:53248
	ds_read_b128 v[196:199], v149 offset:54272
	ds_read_b128 v[200:203], v149 offset:55296
	ds_read_b128 v[204:207], v149 offset:56320
	global_load_lds_dwordx4 v[228:229], off
	v_lshl_add_u64 v[224:225], v[224:225], 0, s[52:53]
	s_mov_b32 m0, s68
	s_nop 0
	global_load_lds_dwordx4 v[224:225], off
	v_readfirstlane_b32 s68, v147
	v_lshl_add_u64 v[246:247], v[226:227], 0, s[54:55]
	s_mov_b32 m0, s68
	v_readfirstlane_b32 s68, v148
	global_load_lds_dwordx4 v[246:247], off
	v_lshl_add_u64 v[246:247], v[226:227], 0, s[56:57]
	s_mov_b32 m0, s68
	s_nop 0
	global_load_lds_dwordx4 v[246:247], off
	s_waitcnt vmcnt(6)
	s_barrier
	s_waitcnt lgkmcnt(0)
	s_setprio 1
	s_waitcnt lgkmcnt(0)
	v_mfma_f32_16x16x32_bf16 v[60:63], v[160:163], v[176:179], v[60:63]
	v_mfma_f32_16x16x32_bf16 v[56:59], v[164:167], v[176:179], v[56:59]
	v_mfma_f32_16x16x32_bf16 v[52:55], v[160:163], v[184:187], v[52:55]
	v_mfma_f32_16x16x32_bf16 v[48:51], v[164:167], v[184:187], v[48:51]
	v_mfma_f32_16x16x32_bf16 v[44:47], v[160:163], v[192:195], v[44:47]
	v_mfma_f32_16x16x32_bf16 v[40:43], v[164:167], v[192:195], v[40:43]
	v_mfma_f32_16x16x32_bf16 v[36:39], v[160:163], v[200:203], v[36:39]
	v_mfma_f32_16x16x32_bf16 v[32:35], v[164:167], v[200:203], v[32:35]
	v_mfma_f32_16x16x32_bf16 v[60:63], v[168:171], v[180:183], v[60:63]
	v_mfma_f32_16x16x32_bf16 v[56:59], v[172:175], v[180:183], v[56:59]
	v_mfma_f32_16x16x32_bf16 v[52:55], v[168:171], v[188:191], v[52:55]
	v_mfma_f32_16x16x32_bf16 v[48:51], v[172:175], v[188:191], v[48:51]
	v_mfma_f32_16x16x32_bf16 v[44:47], v[168:171], v[196:199], v[44:47]
	v_mfma_f32_16x16x32_bf16 v[40:43], v[172:175], v[196:199], v[40:43]
	v_mfma_f32_16x16x32_bf16 v[36:39], v[168:171], v[204:207], v[36:39]
	v_mfma_f32_16x16x32_bf16 v[32:35], v[172:175], v[204:207], v[32:35]
	s_setprio 0
	s_setprio 1
	v_mfma_f32_16x16x32_bf16 v[28:31], v[208:211], v[176:179], v[28:31]
	v_mfma_f32_16x16x32_bf16 v[24:27], v[212:215], v[176:179], v[24:27]
	v_mfma_f32_16x16x32_bf16 v[20:23], v[208:211], v[184:187], v[20:23]
	v_mfma_f32_16x16x32_bf16 v[16:19], v[212:215], v[184:187], v[16:19]
	v_mfma_f32_16x16x32_bf16 v[12:15], v[208:211], v[192:195], v[12:15]
	v_mfma_f32_16x16x32_bf16 v[8:11], v[212:215], v[192:195], v[8:11]
	v_mfma_f32_16x16x32_bf16 v[4:7], v[208:211], v[200:203], v[4:7]
	v_mfma_f32_16x16x32_bf16 v[0:3], v[212:215], v[200:203], v[0:3]
	v_mfma_f32_16x16x32_bf16 v[28:31], v[216:219], v[180:183], v[28:31]
	v_mfma_f32_16x16x32_bf16 v[24:27], v[220:223], v[180:183], v[24:27]
	v_mfma_f32_16x16x32_bf16 v[20:23], v[216:219], v[188:191], v[20:23]
	v_mfma_f32_16x16x32_bf16 v[16:19], v[220:223], v[188:191], v[16:19]
	v_mfma_f32_16x16x32_bf16 v[12:15], v[216:219], v[196:199], v[12:15]
	v_mfma_f32_16x16x32_bf16 v[8:11], v[220:223], v[196:199], v[8:11]
	v_mfma_f32_16x16x32_bf16 v[4:7], v[216:219], v[204:207], v[4:7]
	v_mfma_f32_16x16x32_bf16 v[0:3], v[220:223], v[204:207], v[0:3]
	s_setprio 0
	s_add_i32 s59, s59, 2
	s_add_u32 s64, s64, 0x100
	s_addc_u32 s65, s65, 0
	s_add_u32 s66, s66, 0x100
	s_addc_u32 s67, s67, 0
	s_cmp_lt_u32 s59, 28
	s_barrier
	s_cbranch_scc1 .LBB0_1018
	s_add_u32 s62, s72, s62
	s_addc_u32 s63, s73, s63
	v_readfirstlane_b32 s59, v150
	v_lshl_add_u64 v[208:209], s[62:63], 0, v[128:129]
	s_mov_b32 m0, s59
	v_readfirstlane_b32 s59, v151
	ds_read_b128 v[160:163], v152
	ds_read_b128 v[164:167], v152 offset:256
	ds_read_b128 v[168:171], v153
	ds_read_b128 v[172:175], v153 offset:256
	ds_read_b128 v[176:179], v149
	ds_read_b128 v[180:183], v149 offset:1024
	ds_read_b128 v[184:187], v149 offset:2048
	ds_read_b128 v[188:191], v149 offset:3072
	ds_read_b128 v[192:195], v149 offset:4096
	ds_read_b128 v[196:199], v149 offset:5120
	ds_read_b128 v[200:203], v149 offset:6144
	ds_read_b128 v[204:207], v149 offset:7168
	global_load_lds_dwordx4 v[208:209], off
	v_lshl_add_u64 v[208:209], v[208:209], 0, s[8:9]
	s_mov_b32 m0, s59
	s_nop 0
	global_load_lds_dwordx4 v[208:209], off
	s_barrier
	s_waitcnt lgkmcnt(0)
	s_setprio 1
	s_waitcnt lgkmcnt(0)
	v_mfma_f32_16x16x32_bf16 v[124:127], v[160:163], v[176:179], v[124:127]
	v_mfma_f32_16x16x32_bf16 v[116:119], v[160:163], v[184:187], v[116:119]
	v_mfma_f32_16x16x32_bf16 v[108:111], v[160:163], v[192:195], v[108:111]
	v_mfma_f32_16x16x32_bf16 v[100:103], v[160:163], v[200:203], v[100:103]
	v_mfma_f32_16x16x32_bf16 v[96:99], v[164:167], v[200:203], v[96:99]
	v_mfma_f32_16x16x32_bf16 v[124:127], v[168:171], v[180:183], v[124:127]
	v_mfma_f32_16x16x32_bf16 v[120:123], v[164:167], v[176:179], v[120:123]
	v_mfma_f32_16x16x32_bf16 v[116:119], v[168:171], v[188:191], v[116:119]
	v_mfma_f32_16x16x32_bf16 v[112:115], v[164:167], v[184:187], v[112:115]
	v_mfma_f32_16x16x32_bf16 v[108:111], v[168:171], v[196:199], v[108:111]
	v_mfma_f32_16x16x32_bf16 v[104:107], v[164:167], v[192:195], v[104:107]
	v_mfma_f32_16x16x32_bf16 v[100:103], v[168:171], v[204:207], v[100:103]
	v_mfma_f32_16x16x32_bf16 v[96:99], v[172:175], v[204:207], v[96:99]
	v_mfma_f32_16x16x32_bf16 v[208:211], v[172:175], v[180:183], v[120:123]
	v_mfma_f32_16x16x32_bf16 v[212:215], v[172:175], v[188:191], v[112:115]
	v_mfma_f32_16x16x32_bf16 v[216:219], v[172:175], v[196:199], v[104:107]
	s_setprio 0
	s_barrier
; #define LDA(dst, b, h) for (int m = 0; m < 4; ++m) { \
;     dst[m][0] = *reinterpret_cast<const bf16x8*>((char*)SA(b, h) + aoff0 + m * 2048); \
;     dst[m][1] = *reinterpret_cast<const bf16x8*>((char*)SA(b, h) + aoff1 + m * 2048); }
; #define LDB(dst, b, h) for (int n = 0; n < 2; ++n) { \
;     dst[n][0] = *reinterpret_cast<const bf16x8*>((char*)SB(b, h) + boff0 + n * 256); \
;     dst[n][1] = *reinterpret_cast<const bf16x8*>((char*)SB(b, h) + boff1 + n * 256); }
; #define MMA(ai, bj, At, Btf) do { __builtin_amdgcn_s_setprio(1); \
;     for (int m = 0; m < 4; ++m) for (int n = 0; n < 2; ++n) for (int k = 0; k < 2; ++k) \
;       acc[ai][bj][m][n] = __builtin_amdgcn_mfma_f32_16x16x32_bf16(Btf[n][k], At[m][k], acc[ai][bj][m][n], 0, 0, 0); \
;     __builtin_amdgcn_s_setprio(0); } while (0)
; #define WAIT_V(n) asm volatile("s_waitcnt vmcnt(" #n ")" ::: "memory")
; #define WAIT_L(n) asm volatile("s_waitcnt lgkmcnt(" #n ")" ::: "memory")
; #define BAR __builtin_amdgcn_s_barrier()
; template <int EPI> ...
;     ...
;     LDB(B1, 0, 1); BAR; WAIT_L(0); MMA(0, 1, At, B1); BAR;
;     LDA(At, 0, 1); WAIT_V(4); BAR; WAIT_L(0); MMA(1, 0, At, B0); MMA(1, 1, At, B1); BAR; }
;   { LDB(B0, 1, 0); LDA(At, 1, 0); WAIT_V(2); BAR; WAIT_L(0); MMA(0, 0, At, B0); BAR;
	s_nop 0
	ds_read_b128 v[104:107], v154
	ds_read_b128 v[112:115], v154 offset:256
	ds_read_b128 v[120:123], v155
	ds_read_b128 v[220:223], v155 offset:256
	s_barrier
	s_waitcnt lgkmcnt(0)
	s_setprio 1
	s_waitcnt lgkmcnt(0)
	v_mfma_f32_16x16x32_bf16 v[84:87], v[104:107], v[184:187], v[84:87]
	v_mfma_f32_16x16x32_bf16 v[76:79], v[104:107], v[192:195], v[76:79]
	v_mfma_f32_16x16x32_bf16 v[72:75], v[112:115], v[192:195], v[72:75]
	v_mfma_f32_16x16x32_bf16 v[92:95], v[104:107], v[176:179], v[92:95]
	v_mfma_f32_16x16x32_bf16 v[88:91], v[112:115], v[176:179], v[88:91]
	v_mfma_f32_16x16x32_bf16 v[84:87], v[120:123], v[188:191], v[84:87]
	v_mfma_f32_16x16x32_bf16 v[80:83], v[112:115], v[184:187], v[80:83]
	v_mfma_f32_16x16x32_bf16 v[76:79], v[120:123], v[196:199], v[76:79]
	v_mfma_f32_16x16x32_bf16 v[72:75], v[220:223], v[196:199], v[72:75]
	v_mfma_f32_16x16x32_bf16 v[68:71], v[104:107], v[200:203], v[68:71]
	v_mfma_f32_16x16x32_bf16 v[64:67], v[112:115], v[200:203], v[64:67]
	v_mfma_f32_16x16x32_bf16 v[224:227], v[120:123], v[180:183], v[92:95]
	v_mfma_f32_16x16x32_bf16 v[176:179], v[220:223], v[180:183], v[88:91]
	v_mfma_f32_16x16x32_bf16 v[180:183], v[220:223], v[188:191], v[80:83]
	v_mfma_f32_16x16x32_bf16 v[184:187], v[120:123], v[204:207], v[68:71]
	v_mfma_f32_16x16x32_bf16 v[188:191], v[220:223], v[204:207], v[64:67]
	s_setprio 0
	s_barrier
	s_nop 0
	ds_read_b128 v[64:67], v149 offset:16384
	ds_read_b128 v[68:71], v149 offset:17408
	ds_read_b128 v[80:83], v149 offset:18432
	ds_read_b128 v[88:91], v149 offset:19456
	ds_read_b128 v[92:95], v149 offset:20480
	ds_read_b128 v[192:195], v149 offset:21504
	ds_read_b128 v[196:199], v149 offset:22528
	ds_read_b128 v[200:203], v149 offset:23552
	s_waitcnt vmcnt(4)
	s_barrier
	s_waitcnt lgkmcnt(0)
	s_setprio 1
	s_waitcnt lgkmcnt(0)
	v_mfma_f32_16x16x32_bf16 v[52:55], v[160:163], v[80:83], v[52:55]
	v_mfma_f32_16x16x32_bf16 v[44:47], v[160:163], v[92:95], v[44:47]
	v_mfma_f32_16x16x32_bf16 v[36:39], v[160:163], v[196:199], v[36:39]
	v_mfma_f32_16x16x32_bf16 v[60:63], v[160:163], v[64:67], v[60:63]
	v_mfma_f32_16x16x32_bf16 v[56:59], v[164:167], v[64:67], v[56:59]
	v_mfma_f32_16x16x32_bf16 v[52:55], v[168:171], v[88:91], v[52:55]
	v_mfma_f32_16x16x32_bf16 v[48:51], v[164:167], v[80:83], v[48:51]
	v_mfma_f32_16x16x32_bf16 v[44:47], v[168:171], v[192:195], v[44:47]
	v_mfma_f32_16x16x32_bf16 v[40:43], v[164:167], v[92:95], v[40:43]
	v_mfma_f32_16x16x32_bf16 v[36:39], v[168:171], v[200:203], v[36:39]
	v_mfma_f32_16x16x32_bf16 v[32:35], v[164:167], v[196:199], v[32:35]
	v_mfma_f32_16x16x32_bf16 v[204:207], v[168:171], v[68:71], v[60:63]
	v_mfma_f32_16x16x32_bf16 v[228:231], v[172:175], v[68:71], v[56:59]
	v_mfma_f32_16x16x32_bf16 v[232:235], v[172:175], v[88:91], v[48:51]
	v_mfma_f32_16x16x32_bf16 v[236:239], v[172:175], v[192:195], v[40:43]
	v_mfma_f32_16x16x32_bf16 v[160:163], v[172:175], v[200:203], v[32:35]
	s_setprio 0
	s_setprio 1
	v_mfma_f32_16x16x32_bf16 v[28:31], v[104:107], v[64:67], v[28:31]
	v_mfma_f32_16x16x32_bf16 v[20:23], v[104:107], v[80:83], v[20:23]
	v_mfma_f32_16x16x32_bf16 v[12:15], v[104:107], v[92:95], v[12:15]
	v_mfma_f32_16x16x32_bf16 v[4:7], v[104:107], v[196:199], v[4:7]
	v_mfma_f32_16x16x32_bf16 v[28:31], v[120:123], v[68:71], v[28:31]
	v_mfma_f32_16x16x32_bf16 v[24:27], v[112:115], v[64:67], v[24:27]
	v_mfma_f32_16x16x32_bf16 v[20:23], v[120:123], v[88:91], v[20:23]
	v_mfma_f32_16x16x32_bf16 v[16:19], v[112:115], v[80:83], v[16:19]
	v_mfma_f32_16x16x32_bf16 v[12:15], v[120:123], v[192:195], v[12:15]
	v_mfma_f32_16x16x32_bf16 v[8:11], v[112:115], v[92:95], v[8:11]
	v_mfma_f32_16x16x32_bf16 v[4:7], v[120:123], v[200:203], v[4:7]
	v_mfma_f32_16x16x32_bf16 v[0:3], v[112:115], v[196:199], v[0:3]
	v_mfma_f32_16x16x32_bf16 v[164:167], v[220:223], v[68:71], v[24:27]
	v_mfma_f32_16x16x32_bf16 v[168:171], v[220:223], v[88:91], v[16:19]
	v_mfma_f32_16x16x32_bf16 v[172:175], v[220:223], v[192:195], v[8:11]
	v_mfma_f32_16x16x32_bf16 v[192:195], v[220:223], v[200:203], v[0:3]
	s_setprio 0
	s_barrier
	s_nop 1
	ds_read_b128 v[0:3], v156
	ds_read_b128 v[8:11], v156 offset:256
	ds_read_b128 v[16:19], v157
	ds_read_b128 v[24:27], v157 offset:256
	ds_read_b128 v[32:35], v149 offset:32768
	ds_read_b128 v[40:43], v149 offset:33792
	ds_read_b128 v[48:51], v149 offset:34816
	ds_read_b128 v[56:59], v149 offset:35840
	ds_read_b128 v[60:63], v149 offset:36864
	ds_read_b128 v[68:71], v149 offset:37888
	ds_read_b128 v[196:199], v149 offset:38912
	ds_read_b128 v[200:203], v149 offset:39936
	s_waitcnt vmcnt(2)
	s_barrier
; #define LDA(dst, b, h) for (int m = 0; m < 4; ++m) { \
;     dst[m][0] = *reinterpret_cast<const bf16x8*>((char*)SA(b, h) + aoff0 + m * 2048); \
;     dst[m][1] = *reinterpret_cast<const bf16x8*>((char*)SA(b, h) + aoff1 + m * 2048); }
; #define LDB(dst, b, h) for (int n = 0; n < 2; ++n) { \
;     dst[n][0] = *reinterpret_cast<const bf16x8*>((char*)SB(b, h) + boff0 + n * 256); \
;     dst[n][1] = *reinterpret_cast<const bf16x8*>((char*)SB(b, h) + boff1 + n * 256); }
; #define MMA(ai, bj, At, Btf) do { __builtin_amdgcn_s_setprio(1); \
;     for (int m = 0; m < 4; ++m) for (int n = 0; n < 2; ++n) for (int k = 0; k < 2; ++k) \
;       acc[ai][bj][m][n] = __builtin_amdgcn_mfma_f32_16x16x32_bf16(Btf[n][k], At[m][k], acc[ai][bj][m][n], 0, 0, 0); \
;     __builtin_amdgcn_s_setprio(0); } while (0)
; #define WAIT_V(n) asm volatile("s_waitcnt vmcnt(" #n ")" ::: "memory")
; #define WAIT_L(n) asm volatile("s_waitcnt lgkmcnt(" #n ")" ::: "memory")
; #define BAR __builtin_amdgcn_s_barrier()
; template <int EPI> ...
;     ...
;   { LDB(B0, 1, 0); LDA(At, 1, 0); WAIT_V(2); BAR; WAIT_L(0); MMA(0, 0, At, B0); BAR;
;     LDB(B1, 1, 1); WAIT_V(0); BAR; WAIT_L(0); MMA(0, 1, At, B1); BAR;
;     LDA(At, 1, 1); BAR; WAIT_L(0); MMA(1, 0, At, B0); MMA(1, 1, At, B1); BAR; }
;   if (wr == 0) BAR;
	s_waitcnt lgkmcnt(0)
	s_setprio 1
	s_waitcnt lgkmcnt(0)
	v_mfma_f32_16x16x32_bf16 v[64:67], v[0:3], v[32:35], v[124:127]
	v_mfma_f32_16x16x32_bf16 v[120:123], v[16:19], v[40:43], v[64:67]
	v_mfma_f32_16x16x32_bf16 v[64:67], v[8:11], v[32:35], v[208:211]
	v_mfma_f32_16x16x32_bf16 v[124:127], v[24:27], v[40:43], v[64:67]
	v_mfma_f32_16x16x32_bf16 v[64:67], v[0:3], v[48:51], v[116:119]
	v_mfma_f32_16x16x32_bf16 v[112:115], v[16:19], v[56:59], v[64:67]
	v_mfma_f32_16x16x32_bf16 v[64:67], v[8:11], v[48:51], v[212:215]
	v_mfma_f32_16x16x32_bf16 v[116:119], v[24:27], v[56:59], v[64:67]
	v_mfma_f32_16x16x32_bf16 v[64:67], v[0:3], v[60:63], v[108:111]
	v_mfma_f32_16x16x32_bf16 v[104:107], v[16:19], v[68:71], v[64:67]
	v_mfma_f32_16x16x32_bf16 v[64:67], v[8:11], v[60:63], v[216:219]
	v_mfma_f32_16x16x32_bf16 v[108:111], v[24:27], v[68:71], v[64:67]
	v_mfma_f32_16x16x32_bf16 v[64:67], v[0:3], v[196:199], v[100:103]
	v_mfma_f32_16x16x32_bf16 v[88:91], v[16:19], v[200:203], v[64:67]
	v_mfma_f32_16x16x32_bf16 v[64:67], v[8:11], v[196:199], v[96:99]
	v_mfma_f32_16x16x32_bf16 v[92:95], v[24:27], v[200:203], v[64:67]
	s_setprio 0
	s_barrier
	ds_read_b128 v[208:211], v158
	ds_read_b128 v[212:215], v158 offset:256
	ds_read_b128 v[216:219], v159
	ds_read_b128 v[220:223], v159 offset:256
	s_waitcnt vmcnt(0)
	s_barrier
	s_waitcnt lgkmcnt(0)
	s_setprio 1
	s_waitcnt lgkmcnt(0)
	v_mfma_f32_16x16x32_bf16 v[64:67], v[208:211], v[32:35], v[224:227]
	v_mfma_f32_16x16x32_bf16 v[32:35], v[212:215], v[32:35], v[176:179]
	v_mfma_f32_16x16x32_bf16 v[100:103], v[220:223], v[40:43], v[32:35]
	v_mfma_f32_16x16x32_bf16 v[32:35], v[208:211], v[48:51], v[84:87]
	v_mfma_f32_16x16x32_bf16 v[80:83], v[216:219], v[56:59], v[32:35]
	v_mfma_f32_16x16x32_bf16 v[32:35], v[212:215], v[48:51], v[180:183]
	v_mfma_f32_16x16x32_bf16 v[84:87], v[220:223], v[56:59], v[32:35]
	v_mfma_f32_16x16x32_bf16 v[32:35], v[208:211], v[60:63], v[76:79]
	v_mfma_f32_16x16x32_bf16 v[96:99], v[216:219], v[40:43], v[64:67]
	v_mfma_f32_16x16x32_bf16 v[64:67], v[216:219], v[68:71], v[32:35]
	v_mfma_f32_16x16x32_bf16 v[32:35], v[212:215], v[60:63], v[72:75]
	v_mfma_f32_16x16x32_bf16 v[68:71], v[220:223], v[68:71], v[32:35]
	v_mfma_f32_16x16x32_bf16 v[32:35], v[208:211], v[196:199], v[184:187]
	v_mfma_f32_16x16x32_bf16 v[56:59], v[216:219], v[200:203], v[32:35]
	v_mfma_f32_16x16x32_bf16 v[32:35], v[212:215], v[196:199], v[188:191]
	v_mfma_f32_16x16x32_bf16 v[60:63], v[220:223], v[200:203], v[32:35]
	s_setprio 0
	s_barrier
	ds_read_b128 v[176:179], v149 offset:49152
	ds_read_b128 v[180:183], v149 offset:50176
	ds_read_b128 v[184:187], v149 offset:51200
	ds_read_b128 v[188:191], v149 offset:52224
	ds_read_b128 v[196:199], v149 offset:53248
	ds_read_b128 v[200:203], v149 offset:54272
	ds_read_b128 v[224:227], v149 offset:55296
	ds_read_b128 v[240:243], v149 offset:56320
	s_barrier
	s_waitcnt lgkmcnt(0)
	s_setprio 1
	s_waitcnt lgkmcnt(0)
	v_mfma_f32_16x16x32_bf16 v[32:35], v[0:3], v[176:179], v[204:207]
	v_mfma_f32_16x16x32_bf16 v[72:75], v[16:19], v[180:183], v[32:35]
	v_mfma_f32_16x16x32_bf16 v[32:35], v[8:11], v[176:179], v[228:231]
	v_mfma_f32_16x16x32_bf16 v[76:79], v[24:27], v[180:183], v[32:35]
	v_mfma_f32_16x16x32_bf16 v[32:35], v[0:3], v[184:187], v[52:55]
	v_mfma_f32_16x16x32_bf16 v[48:51], v[16:19], v[188:191], v[32:35]
	v_mfma_f32_16x16x32_bf16 v[32:35], v[8:11], v[184:187], v[232:235]
	v_mfma_f32_16x16x32_bf16 v[52:55], v[24:27], v[188:191], v[32:35]
	v_mfma_f32_16x16x32_bf16 v[32:35], v[0:3], v[196:199], v[44:47]
	v_mfma_f32_16x16x32_bf16 v[40:43], v[16:19], v[200:203], v[32:35]
	v_mfma_f32_16x16x32_bf16 v[32:35], v[8:11], v[196:199], v[236:239]
	v_mfma_f32_16x16x32_bf16 v[0:3], v[0:3], v[224:227], v[36:39]
	v_mfma_f32_16x16x32_bf16 v[44:47], v[24:27], v[200:203], v[32:35]
	v_mfma_f32_16x16x32_bf16 v[32:35], v[16:19], v[240:243], v[0:3]
	v_mfma_f32_16x16x32_bf16 v[0:3], v[8:11], v[224:227], v[160:163]
	v_mfma_f32_16x16x32_bf16 v[36:39], v[24:27], v[240:243], v[0:3]
	s_setprio 0
	s_setprio 1
	v_mfma_f32_16x16x32_bf16 v[0:3], v[208:211], v[176:179], v[28:31]
	v_mfma_f32_16x16x32_bf16 v[24:27], v[216:219], v[180:183], v[0:3]
	v_mfma_f32_16x16x32_bf16 v[0:3], v[212:215], v[176:179], v[164:167]
	v_mfma_f32_16x16x32_bf16 v[28:31], v[220:223], v[180:183], v[0:3]
	v_mfma_f32_16x16x32_bf16 v[0:3], v[208:211], v[184:187], v[20:23]
	v_mfma_f32_16x16x32_bf16 v[16:19], v[216:219], v[188:191], v[0:3]
	v_mfma_f32_16x16x32_bf16 v[0:3], v[212:215], v[184:187], v[168:171]
	v_mfma_f32_16x16x32_bf16 v[20:23], v[220:223], v[188:191], v[0:3]
	v_mfma_f32_16x16x32_bf16 v[0:3], v[208:211], v[196:199], v[12:15]
	v_mfma_f32_16x16x32_bf16 v[8:11], v[216:219], v[200:203], v[0:3]
	v_mfma_f32_16x16x32_bf16 v[0:3], v[212:215], v[196:199], v[172:175]
	v_mfma_f32_16x16x32_bf16 v[12:15], v[220:223], v[200:203], v[0:3]
	v_mfma_f32_16x16x32_bf16 v[0:3], v[208:211], v[224:227], v[4:7]
	v_mfma_f32_16x16x32_bf16 v[4:7], v[212:215], v[224:227], v[192:195]
	v_mfma_f32_16x16x32_bf16 v[0:3], v[216:219], v[240:243], v[0:3]
	v_mfma_f32_16x16x32_bf16 v[4:7], v[220:223], v[240:243], v[4:7]
	s_setprio 0
	s_barrier
	s_and_saveexec_b64 s[62:63], s[2:3]
	s_cbranch_execz .LBB0_1012
	s_barrier
	s_branch .LBB0_1012

; #define STAGE(P, BASE, br, kt) do { const char* _gb = (const char*)(BASE) + ((size_t)(br) * K + (size_t)(kt) * BK) * 2; \
;     __builtin_amdgcn_global_load_lds((const unsigned*)(_gb + loff0), (unsigned*)((char*)(P) + tid * 16), 16, 0, 0); \
;     __builtin_amdgcn_global_load_lds((const unsigned*)(_gb + (size_t)K * 128 + loff0), (unsigned*)((char*)(P) + tid * 16 + 8192), 16, 0, 0); } while (0)
; #define LDA(dst, b, h) for (int m = 0; m < 4; ++m) { \
;     dst[m][0] = *reinterpret_cast<const bf16x8*>((char*)SA(b, h) + aoff0 + m * 2048); \
;     dst[m][1] = *reinterpret_cast<const bf16x8*>((char*)SA(b, h) + aoff1 + m * 2048); }
; #define LDB(dst, b, h) for (int n = 0; n < 2; ++n) { \
;     dst[n][0] = *reinterpret_cast<const bf16x8*>((char*)SB(b, h) + boff0 + n * 256); \
;     dst[n][1] = *reinterpret_cast<const bf16x8*>((char*)SB(b, h) + boff1 + n * 256); }
; #define MMA(ai, bj, At, Btf) do { __builtin_amdgcn_s_setprio(1); \
;     for (int m = 0; m < 4; ++m) for (int n = 0; n < 2; ++n) for (int k = 0; k < 2; ++k) \
;       acc[ai][bj][m][n] = __builtin_amdgcn_mfma_f32_16x16x32_bf16(Btf[n][k], At[m][k], acc[ai][bj][m][n], 0, 0, 0); \
;     __builtin_amdgcn_s_setprio(0); } while (0)
; #define WAIT_V(n) asm volatile("s_waitcnt vmcnt(" #n ")" ::: "memory")
; #define WAIT_L(n) asm volatile("s_waitcnt lgkmcnt(" #n ")" ::: "memory")
; #define BAR __builtin_amdgcn_s_barrier()
; #define SCHED __builtin_amdgcn_sched_barrier(0)
; template <int EPI> ...
;     ...
;   WAIT_V(4); BAR;
;   STAGE(SB(1, 0), Bt, bcol, 1); STAGE(SA(1, 0), A, brow, 1); STAGE(SB(1, 1), Bt, bcol + HALF, 1);
;   WAIT_V(6); BAR;
;   for (int t = 0; t < nt - 2; t += 2) {
;     LDB(B0, 0, 0); SCHED; LDA(At, 0, 0); STAGE(SA(1, 1), A, brow + HALF, t + 1);
;     WAIT_L(8); BAR; WAIT_L(0); MMA(0, 0, At, B0); BAR; SCHED;
;     LDB(B1, 0, 1); STAGE(SB(0, 0), Bt, bcol, t + 2);
;     BAR; WAIT_L(0); MMA(0, 1, At, B1); BAR;
;     LDA(At, 0, 1); STAGE(SA(0, 0), A, brow, t + 2);
;     BAR; WAIT_L(0); MMA(1, 0, At, B0); BAR; SCHED;
;     STAGE(SB(0, 1), Bt, bcol + HALF, t + 2);
;     WAIT_V(6); BAR; MMA(1, 1, At, B1); BAR;
.LBB0_1104:
	s_or_b64 exec, exec, s[70:71]
	v_readfirstlane_b32 s65, v144
	v_lshl_add_u64 v[6:7], v[0:1], 0, s[12:13]
	s_mov_b32 m0, s65
	v_readfirstlane_b32 s65, v145
	s_waitcnt vmcnt(2)
	s_barrier
	global_load_lds_dwordx4 v[6:7], off
	v_lshl_add_u64 v[0:1], v[0:1], 0, s[16:17]
	s_mov_b32 m0, s65
	v_readfirstlane_b32 s65, v146
	global_load_lds_dwordx4 v[0:1], off
	v_lshl_add_u64 v[0:1], v[2:3], 0, s[12:13]
	s_mov_b32 m0, s65
	v_readfirstlane_b32 s65, v147
	global_load_lds_dwordx4 v[0:1], off
	v_lshl_add_u64 v[0:1], v[2:3], 0, s[16:17]
	s_mov_b32 m0, s65
	v_readfirstlane_b32 s65, v148
	global_load_lds_dwordx4 v[0:1], off
	v_lshl_add_u64 v[0:1], v[4:5], 0, s[12:13]
	s_mov_b32 m0, s65
	v_readfirstlane_b32 s65, v149
	global_load_lds_dwordx4 v[0:1], off
	v_lshl_add_u64 v[0:1], v[4:5], 0, s[16:17]
	s_mov_b32 m0, s65
	s_add_u32 s66, s6, s66
	global_load_lds_dwordx4 v[0:1], off
	s_addc_u32 s67, s7, s67
	s_add_u32 s68, s6, s68
	v_mov_b32_e32 v0, 0
	s_addc_u32 s69, s7, s69
	s_mov_b32 s65, -2
	v_mov_b32_e32 v1, v0
	v_mov_b32_e32 v2, v0
	v_mov_b32_e32 v3, v0
	v_mov_b32_e32 v4, v0
	v_mov_b32_e32 v5, v0
	v_mov_b32_e32 v6, v0
	v_mov_b32_e32 v7, v0
	s_waitcnt vmcnt(6)
	s_barrier
.LBB0_1105:
	ds_read_b128 v[162:165], v153
	ds_read_b128 v[166:169], v153 offset:256
	ds_read_b128 v[170:173], v154
	ds_read_b128 v[174:177], v154 offset:256
	v_lshl_add_u64 v[226:227], s[66:67], 0, v[130:131]
	v_readfirstlane_b32 s70, v151
	v_lshl_add_u64 v[210:211], v[226:227], 0, s[18:19]
	s_mov_b32 m0, s70
	v_readfirstlane_b32 s70, v152
	ds_read_b128 v[178:181], v150
	ds_read_b128 v[182:185], v150 offset:1024
	ds_read_b128 v[186:189], v150 offset:2048
	ds_read_b128 v[190:193], v150 offset:3072
	ds_read_b128 v[194:197], v150 offset:4096
	ds_read_b128 v[198:201], v150 offset:5120
	ds_read_b128 v[202:205], v150 offset:6144
	ds_read_b128 v[206:209], v150 offset:7168
	global_load_lds_dwordx4 v[210:211], off
	v_lshl_add_u64 v[210:211], v[226:227], 0, s[20:21]
	s_mov_b32 m0, s70
	s_nop 0
	global_load_lds_dwordx4 v[210:211], off
	s_waitcnt lgkmcnt(8)
	ds_read_b128 v[210:213], v155
	ds_read_b128 v[214:217], v155 offset:256
	ds_read_b128 v[218:221], v156
	ds_read_b128 v[222:225], v156 offset:256
	s_barrier
	s_waitcnt lgkmcnt(0)
	s_setprio 1
	s_waitcnt lgkmcnt(0)
	v_mfma_f32_16x16x32_bf16 v[124:127], v[162:165], v[178:181], v[124:127]
	v_mfma_f32_16x16x32_bf16 v[120:123], v[166:169], v[178:181], v[120:123]
	v_mfma_f32_16x16x32_bf16 v[116:119], v[162:165], v[186:189], v[116:119]
	v_mfma_f32_16x16x32_bf16 v[112:115], v[166:169], v[186:189], v[112:115]
	v_mfma_f32_16x16x32_bf16 v[108:111], v[162:165], v[194:197], v[108:111]
	v_mfma_f32_16x16x32_bf16 v[104:107], v[166:169], v[194:197], v[104:107]
	v_mfma_f32_16x16x32_bf16 v[100:103], v[162:165], v[202:205], v[100:103]
	v_mfma_f32_16x16x32_bf16 v[96:99], v[166:169], v[202:205], v[96:99]
	v_mfma_f32_16x16x32_bf16 v[124:127], v[170:173], v[182:185], v[124:127]
	v_mfma_f32_16x16x32_bf16 v[120:123], v[174:177], v[182:185], v[120:123]
	v_mfma_f32_16x16x32_bf16 v[116:119], v[170:173], v[190:193], v[116:119]
	v_mfma_f32_16x16x32_bf16 v[112:115], v[174:177], v[190:193], v[112:115]
	v_mfma_f32_16x16x32_bf16 v[108:111], v[170:173], v[198:201], v[108:111]
	v_mfma_f32_16x16x32_bf16 v[104:107], v[174:177], v[198:201], v[104:107]
	v_mfma_f32_16x16x32_bf16 v[100:103], v[170:173], v[206:209], v[100:103]
	v_mfma_f32_16x16x32_bf16 v[96:99], v[174:177], v[206:209], v[96:99]
	s_setprio 0
	s_waitcnt lgkmcnt(0)
	s_setprio 1
	s_waitcnt lgkmcnt(0)
	v_mfma_f32_16x16x32_bf16 v[92:95], v[210:213], v[178:181], v[92:95]
	v_mfma_f32_16x16x32_bf16 v[88:91], v[214:217], v[178:181], v[88:91]
	v_mfma_f32_16x16x32_bf16 v[84:87], v[210:213], v[186:189], v[84:87]
	v_mfma_f32_16x16x32_bf16 v[80:83], v[214:217], v[186:189], v[80:83]
	v_mfma_f32_16x16x32_bf16 v[76:79], v[210:213], v[194:197], v[76:79]
	v_mfma_f32_16x16x32_bf16 v[72:75], v[214:217], v[194:197], v[72:75]
	v_mfma_f32_16x16x32_bf16 v[68:71], v[210:213], v[202:205], v[68:71]
	v_mfma_f32_16x16x32_bf16 v[64:67], v[214:217], v[202:205], v[64:67]
	v_mfma_f32_16x16x32_bf16 v[92:95], v[218:221], v[182:185], v[92:95]
	v_mfma_f32_16x16x32_bf16 v[88:91], v[222:225], v[182:185], v[88:91]
	v_mfma_f32_16x16x32_bf16 v[84:87], v[218:221], v[190:193], v[84:87]
	v_mfma_f32_16x16x32_bf16 v[80:83], v[222:225], v[190:193], v[80:83]
	v_mfma_f32_16x16x32_bf16 v[76:79], v[218:221], v[198:201], v[76:79]
	v_mfma_f32_16x16x32_bf16 v[72:75], v[222:225], v[198:201], v[72:75]
	v_mfma_f32_16x16x32_bf16 v[68:71], v[218:221], v[206:209], v[68:71]
	v_mfma_f32_16x16x32_bf16 v[64:67], v[222:225], v[206:209], v[64:67]
	s_setprio 0
	s_barrier
	v_lshl_add_u64 v[228:229], s[68:69], 0, v[130:131]
	v_readfirstlane_b32 s70, v136
	v_lshl_add_u64 v[230:231], v[228:229], 0, s[22:23]
	s_mov_b32 m0, s70
	v_readfirstlane_b32 s70, v137
	global_load_lds_dwordx4 v[230:231], off
	v_lshl_add_u64 v[230:231], v[228:229], 0, s[24:25]
	s_mov_b32 m0, s70
	s_nop 0
	global_load_lds_dwordx4 v[230:231], off
	v_readfirstlane_b32 s70, v138
	v_lshl_add_u64 v[230:231], v[226:227], 0, s[26:27]
	s_mov_b32 m0, s70
	v_readfirstlane_b32 s70, v139
	ds_read_b128 v[178:181], v150 offset:16384
	ds_read_b128 v[182:185], v150 offset:17408
	ds_read_b128 v[186:189], v150 offset:18432
	ds_read_b128 v[190:193], v150 offset:19456
	ds_read_b128 v[194:197], v150 offset:20480
	ds_read_b128 v[198:201], v150 offset:21504
	ds_read_b128 v[202:205], v150 offset:22528
	ds_read_b128 v[206:209], v150 offset:23552
	global_load_lds_dwordx4 v[230:231], off
	v_lshl_add_u64 v[230:231], v[226:227], 0, s[28:29]
	s_mov_b32 m0, s70
	s_nop 0
	global_load_lds_dwordx4 v[230:231], off
	v_readfirstlane_b32 s70, v140
	v_lshl_add_u64 v[246:247], v[228:229], 0, s[30:31]
	s_mov_b32 m0, s70
	v_readfirstlane_b32 s70, v141
	global_load_lds_dwordx4 v[246:247], off
	v_lshl_add_u64 v[246:247], v[228:229], 0, s[36:37]
	s_mov_b32 m0, s70
	s_nop 0
	global_load_lds_dwordx4 v[246:247], off
	s_waitcnt vmcnt(6)
	s_barrier
; #define STAGE(P, BASE, br, kt) do { const char* _gb = (const char*)(BASE) + ((size_t)(br) * K + (size_t)(kt) * BK) * 2; \
;     __builtin_amdgcn_global_load_lds((const unsigned*)(_gb + loff0), (unsigned*)((char*)(P) + tid * 16), 16, 0, 0); \
;     __builtin_amdgcn_global_load_lds((const unsigned*)(_gb + (size_t)K * 128 + loff0), (unsigned*)((char*)(P) + tid * 16 + 8192), 16, 0, 0); } while (0)
; #define LDA(dst, b, h) for (int m = 0; m < 4; ++m) { \
;     dst[m][0] = *reinterpret_cast<const bf16x8*>((char*)SA(b, h) + aoff0 + m * 2048); \
;     dst[m][1] = *reinterpret_cast<const bf16x8*>((char*)SA(b, h) + aoff1 + m * 2048); }
; #define LDB(dst, b, h) for (int n = 0; n < 2; ++n) { \
;     dst[n][0] = *reinterpret_cast<const bf16x8*>((char*)SB(b, h) + boff0 + n * 256); \
;     dst[n][1] = *reinterpret_cast<const bf16x8*>((char*)SB(b, h) + boff1 + n * 256); }
; #define MMA(ai, bj, At, Btf) do { __builtin_amdgcn_s_setprio(1); \
;     for (int m = 0; m < 4; ++m) for (int n = 0; n < 2; ++n) for (int k = 0; k < 2; ++k) \
;       acc[ai][bj][m][n] = __builtin_amdgcn_mfma_f32_16x16x32_bf16(Btf[n][k], At[m][k], acc[ai][bj][m][n], 0, 0, 0); \
;     __builtin_amdgcn_s_setprio(0); } while (0)
; #define WAIT_V(n) asm volatile("s_waitcnt vmcnt(" #n ")" ::: "memory")
; #define WAIT_L(n) asm volatile("s_waitcnt lgkmcnt(" #n ")" ::: "memory")
; #define BAR __builtin_amdgcn_s_barrier()
; #define SCHED __builtin_amdgcn_sched_barrier(0)
; template <int EPI> ...
;     ...
;     BAR; WAIT_L(0); MMA(1, 0, At, B0); BAR; SCHED;
;     STAGE(SB(0, 1), Bt, bcol + HALF, t + 2);
;     WAIT_V(6); BAR; MMA(1, 1, At, B1); BAR;
;     LDB(B0, 1, 0); SCHED; LDA(At, 1, 0); STAGE(SA(0, 1), A, brow + HALF, t + 2);
;     WAIT_L(8); BAR; WAIT_L(0); MMA(0, 0, At, B0); BAR; SCHED;
;     LDB(B1, 1, 1); STAGE(SB(1, 0), Bt, bcol, t + 3);
;     BAR; WAIT_L(0); MMA(0, 1, At, B1); BAR;
	s_waitcnt lgkmcnt(0)
	s_setprio 1
	s_waitcnt lgkmcnt(0)
	v_mfma_f32_16x16x32_bf16 v[60:63], v[162:165], v[178:181], v[60:63]
	v_mfma_f32_16x16x32_bf16 v[56:59], v[166:169], v[178:181], v[56:59]
	v_mfma_f32_16x16x32_bf16 v[52:55], v[162:165], v[186:189], v[52:55]
	v_mfma_f32_16x16x32_bf16 v[48:51], v[166:169], v[186:189], v[48:51]
	v_mfma_f32_16x16x32_bf16 v[44:47], v[162:165], v[194:197], v[44:47]
	v_mfma_f32_16x16x32_bf16 v[40:43], v[166:169], v[194:197], v[40:43]
	v_mfma_f32_16x16x32_bf16 v[36:39], v[162:165], v[202:205], v[36:39]
	v_mfma_f32_16x16x32_bf16 v[32:35], v[166:169], v[202:205], v[32:35]
	v_mfma_f32_16x16x32_bf16 v[60:63], v[170:173], v[182:185], v[60:63]
	v_mfma_f32_16x16x32_bf16 v[56:59], v[174:177], v[182:185], v[56:59]
	v_mfma_f32_16x16x32_bf16 v[52:55], v[170:173], v[190:193], v[52:55]
	v_mfma_f32_16x16x32_bf16 v[48:51], v[174:177], v[190:193], v[48:51]
	v_mfma_f32_16x16x32_bf16 v[44:47], v[170:173], v[198:201], v[44:47]
	v_mfma_f32_16x16x32_bf16 v[40:43], v[174:177], v[198:201], v[40:43]
	v_mfma_f32_16x16x32_bf16 v[36:39], v[170:173], v[206:209], v[36:39]
	v_mfma_f32_16x16x32_bf16 v[32:35], v[174:177], v[206:209], v[32:35]
	s_setprio 0
	s_setprio 1
	v_mfma_f32_16x16x32_bf16 v[28:31], v[210:213], v[178:181], v[28:31]
	v_mfma_f32_16x16x32_bf16 v[24:27], v[214:217], v[178:181], v[24:27]
	v_mfma_f32_16x16x32_bf16 v[20:23], v[210:213], v[186:189], v[20:23]
	v_mfma_f32_16x16x32_bf16 v[16:19], v[214:217], v[186:189], v[16:19]
	v_mfma_f32_16x16x32_bf16 v[12:15], v[210:213], v[194:197], v[12:15]
	v_mfma_f32_16x16x32_bf16 v[8:11], v[214:217], v[194:197], v[8:11]
	v_mfma_f32_16x16x32_bf16 v[4:7], v[210:213], v[202:205], v[4:7]
	v_mfma_f32_16x16x32_bf16 v[0:3], v[214:217], v[202:205], v[0:3]
	v_mfma_f32_16x16x32_bf16 v[28:31], v[218:221], v[182:185], v[28:31]
	v_mfma_f32_16x16x32_bf16 v[24:27], v[222:225], v[182:185], v[24:27]
	v_mfma_f32_16x16x32_bf16 v[20:23], v[218:221], v[190:193], v[20:23]
	v_mfma_f32_16x16x32_bf16 v[16:19], v[222:225], v[190:193], v[16:19]
	v_mfma_f32_16x16x32_bf16 v[12:15], v[218:221], v[198:201], v[12:15]
	v_mfma_f32_16x16x32_bf16 v[8:11], v[222:225], v[198:201], v[8:11]
	v_mfma_f32_16x16x32_bf16 v[4:7], v[218:221], v[206:209], v[4:7]
	v_mfma_f32_16x16x32_bf16 v[0:3], v[222:225], v[206:209], v[0:3]
	s_setprio 0
	s_barrier
	ds_read_b128 v[162:165], v157
	ds_read_b128 v[166:169], v157 offset:256
	ds_read_b128 v[170:173], v158
	ds_read_b128 v[174:177], v158 offset:256
	v_readfirstlane_b32 s70, v142
	v_lshl_add_u64 v[210:211], v[226:227], 0, s[38:39]
	s_mov_b32 m0, s70
	v_readfirstlane_b32 s70, v143
	ds_read_b128 v[178:181], v150 offset:32768
	ds_read_b128 v[182:185], v150 offset:33792
	ds_read_b128 v[186:189], v150 offset:34816
	ds_read_b128 v[190:193], v150 offset:35840
	ds_read_b128 v[194:197], v150 offset:36864
	ds_read_b128 v[198:201], v150 offset:37888
	ds_read_b128 v[202:205], v150 offset:38912
	ds_read_b128 v[206:209], v150 offset:39936
	global_load_lds_dwordx4 v[210:211], off
	v_lshl_add_u64 v[210:211], v[226:227], 0, s[46:47]
	s_mov_b32 m0, s70
	s_nop 0
	global_load_lds_dwordx4 v[210:211], off
	s_waitcnt lgkmcnt(8)
	ds_read_b128 v[210:213], v159
	ds_read_b128 v[214:217], v159 offset:256
	ds_read_b128 v[218:221], v160
	ds_read_b128 v[222:225], v160 offset:256
	s_barrier
	s_waitcnt lgkmcnt(0)
	s_setprio 1
	s_waitcnt lgkmcnt(0)
	v_mfma_f32_16x16x32_bf16 v[124:127], v[162:165], v[178:181], v[124:127]
	v_mfma_f32_16x16x32_bf16 v[120:123], v[166:169], v[178:181], v[120:123]
	v_mfma_f32_16x16x32_bf16 v[116:119], v[162:165], v[186:189], v[116:119]
	v_mfma_f32_16x16x32_bf16 v[112:115], v[166:169], v[186:189], v[112:115]
	v_mfma_f32_16x16x32_bf16 v[108:111], v[162:165], v[194:197], v[108:111]
	v_mfma_f32_16x16x32_bf16 v[104:107], v[166:169], v[194:197], v[104:107]
	v_mfma_f32_16x16x32_bf16 v[100:103], v[162:165], v[202:205], v[100:103]
	v_mfma_f32_16x16x32_bf16 v[96:99], v[166:169], v[202:205], v[96:99]
	v_mfma_f32_16x16x32_bf16 v[124:127], v[170:173], v[182:185], v[124:127]
	v_mfma_f32_16x16x32_bf16 v[120:123], v[174:177], v[182:185], v[120:123]
	v_mfma_f32_16x16x32_bf16 v[116:119], v[170:173], v[190:193], v[116:119]
	v_mfma_f32_16x16x32_bf16 v[112:115], v[174:177], v[190:193], v[112:115]
	v_mfma_f32_16x16x32_bf16 v[108:111], v[170:173], v[198:201], v[108:111]
	v_mfma_f32_16x16x32_bf16 v[104:107], v[174:177], v[198:201], v[104:107]
	v_mfma_f32_16x16x32_bf16 v[100:103], v[170:173], v[206:209], v[100:103]
	v_mfma_f32_16x16x32_bf16 v[96:99], v[174:177], v[206:209], v[96:99]
	s_setprio 0
	s_waitcnt lgkmcnt(0)
	s_setprio 1
	s_waitcnt lgkmcnt(0)
	v_mfma_f32_16x16x32_bf16 v[92:95], v[210:213], v[178:181], v[92:95]
	v_mfma_f32_16x16x32_bf16 v[88:91], v[214:217], v[178:181], v[88:91]
	v_mfma_f32_16x16x32_bf16 v[84:87], v[210:213], v[186:189], v[84:87]
	v_mfma_f32_16x16x32_bf16 v[80:83], v[214:217], v[186:189], v[80:83]
	v_mfma_f32_16x16x32_bf16 v[76:79], v[210:213], v[194:197], v[76:79]
	v_mfma_f32_16x16x32_bf16 v[72:75], v[214:217], v[194:197], v[72:75]
	v_mfma_f32_16x16x32_bf16 v[68:71], v[210:213], v[202:205], v[68:71]
	v_mfma_f32_16x16x32_bf16 v[64:67], v[214:217], v[202:205], v[64:67]
	v_mfma_f32_16x16x32_bf16 v[92:95], v[218:221], v[182:185], v[92:95]
	v_mfma_f32_16x16x32_bf16 v[88:91], v[222:225], v[182:185], v[88:91]
	v_mfma_f32_16x16x32_bf16 v[84:87], v[218:221], v[190:193], v[84:87]
	v_mfma_f32_16x16x32_bf16 v[80:83], v[222:225], v[190:193], v[80:83]
	v_mfma_f32_16x16x32_bf16 v[76:79], v[218:221], v[198:201], v[76:79]
	v_mfma_f32_16x16x32_bf16 v[72:75], v[222:225], v[198:201], v[72:75]
	v_mfma_f32_16x16x32_bf16 v[68:71], v[218:221], v[206:209], v[68:71]
	v_mfma_f32_16x16x32_bf16 v[64:67], v[222:225], v[206:209], v[64:67]
	s_setprio 0
	s_barrier
; #define STAGE(P, BASE, br, kt) do { const char* _gb = (const char*)(BASE) + ((size_t)(br) * K + (size_t)(kt) * BK) * 2; \
;     __builtin_amdgcn_global_load_lds((const unsigned*)(_gb + loff0), (unsigned*)((char*)(P) + tid * 16), 16, 0, 0); \
;     __builtin_amdgcn_global_load_lds((const unsigned*)(_gb + (size_t)K * 128 + loff0), (unsigned*)((char*)(P) + tid * 16 + 8192), 16, 0, 0); } while (0)
; #define LDA(dst, b, h) for (int m = 0; m < 4; ++m) { \
;     dst[m][0] = *reinterpret_cast<const bf16x8*>((char*)SA(b, h) + aoff0 + m * 2048); \
;     dst[m][1] = *reinterpret_cast<const bf16x8*>((char*)SA(b, h) + aoff1 + m * 2048); }
; #define LDB(dst, b, h) for (int n = 0; n < 2; ++n) { \
;     dst[n][0] = *reinterpret_cast<const bf16x8*>((char*)SB(b, h) + boff0 + n * 256); \
;     dst[n][1] = *reinterpret_cast<const bf16x8*>((char*)SB(b, h) + boff1 + n * 256); }
; #define MMA(ai, bj, At, Btf) do { __builtin_amdgcn_s_setprio(1); \
;     for (int m = 0; m < 4; ++m) for (int n = 0; n < 2; ++n) for (int k = 0; k < 2; ++k) \
;       acc[ai][bj][m][n] = __builtin_amdgcn_mfma_f32_16x16x32_bf16(Btf[n][k], At[m][k], acc[ai][bj][m][n], 0, 0, 0); \
;     __builtin_amdgcn_s_setprio(0); } while (0)
; #define WAIT_V(n) asm volatile("s_waitcnt vmcnt(" #n ")" ::: "memory")
; #define WAIT_L(n) asm volatile("s_waitcnt lgkmcnt(" #n ")" ::: "memory")
; #define BAR __builtin_amdgcn_s_barrier()
; #define SCHED __builtin_amdgcn_sched_barrier(0)
; template <int EPI> ...
;     ...
;     LDB(B1, 1, 1); STAGE(SB(1, 0), Bt, bcol, t + 3);
;     BAR; WAIT_L(0); MMA(0, 1, At, B1); BAR;
;     LDA(At, 1, 1); STAGE(SA(1, 0), A, brow, t + 3);
;     BAR; WAIT_L(0); MMA(1, 0, At, B0); BAR; SCHED;
;     STAGE(SB(1, 1), Bt, bcol + HALF, t + 3);
;     WAIT_V(6); BAR; MMA(1, 1, At, B1); BAR;
;   }
;   { LDB(B0, 0, 0); LDA(At, 0, 0); STAGE(SA(1, 1), A, brow + HALF, nt - 1);
;     BAR; WAIT_L(0); MMA(0, 0, At, B0); BAR;
	v_readfirstlane_b32 s70, v144
	v_lshl_add_u64 v[230:231], v[228:229], 0, s[48:49]
	s_mov_b32 m0, s70
	v_readfirstlane_b32 s70, v145
	global_load_lds_dwordx4 v[230:231], off
	v_lshl_add_u64 v[230:231], v[228:229], 0, s[50:51]
	s_mov_b32 m0, s70
	s_nop 0
	global_load_lds_dwordx4 v[230:231], off
	v_readfirstlane_b32 s70, v146
	v_lshl_add_u64 v[230:231], v[226:227], 0, s[52:53]
	s_mov_b32 m0, s70
	v_readfirstlane_b32 s70, v147
	ds_read_b128 v[178:181], v150 offset:49152
	ds_read_b128 v[182:185], v150 offset:50176
	ds_read_b128 v[186:189], v150 offset:51200
	ds_read_b128 v[190:193], v150 offset:52224
	ds_read_b128 v[194:197], v150 offset:53248
	ds_read_b128 v[198:201], v150 offset:54272
	ds_read_b128 v[202:205], v150 offset:55296
	ds_read_b128 v[206:209], v150 offset:56320
	global_load_lds_dwordx4 v[230:231], off
	v_lshl_add_u64 v[226:227], v[226:227], 0, s[54:55]
	s_mov_b32 m0, s70
	s_nop 0
	global_load_lds_dwordx4 v[226:227], off
	v_readfirstlane_b32 s70, v148
	v_lshl_add_u64 v[246:247], v[228:229], 0, s[56:57]
	s_mov_b32 m0, s70
	v_readfirstlane_b32 s70, v149
	global_load_lds_dwordx4 v[246:247], off
	v_lshl_add_u64 v[246:247], v[228:229], 0, s[58:59]
	s_mov_b32 m0, s70
	s_nop 0
	global_load_lds_dwordx4 v[246:247], off
	s_waitcnt vmcnt(6)
	s_barrier
	s_waitcnt lgkmcnt(0)
	s_setprio 1
	s_waitcnt lgkmcnt(0)
	v_mfma_f32_16x16x32_bf16 v[60:63], v[162:165], v[178:181], v[60:63]
	v_mfma_f32_16x16x32_bf16 v[56:59], v[166:169], v[178:181], v[56:59]
	v_mfma_f32_16x16x32_bf16 v[52:55], v[162:165], v[186:189], v[52:55]
	v_mfma_f32_16x16x32_bf16 v[48:51], v[166:169], v[186:189], v[48:51]
	v_mfma_f32_16x16x32_bf16 v[44:47], v[162:165], v[194:197], v[44:47]
	v_mfma_f32_16x16x32_bf16 v[40:43], v[166:169], v[194:197], v[40:43]
	v_mfma_f32_16x16x32_bf16 v[36:39], v[162:165], v[202:205], v[36:39]
	v_mfma_f32_16x16x32_bf16 v[32:35], v[166:169], v[202:205], v[32:35]
	v_mfma_f32_16x16x32_bf16 v[60:63], v[170:173], v[182:185], v[60:63]
	v_mfma_f32_16x16x32_bf16 v[56:59], v[174:177], v[182:185], v[56:59]
	v_mfma_f32_16x16x32_bf16 v[52:55], v[170:173], v[190:193], v[52:55]
	v_mfma_f32_16x16x32_bf16 v[48:51], v[174:177], v[190:193], v[48:51]
	v_mfma_f32_16x16x32_bf16 v[44:47], v[170:173], v[198:201], v[44:47]
	v_mfma_f32_16x16x32_bf16 v[40:43], v[174:177], v[198:201], v[40:43]
	v_mfma_f32_16x16x32_bf16 v[36:39], v[170:173], v[206:209], v[36:39]
	v_mfma_f32_16x16x32_bf16 v[32:35], v[174:177], v[206:209], v[32:35]
	s_setprio 0
	s_setprio 1
	v_mfma_f32_16x16x32_bf16 v[28:31], v[210:213], v[178:181], v[28:31]
	v_mfma_f32_16x16x32_bf16 v[24:27], v[214:217], v[178:181], v[24:27]
	v_mfma_f32_16x16x32_bf16 v[20:23], v[210:213], v[186:189], v[20:23]
	v_mfma_f32_16x16x32_bf16 v[16:19], v[214:217], v[186:189], v[16:19]
	v_mfma_f32_16x16x32_bf16 v[12:15], v[210:213], v[194:197], v[12:15]
	v_mfma_f32_16x16x32_bf16 v[8:11], v[214:217], v[194:197], v[8:11]
	v_mfma_f32_16x16x32_bf16 v[4:7], v[210:213], v[202:205], v[4:7]
	v_mfma_f32_16x16x32_bf16 v[0:3], v[214:217], v[202:205], v[0:3]
	v_mfma_f32_16x16x32_bf16 v[28:31], v[218:221], v[182:185], v[28:31]
	v_mfma_f32_16x16x32_bf16 v[24:27], v[222:225], v[182:185], v[24:27]
	v_mfma_f32_16x16x32_bf16 v[20:23], v[218:221], v[190:193], v[20:23]
	v_mfma_f32_16x16x32_bf16 v[16:19], v[222:225], v[190:193], v[16:19]
	v_mfma_f32_16x16x32_bf16 v[12:15], v[218:221], v[198:201], v[12:15]
	v_mfma_f32_16x16x32_bf16 v[8:11], v[222:225], v[198:201], v[8:11]
	v_mfma_f32_16x16x32_bf16 v[4:7], v[218:221], v[206:209], v[4:7]
	v_mfma_f32_16x16x32_bf16 v[0:3], v[222:225], v[206:209], v[0:3]
	s_setprio 0
	s_add_i32 s65, s65, 2
	s_add_u32 s66, s66, 0x100
	s_addc_u32 s67, s67, 0
	s_add_u32 s68, s68, 0x100
	s_addc_u32 s69, s69, 0
	s_cmp_lt_u32 s65, 28
	s_barrier
	s_cbranch_scc1 .LBB0_1105
	v_readfirstlane_b32 s65, v151
	v_lshl_add_u64 v[210:211], v[132:133], 0, s[60:61]
	s_mov_b32 m0, s65
	v_readfirstlane_b32 s65, v152
	ds_read_b128 v[162:165], v153
	ds_read_b128 v[166:169], v153 offset:256
	ds_read_b128 v[170:173], v154
	ds_read_b128 v[174:177], v154 offset:256
	ds_read_b128 v[178:181], v150
	ds_read_b128 v[182:185], v150 offset:1024
	ds_read_b128 v[186:189], v150 offset:2048
	ds_read_b128 v[190:193], v150 offset:3072
	ds_read_b128 v[194:197], v150 offset:4096
	ds_read_b128 v[198:201], v150 offset:5120
	ds_read_b128 v[202:205], v150 offset:6144
	ds_read_b128 v[206:209], v150 offset:7168
	global_load_lds_dwordx4 v[210:211], off
	v_lshl_add_u64 v[132:133], v[132:133], 0, s[62:63]
	s_mov_b32 m0, s65
	s_nop 0
	global_load_lds_dwordx4 v[132:133], off
	s_barrier
	s_waitcnt lgkmcnt(0)
	s_setprio 1
	s_waitcnt lgkmcnt(0)
	v_mfma_f32_16x16x32_bf16 v[124:127], v[162:165], v[178:181], v[124:127]
	v_mfma_f32_16x16x32_bf16 v[116:119], v[162:165], v[186:189], v[116:119]
	v_mfma_f32_16x16x32_bf16 v[108:111], v[162:165], v[194:197], v[108:111]
	v_mfma_f32_16x16x32_bf16 v[100:103], v[162:165], v[202:205], v[100:103]
	v_mfma_f32_16x16x32_bf16 v[124:127], v[170:173], v[182:185], v[124:127]
	v_mfma_f32_16x16x32_bf16 v[120:123], v[166:169], v[178:181], v[120:123]
	v_mfma_f32_16x16x32_bf16 v[116:119], v[170:173], v[190:193], v[116:119]
	v_mfma_f32_16x16x32_bf16 v[112:115], v[166:169], v[186:189], v[112:115]
	v_mfma_f32_16x16x32_bf16 v[108:111], v[170:173], v[198:201], v[108:111]
	v_mfma_f32_16x16x32_bf16 v[104:107], v[166:169], v[194:197], v[104:107]
	v_mfma_f32_16x16x32_bf16 v[100:103], v[170:173], v[206:209], v[100:103]
	v_mfma_f32_16x16x32_bf16 v[96:99], v[166:169], v[202:205], v[96:99]
	v_mfma_f32_16x16x32_bf16 v[210:213], v[174:177], v[182:185], v[120:123]
	v_mfma_f32_16x16x32_bf16 v[214:217], v[174:177], v[190:193], v[112:115]
	v_mfma_f32_16x16x32_bf16 v[218:221], v[174:177], v[198:201], v[104:107]
	v_mfma_f32_16x16x32_bf16 v[222:225], v[174:177], v[206:209], v[96:99]
	s_setprio 0
	s_barrier
; #define LDA(dst, b, h) for (int m = 0; m < 4; ++m) { \
;     dst[m][0] = *reinterpret_cast<const bf16x8*>((char*)SA(b, h) + aoff0 + m * 2048); \
;     dst[m][1] = *reinterpret_cast<const bf16x8*>((char*)SA(b, h) + aoff1 + m * 2048); }
; #define LDB(dst, b, h) for (int n = 0; n < 2; ++n) { \
;     dst[n][0] = *reinterpret_cast<const bf16x8*>((char*)SB(b, h) + boff0 + n * 256); \
;     dst[n][1] = *reinterpret_cast<const bf16x8*>((char*)SB(b, h) + boff1 + n * 256); }
; #define MMA(ai, bj, At, Btf) do { __builtin_amdgcn_s_setprio(1); \
;     for (int m = 0; m < 4; ++m) for (int n = 0; n < 2; ++n) for (int k = 0; k < 2; ++k) \
;       acc[ai][bj][m][n] = __builtin_amdgcn_mfma_f32_16x16x32_bf16(Btf[n][k], At[m][k], acc[ai][bj][m][n], 0, 0, 0); \
;     __builtin_amdgcn_s_setprio(0); } while (0)
; #define WAIT_V(n) asm volatile("s_waitcnt vmcnt(" #n ")" ::: "memory")
; #define WAIT_L(n) asm volatile("s_waitcnt lgkmcnt(" #n ")" ::: "memory")
; #define BAR __builtin_amdgcn_s_barrier()
; template <int EPI> ...
;     ...
;     LDB(B1, 0, 1); BAR; WAIT_L(0); MMA(0, 1, At, B1); BAR;
;     LDA(At, 0, 1); WAIT_V(4); BAR; WAIT_L(0); MMA(1, 0, At, B0); MMA(1, 1, At, B1); BAR; }
;   { LDB(B0, 1, 0); LDA(At, 1, 0); WAIT_V(2); BAR; WAIT_L(0); MMA(0, 0, At, B0); BAR;
	s_nop 1
	ds_read_b128 v[96:99], v155
	ds_read_b128 v[104:107], v155 offset:256
	ds_read_b128 v[112:115], v156
	ds_read_b128 v[120:123], v156 offset:256
	s_barrier
	s_waitcnt lgkmcnt(0)
	s_setprio 1
	s_waitcnt lgkmcnt(0)
	v_mfma_f32_16x16x32_bf16 v[92:95], v[96:99], v[178:181], v[92:95]
	v_mfma_f32_16x16x32_bf16 v[84:87], v[96:99], v[186:189], v[84:87]
	v_mfma_f32_16x16x32_bf16 v[76:79], v[96:99], v[194:197], v[76:79]
	v_mfma_f32_16x16x32_bf16 v[68:71], v[96:99], v[202:205], v[68:71]
	v_mfma_f32_16x16x32_bf16 v[92:95], v[112:115], v[182:185], v[92:95]
	v_mfma_f32_16x16x32_bf16 v[88:91], v[104:107], v[178:181], v[88:91]
	v_mfma_f32_16x16x32_bf16 v[84:87], v[112:115], v[190:193], v[84:87]
	v_mfma_f32_16x16x32_bf16 v[80:83], v[104:107], v[186:189], v[80:83]
	v_mfma_f32_16x16x32_bf16 v[76:79], v[112:115], v[198:201], v[76:79]
	v_mfma_f32_16x16x32_bf16 v[72:75], v[104:107], v[194:197], v[72:75]
	v_mfma_f32_16x16x32_bf16 v[68:71], v[112:115], v[206:209], v[68:71]
	v_mfma_f32_16x16x32_bf16 v[64:67], v[104:107], v[202:205], v[64:67]
	v_mfma_f32_16x16x32_bf16 v[178:181], v[120:123], v[182:185], v[88:91]
	v_mfma_f32_16x16x32_bf16 v[182:185], v[120:123], v[190:193], v[80:83]
	v_mfma_f32_16x16x32_bf16 v[186:189], v[120:123], v[198:201], v[72:75]
	v_mfma_f32_16x16x32_bf16 v[190:193], v[120:123], v[206:209], v[64:67]
	s_setprio 0
	s_barrier
	s_nop 1
	ds_read_b128 v[64:67], v150 offset:16384
	ds_read_b128 v[72:75], v150 offset:17408
	ds_read_b128 v[80:83], v150 offset:18432
	ds_read_b128 v[88:91], v150 offset:19456
	ds_read_b128 v[194:197], v150 offset:20480
	ds_read_b128 v[198:201], v150 offset:21504
	ds_read_b128 v[202:205], v150 offset:22528
	ds_read_b128 v[206:209], v150 offset:23552
	s_waitcnt vmcnt(4)
	s_barrier
	s_waitcnt lgkmcnt(0)
	s_setprio 1
	s_waitcnt lgkmcnt(0)
	v_mfma_f32_16x16x32_bf16 v[60:63], v[162:165], v[64:67], v[60:63]
	v_mfma_f32_16x16x32_bf16 v[56:59], v[166:169], v[64:67], v[56:59]
	v_mfma_f32_16x16x32_bf16 v[52:55], v[162:165], v[80:83], v[52:55]
	v_mfma_f32_16x16x32_bf16 v[40:43], v[166:169], v[194:197], v[40:43]
	v_mfma_f32_16x16x32_bf16 v[36:39], v[162:165], v[202:205], v[36:39]
	v_mfma_f32_16x16x32_bf16 v[60:63], v[170:173], v[72:75], v[60:63]
	v_mfma_f32_16x16x32_bf16 v[56:59], v[174:177], v[72:75], v[56:59]
	v_mfma_f32_16x16x32_bf16 v[52:55], v[170:173], v[88:91], v[52:55]
	v_mfma_f32_16x16x32_bf16 v[48:51], v[166:169], v[80:83], v[48:51]
	v_mfma_f32_16x16x32_bf16 v[44:47], v[162:165], v[194:197], v[44:47]
	v_mfma_f32_16x16x32_bf16 v[40:43], v[174:177], v[198:201], v[40:43]
	v_mfma_f32_16x16x32_bf16 v[36:39], v[170:173], v[206:209], v[36:39]
	v_mfma_f32_16x16x32_bf16 v[32:35], v[166:169], v[202:205], v[32:35]
	v_mfma_f32_16x16x32_bf16 v[226:229], v[174:177], v[88:91], v[48:51]
	v_mfma_f32_16x16x32_bf16 v[230:233], v[170:173], v[198:201], v[44:47]
	v_mfma_f32_16x16x32_bf16 v[162:165], v[174:177], v[206:209], v[32:35]
	s_setprio 0
	s_setprio 1
	v_mfma_f32_16x16x32_bf16 v[24:27], v[104:107], v[64:67], v[24:27]
	v_mfma_f32_16x16x32_bf16 v[20:23], v[96:99], v[80:83], v[20:23]
	v_mfma_f32_16x16x32_bf16 v[8:11], v[104:107], v[194:197], v[8:11]
	v_mfma_f32_16x16x32_bf16 v[4:7], v[96:99], v[202:205], v[4:7]
	v_mfma_f32_16x16x32_bf16 v[28:31], v[96:99], v[64:67], v[28:31]
	v_mfma_f32_16x16x32_bf16 v[24:27], v[120:123], v[72:75], v[24:27]
	v_mfma_f32_16x16x32_bf16 v[20:23], v[112:115], v[88:91], v[20:23]
	v_mfma_f32_16x16x32_bf16 v[16:19], v[104:107], v[80:83], v[16:19]
	v_mfma_f32_16x16x32_bf16 v[12:15], v[96:99], v[194:197], v[12:15]
	v_mfma_f32_16x16x32_bf16 v[8:11], v[120:123], v[198:201], v[8:11]
	v_mfma_f32_16x16x32_bf16 v[4:7], v[112:115], v[206:209], v[4:7]
	v_mfma_f32_16x16x32_bf16 v[0:3], v[104:107], v[202:205], v[0:3]
	v_mfma_f32_16x16x32_bf16 v[166:169], v[112:115], v[72:75], v[28:31]
	v_mfma_f32_16x16x32_bf16 v[170:173], v[120:123], v[88:91], v[16:19]
	v_mfma_f32_16x16x32_bf16 v[174:177], v[112:115], v[198:201], v[12:15]
	v_mfma_f32_16x16x32_bf16 v[194:197], v[120:123], v[206:209], v[0:3]
	s_setprio 0
	s_barrier
	s_nop 1
	ds_read_b128 v[0:3], v157
	ds_read_b128 v[198:201], v157 offset:256
	ds_read_b128 v[12:15], v158
	ds_read_b128 v[202:205], v158 offset:256
	ds_read_b128 v[16:19], v150 offset:32768
	ds_read_b128 v[28:31], v150 offset:33792
	ds_read_b128 v[32:35], v150 offset:34816
	ds_read_b128 v[44:47], v150 offset:35840
	ds_read_b128 v[48:51], v150 offset:36864
	ds_read_b128 v[206:209], v150 offset:37888
	ds_read_b128 v[234:237], v150 offset:38912
	ds_read_b128 v[238:241], v150 offset:39936
	s_waitcnt vmcnt(2)
	s_barrier
; #define LDA(dst, b, h) for (int m = 0; m < 4; ++m) { \
;     dst[m][0] = *reinterpret_cast<const bf16x8*>((char*)SA(b, h) + aoff0 + m * 2048); \
;     dst[m][1] = *reinterpret_cast<const bf16x8*>((char*)SA(b, h) + aoff1 + m * 2048); }
; #define LDB(dst, b, h) for (int n = 0; n < 2; ++n) { \
;     dst[n][0] = *reinterpret_cast<const bf16x8*>((char*)SB(b, h) + boff0 + n * 256); \
;     dst[n][1] = *reinterpret_cast<const bf16x8*>((char*)SB(b, h) + boff1 + n * 256); }
; #define MMA(ai, bj, At, Btf) do { __builtin_amdgcn_s_setprio(1); \
;     for (int m = 0; m < 4; ++m) for (int n = 0; n < 2; ++n) for (int k = 0; k < 2; ++k) \
;       acc[ai][bj][m][n] = __builtin_amdgcn_mfma_f32_16x16x32_bf16(Btf[n][k], At[m][k], acc[ai][bj][m][n], 0, 0, 0); \
;     __builtin_amdgcn_s_setprio(0); } while (0)
; #define WAIT_V(n) asm volatile("s_waitcnt vmcnt(" #n ")" ::: "memory")
; #define WAIT_L(n) asm volatile("s_waitcnt lgkmcnt(" #n ")" ::: "memory")
; #define BAR __builtin_amdgcn_s_barrier()
; template <int EPI> ...
;     ...
;   { LDB(B0, 1, 0); LDA(At, 1, 0); WAIT_V(2); BAR; WAIT_L(0); MMA(0, 0, At, B0); BAR;
;     LDB(B1, 1, 1); WAIT_V(0); BAR; WAIT_L(0); MMA(0, 1, At, B1); BAR;
;     LDA(At, 1, 1); BAR; WAIT_L(0); MMA(1, 0, At, B0); MMA(1, 1, At, B1); BAR; }
;   if (wr == 0) BAR;
	s_waitcnt lgkmcnt(0)
	s_setprio 1
	s_waitcnt lgkmcnt(0)
	v_mfma_f32_16x16x32_bf16 v[64:67], v[0:3], v[16:19], v[124:127]
	v_mfma_f32_16x16x32_bf16 v[120:123], v[12:15], v[28:31], v[64:67]
	v_mfma_f32_16x16x32_bf16 v[64:67], v[198:201], v[16:19], v[210:213]
	v_mfma_f32_16x16x32_bf16 v[112:115], v[202:205], v[28:31], v[64:67]
	v_mfma_f32_16x16x32_bf16 v[64:67], v[0:3], v[32:35], v[116:119]
	v_mfma_f32_16x16x32_bf16 v[104:107], v[12:15], v[44:47], v[64:67]
	v_mfma_f32_16x16x32_bf16 v[64:67], v[198:201], v[32:35], v[214:217]
	v_mfma_f32_16x16x32_bf16 v[96:99], v[202:205], v[44:47], v[64:67]
	v_mfma_f32_16x16x32_bf16 v[64:67], v[0:3], v[48:51], v[108:111]
	v_mfma_f32_16x16x32_bf16 v[88:91], v[12:15], v[206:209], v[64:67]
	v_mfma_f32_16x16x32_bf16 v[64:67], v[198:201], v[48:51], v[218:221]
	v_mfma_f32_16x16x32_bf16 v[80:83], v[202:205], v[206:209], v[64:67]
	v_mfma_f32_16x16x32_bf16 v[64:67], v[0:3], v[234:237], v[100:103]
	v_mfma_f32_16x16x32_bf16 v[72:75], v[12:15], v[238:241], v[64:67]
	v_mfma_f32_16x16x32_bf16 v[64:67], v[198:201], v[234:237], v[222:225]
	v_mfma_f32_16x16x32_bf16 v[64:67], v[202:205], v[238:241], v[64:67]
	s_setprio 0
	s_barrier
	ds_read_b128 v[210:213], v159
	ds_read_b128 v[214:217], v159 offset:256
	ds_read_b128 v[218:221], v160
	ds_read_b128 v[222:225], v160 offset:256
	s_waitcnt vmcnt(0)
	s_barrier
	s_waitcnt lgkmcnt(0)
	s_setprio 1
	s_waitcnt lgkmcnt(0)
	v_mfma_f32_16x16x32_bf16 v[92:95], v[210:213], v[16:19], v[92:95]
	v_mfma_f32_16x16x32_bf16 v[16:19], v[214:217], v[16:19], v[178:181]
	v_mfma_f32_16x16x32_bf16 v[116:119], v[222:225], v[28:31], v[16:19]
	v_mfma_f32_16x16x32_bf16 v[16:19], v[210:213], v[32:35], v[84:87]
	v_mfma_f32_16x16x32_bf16 v[108:111], v[218:221], v[44:47], v[16:19]
	v_mfma_f32_16x16x32_bf16 v[16:19], v[214:217], v[32:35], v[182:185]
	v_mfma_f32_16x16x32_bf16 v[100:103], v[222:225], v[44:47], v[16:19]
	v_mfma_f32_16x16x32_bf16 v[16:19], v[210:213], v[48:51], v[76:79]
	v_mfma_f32_16x16x32_bf16 v[124:127], v[218:221], v[28:31], v[92:95]
	v_mfma_f32_16x16x32_bf16 v[92:95], v[218:221], v[206:209], v[16:19]
	v_mfma_f32_16x16x32_bf16 v[16:19], v[214:217], v[48:51], v[186:189]
	v_mfma_f32_16x16x32_bf16 v[84:87], v[222:225], v[206:209], v[16:19]
	v_mfma_f32_16x16x32_bf16 v[16:19], v[210:213], v[234:237], v[68:71]
	v_mfma_f32_16x16x32_bf16 v[76:79], v[218:221], v[238:241], v[16:19]
	v_mfma_f32_16x16x32_bf16 v[16:19], v[214:217], v[234:237], v[190:193]
	v_mfma_f32_16x16x32_bf16 v[68:71], v[222:225], v[238:241], v[16:19]
	s_setprio 0
	s_barrier
	ds_read_b128 v[178:181], v150 offset:49152
	ds_read_b128 v[182:185], v150 offset:50176
	ds_read_b128 v[186:189], v150 offset:51200
	ds_read_b128 v[190:193], v150 offset:52224
	ds_read_b128 v[206:209], v150 offset:53248
	ds_read_b128 v[234:237], v150 offset:54272
	ds_read_b128 v[238:241], v150 offset:55296
	ds_read_b128 v[242:245], v150 offset:56320
	s_barrier
	s_waitcnt lgkmcnt(0)
	s_setprio 1
	s_waitcnt lgkmcnt(0)
	v_mfma_f32_16x16x32_bf16 v[16:19], v[0:3], v[178:181], v[60:63]
	v_mfma_f32_16x16x32_bf16 v[60:63], v[12:15], v[182:185], v[16:19]
	v_mfma_f32_16x16x32_bf16 v[16:19], v[198:201], v[178:181], v[56:59]
	v_mfma_f32_16x16x32_bf16 v[48:51], v[202:205], v[182:185], v[16:19]
	v_mfma_f32_16x16x32_bf16 v[16:19], v[0:3], v[186:189], v[52:55]
	v_mfma_f32_16x16x32_bf16 v[44:47], v[12:15], v[190:193], v[16:19]
	v_mfma_f32_16x16x32_bf16 v[16:19], v[198:201], v[186:189], v[226:229]
	v_mfma_f32_16x16x32_bf16 v[32:35], v[202:205], v[190:193], v[16:19]
	v_mfma_f32_16x16x32_bf16 v[16:19], v[0:3], v[206:209], v[230:233]
	v_mfma_f32_16x16x32_bf16 v[0:3], v[0:3], v[238:241], v[36:39]
	v_mfma_f32_16x16x32_bf16 v[28:31], v[12:15], v[234:237], v[16:19]
	v_mfma_f32_16x16x32_bf16 v[16:19], v[198:201], v[206:209], v[40:43]
	v_mfma_f32_16x16x32_bf16 v[12:15], v[12:15], v[242:245], v[0:3]
	v_mfma_f32_16x16x32_bf16 v[0:3], v[198:201], v[238:241], v[162:165]
	v_mfma_f32_16x16x32_bf16 v[16:19], v[202:205], v[234:237], v[16:19]
	v_mfma_f32_16x16x32_bf16 v[0:3], v[202:205], v[242:245], v[0:3]
	s_setprio 0
	s_setprio 1
	v_mfma_f32_16x16x32_bf16 v[20:23], v[210:213], v[186:189], v[20:23]
	v_mfma_f32_16x16x32_bf16 v[36:39], v[210:213], v[178:181], v[166:169]
	v_mfma_f32_16x16x32_bf16 v[40:43], v[218:221], v[190:193], v[20:23]
	v_mfma_f32_16x16x32_bf16 v[20:23], v[214:217], v[186:189], v[170:173]
	v_mfma_f32_16x16x32_bf16 v[56:59], v[218:221], v[182:185], v[36:39]
	v_mfma_f32_16x16x32_bf16 v[24:27], v[214:217], v[178:181], v[24:27]
	v_mfma_f32_16x16x32_bf16 v[36:39], v[222:225], v[190:193], v[20:23]
	v_mfma_f32_16x16x32_bf16 v[20:23], v[210:213], v[206:209], v[174:177]
	v_mfma_f32_16x16x32_bf16 v[8:11], v[214:217], v[206:209], v[8:11]
	v_mfma_f32_16x16x32_bf16 v[4:7], v[210:213], v[238:241], v[4:7]
	v_mfma_f32_16x16x32_bf16 v[52:55], v[222:225], v[182:185], v[24:27]
	v_mfma_f32_16x16x32_bf16 v[24:27], v[218:221], v[234:237], v[20:23]
	v_mfma_f32_16x16x32_bf16 v[20:23], v[222:225], v[234:237], v[8:11]
	v_mfma_f32_16x16x32_bf16 v[8:11], v[218:221], v[242:245], v[4:7]
	v_mfma_f32_16x16x32_bf16 v[4:7], v[214:217], v[238:241], v[194:197]
	v_mfma_f32_16x16x32_bf16 v[4:7], v[222:225], v[242:245], v[4:7]
	s_setprio 0
	s_barrier
	s_and_saveexec_b64 s[66:67], s[2:3]
	s_cbranch_execz .LBB0_1099
	s_barrier
	s_branch .LBB0_1099

; #define STAGE(P, BASE, br, kt) do { const char* _gb = (const char*)(BASE) + ((size_t)(br) * K + (size_t)(kt) * BK) * 2; \
;     __builtin_amdgcn_global_load_lds((const unsigned*)(_gb + loff0), (unsigned*)((char*)(P) + tid * 16), 16, 0, 0); \
;     __builtin_amdgcn_global_load_lds((const unsigned*)(_gb + (size_t)K * 128 + loff0), (unsigned*)((char*)(P) + tid * 16 + 8192), 16, 0, 0); } while (0)
; #define LDA(dst, b, h) for (int m = 0; m < 4; ++m) { \
;     dst[m][0] = *reinterpret_cast<const bf16x8*>((char*)SA(b, h) + aoff0 + m * 2048); \
;     dst[m][1] = *reinterpret_cast<const bf16x8*>((char*)SA(b, h) + aoff1 + m * 2048); }
; #define LDB(dst, b, h) for (int n = 0; n < 2; ++n) { \
;     dst[n][0] = *reinterpret_cast<const bf16x8*>((char*)SB(b, h) + boff0 + n * 256); \
;     dst[n][1] = *reinterpret_cast<const bf16x8*>((char*)SB(b, h) + boff1 + n * 256); }
; #define MMA(ai, bj, At, Btf) do { __builtin_amdgcn_s_setprio(1); \
;     for (int m = 0; m < 4; ++m) for (int n = 0; n < 2; ++n) for (int k = 0; k < 2; ++k) \
;       acc[ai][bj][m][n] = __builtin_amdgcn_mfma_f32_16x16x32_bf16(Btf[n][k], At[m][k], acc[ai][bj][m][n], 0, 0, 0); \
;     __builtin_amdgcn_s_setprio(0); } while (0)
; #define WAIT_V(n) asm volatile("s_waitcnt vmcnt(" #n ")" ::: "memory")
; #define WAIT_L(n) asm volatile("s_waitcnt lgkmcnt(" #n ")" ::: "memory")
; #define BAR __builtin_amdgcn_s_barrier()
; #define SCHED __builtin_amdgcn_sched_barrier(0)
; template <int EPI> ...
;     ...
;   WAIT_V(4); BAR;
;   STAGE(SB(1, 0), Bt, bcol, 1); STAGE(SA(1, 0), A, brow, 1); STAGE(SB(1, 1), Bt, bcol + HALF, 1);
;   WAIT_V(6); BAR;
;   for (int t = 0; t < nt - 2; t += 2) {
;     LDB(B0, 0, 0); SCHED; LDA(At, 0, 0); STAGE(SA(1, 1), A, brow + HALF, t + 1);
;     WAIT_L(8); BAR; WAIT_L(0); MMA(0, 0, At, B0); BAR; SCHED;
;     LDB(B1, 0, 1); STAGE(SB(0, 0), Bt, bcol, t + 2);
;     BAR; WAIT_L(0); MMA(0, 1, At, B1); BAR;
;     LDA(At, 0, 1); STAGE(SA(0, 0), A, brow, t + 2);
;     BAR; WAIT_L(0); MMA(1, 0, At, B0); BAR; SCHED;
;     STAGE(SB(0, 1), Bt, bcol + HALF, t + 2);
;     WAIT_V(6); BAR; MMA(1, 1, At, B1); BAR;
.LBB0_1151:
	s_or_b64 exec, exec, s[62:63]
	v_readfirstlane_b32 s62, v143
	v_lshl_add_u64 v[6:7], v[0:1], 0, s[10:11]
	s_mov_b32 m0, s62
	v_readfirstlane_b32 s62, v144
	s_waitcnt vmcnt(2)
	s_barrier
	global_load_lds_dwordx4 v[6:7], off
	v_lshl_add_u64 v[0:1], v[0:1], 0, s[12:13]
	s_mov_b32 m0, s62
	v_readfirstlane_b32 s62, v145
	global_load_lds_dwordx4 v[0:1], off
	v_lshl_add_u64 v[0:1], v[2:3], 0, s[10:11]
	s_mov_b32 m0, s62
	v_readfirstlane_b32 s62, v146
	global_load_lds_dwordx4 v[0:1], off
	v_lshl_add_u64 v[0:1], v[2:3], 0, s[12:13]
	s_mov_b32 m0, s62
	v_readfirstlane_b32 s62, v147
	global_load_lds_dwordx4 v[0:1], off
	v_lshl_add_u64 v[0:1], v[4:5], 0, s[10:11]
	s_mov_b32 m0, s62
	v_readfirstlane_b32 s62, v148
	global_load_lds_dwordx4 v[0:1], off
	v_lshl_add_u64 v[0:1], v[4:5], 0, s[12:13]
	s_mov_b32 m0, s62
	s_ashr_i32 s59, s58, 31
	global_load_lds_dwordx4 v[0:1], off
	s_add_u32 s60, s6, s60
	s_addc_u32 s61, s7, s61
	s_add_u32 s62, s6, s75
	s_addc_u32 s63, s7, s74
	s_add_u32 s64, s6, s64
	v_mov_b32_e32 v0, 0
	s_addc_u32 s65, s7, s65
	s_mov_b32 s74, -2
	v_mov_b32_e32 v1, v0
	v_mov_b32_e32 v2, v0
	v_mov_b32_e32 v3, v0
	v_mov_b32_e32 v4, v0
	v_mov_b32_e32 v5, v0
	v_mov_b32_e32 v6, v0
	v_mov_b32_e32 v7, v0
	s_waitcnt vmcnt(6)
	s_barrier
.LBB0_1152:
	ds_read_b128 v[160:163], v152
	ds_read_b128 v[164:167], v152 offset:256
	ds_read_b128 v[168:171], v153
	ds_read_b128 v[172:175], v153 offset:256
	v_lshl_add_u64 v[224:225], s[62:63], 0, v[132:133]
	v_readfirstlane_b32 s75, v150
	v_lshl_add_u64 v[208:209], v[224:225], 0, s[16:17]
	s_mov_b32 m0, s75
	v_readfirstlane_b32 s75, v151
	ds_read_b128 v[176:179], v149
	ds_read_b128 v[180:183], v149 offset:1024
	ds_read_b128 v[184:187], v149 offset:2048
	ds_read_b128 v[188:191], v149 offset:3072
	ds_read_b128 v[192:195], v149 offset:4096
	ds_read_b128 v[196:199], v149 offset:5120
	ds_read_b128 v[200:203], v149 offset:6144
	ds_read_b128 v[204:207], v149 offset:7168
	global_load_lds_dwordx4 v[208:209], off
	v_lshl_add_u64 v[208:209], v[224:225], 0, s[18:19]
	s_mov_b32 m0, s75
	s_nop 0
	global_load_lds_dwordx4 v[208:209], off
	s_waitcnt lgkmcnt(8)
	ds_read_b128 v[208:211], v154
	ds_read_b128 v[212:215], v154 offset:256
	ds_read_b128 v[216:219], v155
	ds_read_b128 v[220:223], v155 offset:256
	s_barrier
	s_waitcnt lgkmcnt(0)
	s_setprio 1
	s_waitcnt lgkmcnt(0)
	v_mfma_f32_16x16x32_bf16 v[124:127], v[160:163], v[176:179], v[124:127]
	v_mfma_f32_16x16x32_bf16 v[120:123], v[164:167], v[176:179], v[120:123]
	v_mfma_f32_16x16x32_bf16 v[116:119], v[160:163], v[184:187], v[116:119]
	v_mfma_f32_16x16x32_bf16 v[112:115], v[164:167], v[184:187], v[112:115]
	v_mfma_f32_16x16x32_bf16 v[108:111], v[160:163], v[192:195], v[108:111]
	v_mfma_f32_16x16x32_bf16 v[104:107], v[164:167], v[192:195], v[104:107]
	v_mfma_f32_16x16x32_bf16 v[100:103], v[160:163], v[200:203], v[100:103]
	v_mfma_f32_16x16x32_bf16 v[96:99], v[164:167], v[200:203], v[96:99]
	v_mfma_f32_16x16x32_bf16 v[124:127], v[168:171], v[180:183], v[124:127]
	v_mfma_f32_16x16x32_bf16 v[120:123], v[172:175], v[180:183], v[120:123]
	v_mfma_f32_16x16x32_bf16 v[116:119], v[168:171], v[188:191], v[116:119]
	v_mfma_f32_16x16x32_bf16 v[112:115], v[172:175], v[188:191], v[112:115]
	v_mfma_f32_16x16x32_bf16 v[108:111], v[168:171], v[196:199], v[108:111]
	v_mfma_f32_16x16x32_bf16 v[104:107], v[172:175], v[196:199], v[104:107]
	v_mfma_f32_16x16x32_bf16 v[100:103], v[168:171], v[204:207], v[100:103]
	v_mfma_f32_16x16x32_bf16 v[96:99], v[172:175], v[204:207], v[96:99]
	s_setprio 0
	s_waitcnt lgkmcnt(0)
	s_setprio 1
	s_waitcnt lgkmcnt(0)
	v_mfma_f32_16x16x32_bf16 v[92:95], v[208:211], v[176:179], v[92:95]
	v_mfma_f32_16x16x32_bf16 v[88:91], v[212:215], v[176:179], v[88:91]
	v_mfma_f32_16x16x32_bf16 v[84:87], v[208:211], v[184:187], v[84:87]
	v_mfma_f32_16x16x32_bf16 v[80:83], v[212:215], v[184:187], v[80:83]
	v_mfma_f32_16x16x32_bf16 v[76:79], v[208:211], v[192:195], v[76:79]
	v_mfma_f32_16x16x32_bf16 v[72:75], v[212:215], v[192:195], v[72:75]
	v_mfma_f32_16x16x32_bf16 v[68:71], v[208:211], v[200:203], v[68:71]
	v_mfma_f32_16x16x32_bf16 v[64:67], v[212:215], v[200:203], v[64:67]
	v_mfma_f32_16x16x32_bf16 v[92:95], v[216:219], v[180:183], v[92:95]
	v_mfma_f32_16x16x32_bf16 v[88:91], v[220:223], v[180:183], v[88:91]
	v_mfma_f32_16x16x32_bf16 v[84:87], v[216:219], v[188:191], v[84:87]
	v_mfma_f32_16x16x32_bf16 v[80:83], v[220:223], v[188:191], v[80:83]
	v_mfma_f32_16x16x32_bf16 v[76:79], v[216:219], v[196:199], v[76:79]
	v_mfma_f32_16x16x32_bf16 v[72:75], v[220:223], v[196:199], v[72:75]
	v_mfma_f32_16x16x32_bf16 v[68:71], v[216:219], v[204:207], v[68:71]
	v_mfma_f32_16x16x32_bf16 v[64:67], v[220:223], v[204:207], v[64:67]
	s_setprio 0
	s_barrier
	v_lshl_add_u64 v[226:227], s[64:65], 0, v[132:133]
	v_readfirstlane_b32 s75, v135
	v_lshl_add_u64 v[228:229], v[226:227], 0, s[20:21]
	s_mov_b32 m0, s75
	v_readfirstlane_b32 s75, v136
	global_load_lds_dwordx4 v[228:229], off
	v_lshl_add_u64 v[228:229], v[226:227], 0, s[22:23]
	s_mov_b32 m0, s75
	s_nop 0
	global_load_lds_dwordx4 v[228:229], off
	v_readfirstlane_b32 s75, v137
	v_lshl_add_u64 v[228:229], v[224:225], 0, s[24:25]
	s_mov_b32 m0, s75
	v_readfirstlane_b32 s75, v138
	ds_read_b128 v[176:179], v149 offset:16384
	ds_read_b128 v[180:183], v149 offset:17408
	ds_read_b128 v[184:187], v149 offset:18432
	ds_read_b128 v[188:191], v149 offset:19456
	ds_read_b128 v[192:195], v149 offset:20480
	ds_read_b128 v[196:199], v149 offset:21504
	ds_read_b128 v[200:203], v149 offset:22528
	ds_read_b128 v[204:207], v149 offset:23552
	global_load_lds_dwordx4 v[228:229], off
	v_lshl_add_u64 v[228:229], v[224:225], 0, s[26:27]
	s_mov_b32 m0, s75
	s_nop 0
	global_load_lds_dwordx4 v[228:229], off
	v_lshl_add_u64 v[228:229], s[60:61], 0, v[132:133]
	v_readfirstlane_b32 s75, v139
	v_lshl_add_u64 v[246:247], v[228:229], 0, s[28:29]
	s_mov_b32 m0, s75
	v_readfirstlane_b32 s75, v140
	global_load_lds_dwordx4 v[246:247], off
	v_lshl_add_u64 v[246:247], v[228:229], 0, s[30:31]
	s_mov_b32 m0, s75
	s_nop 0
	global_load_lds_dwordx4 v[246:247], off
	s_waitcnt vmcnt(6)
	s_barrier
; #define STAGE(P, BASE, br, kt) do { const char* _gb = (const char*)(BASE) + ((size_t)(br) * K + (size_t)(kt) * BK) * 2; \
;     __builtin_amdgcn_global_load_lds((const unsigned*)(_gb + loff0), (unsigned*)((char*)(P) + tid * 16), 16, 0, 0); \
;     __builtin_amdgcn_global_load_lds((const unsigned*)(_gb + (size_t)K * 128 + loff0), (unsigned*)((char*)(P) + tid * 16 + 8192), 16, 0, 0); } while (0)
; #define LDA(dst, b, h) for (int m = 0; m < 4; ++m) { \
;     dst[m][0] = *reinterpret_cast<const bf16x8*>((char*)SA(b, h) + aoff0 + m * 2048); \
;     dst[m][1] = *reinterpret_cast<const bf16x8*>((char*)SA(b, h) + aoff1 + m * 2048); }
; #define LDB(dst, b, h) for (int n = 0; n < 2; ++n) { \
;     dst[n][0] = *reinterpret_cast<const bf16x8*>((char*)SB(b, h) + boff0 + n * 256); \
;     dst[n][1] = *reinterpret_cast<const bf16x8*>((char*)SB(b, h) + boff1 + n * 256); }
; #define MMA(ai, bj, At, Btf) do { __builtin_amdgcn_s_setprio(1); \
;     for (int m = 0; m < 4; ++m) for (int n = 0; n < 2; ++n) for (int k = 0; k < 2; ++k) \
;       acc[ai][bj][m][n] = __builtin_amdgcn_mfma_f32_16x16x32_bf16(Btf[n][k], At[m][k], acc[ai][bj][m][n], 0, 0, 0); \
;     __builtin_amdgcn_s_setprio(0); } while (0)
; #define WAIT_V(n) asm volatile("s_waitcnt vmcnt(" #n ")" ::: "memory")
; #define WAIT_L(n) asm volatile("s_waitcnt lgkmcnt(" #n ")" ::: "memory")
; #define BAR __builtin_amdgcn_s_barrier()
; template <int EPI> ...
;     ...
;   for (int t = 0; t < nt - 2; t += 2) {
;     LDB(B0, 0, 0); SCHED; LDA(At, 0, 0); STAGE(SA(1, 1), A, brow + HALF, t + 1);
;     WAIT_L(8); BAR; WAIT_L(0); MMA(0, 0, At, B0); BAR; SCHED;
;     LDB(B1, 0, 1); STAGE(SB(0, 0), Bt, bcol, t + 2);
;     BAR; WAIT_L(0); MMA(0, 1, At, B1); BAR;
;     LDA(At, 0, 1); STAGE(SA(0, 0), A, brow, t + 2);
;     BAR; WAIT_L(0); MMA(1, 0, At, B0); BAR; SCHED;
;     STAGE(SB(0, 1), Bt, bcol + HALF, t + 2);
;     WAIT_V(6); BAR; MMA(1, 1, At, B1); BAR;
;     LDB(B0, 1, 0); SCHED; LDA(At, 1, 0); STAGE(SA(0, 1), A, brow + HALF, t + 2);
;     WAIT_L(8); BAR; WAIT_L(0); MMA(0, 0, At, B0); BAR; SCHED;
;     LDB(B1, 1, 1); STAGE(SB(1, 0), Bt, bcol, t + 3);
;     BAR; WAIT_L(0); MMA(0, 1, At, B1); BAR;
;     LDA(At, 1, 1); STAGE(SA(1, 0), A, brow, t + 3);
;     BAR; WAIT_L(0); MMA(1, 0, At, B0); BAR; SCHED;
;     STAGE(SB(1, 1), Bt, bcol + HALF, t + 3);
;     WAIT_V(6); BAR; MMA(1, 1, At, B1); BAR;
;   }
	s_waitcnt lgkmcnt(0)
	s_setprio 1
	s_waitcnt lgkmcnt(0)
	v_mfma_f32_16x16x32_bf16 v[60:63], v[160:163], v[176:179], v[60:63]
	v_mfma_f32_16x16x32_bf16 v[56:59], v[164:167], v[176:179], v[56:59]
	v_mfma_f32_16x16x32_bf16 v[52:55], v[160:163], v[184:187], v[52:55]
	v_mfma_f32_16x16x32_bf16 v[48:51], v[164:167], v[184:187], v[48:51]
	v_mfma_f32_16x16x32_bf16 v[44:47], v[160:163], v[192:195], v[44:47]
	v_mfma_f32_16x16x32_bf16 v[40:43], v[164:167], v[192:195], v[40:43]
	v_mfma_f32_16x16x32_bf16 v[36:39], v[160:163], v[200:203], v[36:39]
	v_mfma_f32_16x16x32_bf16 v[32:35], v[164:167], v[200:203], v[32:35]
	v_mfma_f32_16x16x32_bf16 v[60:63], v[168:171], v[180:183], v[60:63]
	v_mfma_f32_16x16x32_bf16 v[56:59], v[172:175], v[180:183], v[56:59]
	v_mfma_f32_16x16x32_bf16 v[52:55], v[168:171], v[188:191], v[52:55]
	v_mfma_f32_16x16x32_bf16 v[48:51], v[172:175], v[188:191], v[48:51]
	v_mfma_f32_16x16x32_bf16 v[44:47], v[168:171], v[196:199], v[44:47]
	v_mfma_f32_16x16x32_bf16 v[40:43], v[172:175], v[196:199], v[40:43]
	v_mfma_f32_16x16x32_bf16 v[36:39], v[168:171], v[204:207], v[36:39]
	v_mfma_f32_16x16x32_bf16 v[32:35], v[172:175], v[204:207], v[32:35]
	s_setprio 0
	s_setprio 1
	v_mfma_f32_16x16x32_bf16 v[28:31], v[208:211], v[176:179], v[28:31]
	v_mfma_f32_16x16x32_bf16 v[24:27], v[212:215], v[176:179], v[24:27]
	v_mfma_f32_16x16x32_bf16 v[20:23], v[208:211], v[184:187], v[20:23]
	v_mfma_f32_16x16x32_bf16 v[16:19], v[212:215], v[184:187], v[16:19]
	v_mfma_f32_16x16x32_bf16 v[12:15], v[208:211], v[192:195], v[12:15]
	v_mfma_f32_16x16x32_bf16 v[8:11], v[212:215], v[192:195], v[8:11]
	v_mfma_f32_16x16x32_bf16 v[4:7], v[208:211], v[200:203], v[4:7]
	v_mfma_f32_16x16x32_bf16 v[0:3], v[212:215], v[200:203], v[0:3]
	v_mfma_f32_16x16x32_bf16 v[28:31], v[216:219], v[180:183], v[28:31]
	v_mfma_f32_16x16x32_bf16 v[24:27], v[220:223], v[180:183], v[24:27]
	v_mfma_f32_16x16x32_bf16 v[20:23], v[216:219], v[188:191], v[20:23]
	v_mfma_f32_16x16x32_bf16 v[16:19], v[220:223], v[188:191], v[16:19]
	v_mfma_f32_16x16x32_bf16 v[12:15], v[216:219], v[196:199], v[12:15]
	v_mfma_f32_16x16x32_bf16 v[8:11], v[220:223], v[196:199], v[8:11]
	v_mfma_f32_16x16x32_bf16 v[4:7], v[216:219], v[204:207], v[4:7]
	v_mfma_f32_16x16x32_bf16 v[0:3], v[220:223], v[204:207], v[0:3]
	s_setprio 0
	s_barrier
	ds_read_b128 v[160:163], v156
	ds_read_b128 v[164:167], v156 offset:256
	ds_read_b128 v[168:171], v157
	ds_read_b128 v[172:175], v157 offset:256
	v_readfirstlane_b32 s75, v141
	v_lshl_add_u64 v[208:209], v[224:225], 0, s[36:37]
	s_mov_b32 m0, s75
	v_readfirstlane_b32 s75, v142
	ds_read_b128 v[176:179], v149 offset:32768
	ds_read_b128 v[180:183], v149 offset:33792
	ds_read_b128 v[184:187], v149 offset:34816
	ds_read_b128 v[188:191], v149 offset:35840
	ds_read_b128 v[192:195], v149 offset:36864
	ds_read_b128 v[196:199], v149 offset:37888
	ds_read_b128 v[200:203], v149 offset:38912
	ds_read_b128 v[204:207], v149 offset:39936
	global_load_lds_dwordx4 v[208:209], off
	v_lshl_add_u64 v[208:209], v[224:225], 0, s[38:39]
	s_mov_b32 m0, s75
	s_nop 0
	global_load_lds_dwordx4 v[208:209], off
	s_waitcnt lgkmcnt(8)
	ds_read_b128 v[208:211], v158
	ds_read_b128 v[212:215], v158 offset:256
	ds_read_b128 v[216:219], v159
	ds_read_b128 v[220:223], v159 offset:256
	s_barrier
	s_waitcnt lgkmcnt(0)
	s_setprio 1
	s_waitcnt lgkmcnt(0)
	v_mfma_f32_16x16x32_bf16 v[124:127], v[160:163], v[176:179], v[124:127]
	v_mfma_f32_16x16x32_bf16 v[120:123], v[164:167], v[176:179], v[120:123]
	v_mfma_f32_16x16x32_bf16 v[116:119], v[160:163], v[184:187], v[116:119]
	v_mfma_f32_16x16x32_bf16 v[112:115], v[164:167], v[184:187], v[112:115]
	v_mfma_f32_16x16x32_bf16 v[108:111], v[160:163], v[192:195], v[108:111]
	v_mfma_f32_16x16x32_bf16 v[104:107], v[164:167], v[192:195], v[104:107]
	v_mfma_f32_16x16x32_bf16 v[100:103], v[160:163], v[200:203], v[100:103]
	v_mfma_f32_16x16x32_bf16 v[96:99], v[164:167], v[200:203], v[96:99]
	v_mfma_f32_16x16x32_bf16 v[124:127], v[168:171], v[180:183], v[124:127]
	v_mfma_f32_16x16x32_bf16 v[120:123], v[172:175], v[180:183], v[120:123]
	v_mfma_f32_16x16x32_bf16 v[116:119], v[168:171], v[188:191], v[116:119]
	v_mfma_f32_16x16x32_bf16 v[112:115], v[172:175], v[188:191], v[112:115]
	v_mfma_f32_16x16x32_bf16 v[108:111], v[168:171], v[196:199], v[108:111]
	v_mfma_f32_16x16x32_bf16 v[104:107], v[172:175], v[196:199], v[104:107]
	v_mfma_f32_16x16x32_bf16 v[100:103], v[168:171], v[204:207], v[100:103]
	v_mfma_f32_16x16x32_bf16 v[96:99], v[172:175], v[204:207], v[96:99]
	s_setprio 0
	s_waitcnt lgkmcnt(0)
	s_setprio 1
	s_waitcnt lgkmcnt(0)
	v_mfma_f32_16x16x32_bf16 v[92:95], v[208:211], v[176:179], v[92:95]
	v_mfma_f32_16x16x32_bf16 v[88:91], v[212:215], v[176:179], v[88:91]
	v_mfma_f32_16x16x32_bf16 v[84:87], v[208:211], v[184:187], v[84:87]
	v_mfma_f32_16x16x32_bf16 v[80:83], v[212:215], v[184:187], v[80:83]
	v_mfma_f32_16x16x32_bf16 v[76:79], v[208:211], v[192:195], v[76:79]
	v_mfma_f32_16x16x32_bf16 v[72:75], v[212:215], v[192:195], v[72:75]
	v_mfma_f32_16x16x32_bf16 v[68:71], v[208:211], v[200:203], v[68:71]
	v_mfma_f32_16x16x32_bf16 v[64:67], v[212:215], v[200:203], v[64:67]
	v_mfma_f32_16x16x32_bf16 v[92:95], v[216:219], v[180:183], v[92:95]
	v_mfma_f32_16x16x32_bf16 v[88:91], v[220:223], v[180:183], v[88:91]
	v_mfma_f32_16x16x32_bf16 v[84:87], v[216:219], v[188:191], v[84:87]
	v_mfma_f32_16x16x32_bf16 v[80:83], v[220:223], v[188:191], v[80:83]
	v_mfma_f32_16x16x32_bf16 v[76:79], v[216:219], v[196:199], v[76:79]
	v_mfma_f32_16x16x32_bf16 v[72:75], v[220:223], v[196:199], v[72:75]
	v_mfma_f32_16x16x32_bf16 v[68:71], v[216:219], v[204:207], v[68:71]
	v_mfma_f32_16x16x32_bf16 v[64:67], v[220:223], v[204:207], v[64:67]
	s_setprio 0
	s_barrier
; #define STAGE(P, BASE, br, kt) do { const char* _gb = (const char*)(BASE) + ((size_t)(br) * K + (size_t)(kt) * BK) * 2; \
;     __builtin_amdgcn_global_load_lds((const unsigned*)(_gb + loff0), (unsigned*)((char*)(P) + tid * 16), 16, 0, 0); \
;     __builtin_amdgcn_global_load_lds((const unsigned*)(_gb + (size_t)K * 128 + loff0), (unsigned*)((char*)(P) + tid * 16 + 8192), 16, 0, 0); } while (0)
; #define LDA(dst, b, h) for (int m = 0; m < 4; ++m) { \
;     dst[m][0] = *reinterpret_cast<const bf16x8*>((char*)SA(b, h) + aoff0 + m * 2048); \
;     dst[m][1] = *reinterpret_cast<const bf16x8*>((char*)SA(b, h) + aoff1 + m * 2048); }
; #define LDB(dst, b, h) for (int n = 0; n < 2; ++n) { \
;     dst[n][0] = *reinterpret_cast<const bf16x8*>((char*)SB(b, h) + boff0 + n * 256); \
;     dst[n][1] = *reinterpret_cast<const bf16x8*>((char*)SB(b, h) + boff1 + n * 256); }
; #define MMA(ai, bj, At, Btf) do { __builtin_amdgcn_s_setprio(1); \
;     for (int m = 0; m < 4; ++m) for (int n = 0; n < 2; ++n) for (int k = 0; k < 2; ++k) \
;       acc[ai][bj][m][n] = __builtin_amdgcn_mfma_f32_16x16x32_bf16(Btf[n][k], At[m][k], acc[ai][bj][m][n], 0, 0, 0); \
;     __builtin_amdgcn_s_setprio(0); } while (0)
; #define WAIT_V(n) asm volatile("s_waitcnt vmcnt(" #n ")" ::: "memory")
; #define WAIT_L(n) asm volatile("s_waitcnt lgkmcnt(" #n ")" ::: "memory")
; #define BAR __builtin_amdgcn_s_barrier()
; #define SCHED __builtin_amdgcn_sched_barrier(0)
; template <int EPI> ...
;     ...
;     LDB(B1, 1, 1); STAGE(SB(1, 0), Bt, bcol, t + 3);
;     BAR; WAIT_L(0); MMA(0, 1, At, B1); BAR;
;     LDA(At, 1, 1); STAGE(SA(1, 0), A, brow, t + 3);
;     BAR; WAIT_L(0); MMA(1, 0, At, B0); BAR; SCHED;
;     STAGE(SB(1, 1), Bt, bcol + HALF, t + 3);
;     WAIT_V(6); BAR; MMA(1, 1, At, B1); BAR;
;   }
;   { LDB(B0, 0, 0); LDA(At, 0, 0); STAGE(SA(1, 1), A, brow + HALF, nt - 1);
;     BAR; WAIT_L(0); MMA(0, 0, At, B0); BAR;
	v_readfirstlane_b32 s75, v143
	v_lshl_add_u64 v[230:231], v[226:227], 0, s[46:47]
	s_mov_b32 m0, s75
	v_readfirstlane_b32 s75, v144
	global_load_lds_dwordx4 v[230:231], off
	v_lshl_add_u64 v[226:227], v[226:227], 0, s[48:49]
	s_mov_b32 m0, s75
	s_nop 0
	global_load_lds_dwordx4 v[226:227], off
	v_readfirstlane_b32 s75, v145
	v_lshl_add_u64 v[226:227], v[224:225], 0, s[50:51]
	s_mov_b32 m0, s75
	v_readfirstlane_b32 s75, v146
	ds_read_b128 v[176:179], v149 offset:49152
	ds_read_b128 v[180:183], v149 offset:50176
	ds_read_b128 v[184:187], v149 offset:51200
	ds_read_b128 v[188:191], v149 offset:52224
	ds_read_b128 v[192:195], v149 offset:53248
	ds_read_b128 v[196:199], v149 offset:54272
	ds_read_b128 v[200:203], v149 offset:55296
	ds_read_b128 v[204:207], v149 offset:56320
	global_load_lds_dwordx4 v[226:227], off
	v_lshl_add_u64 v[224:225], v[224:225], 0, s[52:53]
	s_mov_b32 m0, s75
	s_nop 0
	global_load_lds_dwordx4 v[224:225], off
	v_readfirstlane_b32 s75, v147
	v_lshl_add_u64 v[246:247], v[228:229], 0, s[54:55]
	s_mov_b32 m0, s75
	v_readfirstlane_b32 s75, v148
	global_load_lds_dwordx4 v[246:247], off
	v_lshl_add_u64 v[246:247], v[228:229], 0, s[56:57]
	s_mov_b32 m0, s75
	s_nop 0
	global_load_lds_dwordx4 v[246:247], off
	s_waitcnt vmcnt(6)
	s_barrier
	s_waitcnt lgkmcnt(0)
	s_setprio 1
	s_waitcnt lgkmcnt(0)
	v_mfma_f32_16x16x32_bf16 v[60:63], v[160:163], v[176:179], v[60:63]
	v_mfma_f32_16x16x32_bf16 v[56:59], v[164:167], v[176:179], v[56:59]
	v_mfma_f32_16x16x32_bf16 v[52:55], v[160:163], v[184:187], v[52:55]
	v_mfma_f32_16x16x32_bf16 v[48:51], v[164:167], v[184:187], v[48:51]
	v_mfma_f32_16x16x32_bf16 v[44:47], v[160:163], v[192:195], v[44:47]
	v_mfma_f32_16x16x32_bf16 v[40:43], v[164:167], v[192:195], v[40:43]
	v_mfma_f32_16x16x32_bf16 v[36:39], v[160:163], v[200:203], v[36:39]
	v_mfma_f32_16x16x32_bf16 v[32:35], v[164:167], v[200:203], v[32:35]
	v_mfma_f32_16x16x32_bf16 v[60:63], v[168:171], v[180:183], v[60:63]
	v_mfma_f32_16x16x32_bf16 v[56:59], v[172:175], v[180:183], v[56:59]
	v_mfma_f32_16x16x32_bf16 v[52:55], v[168:171], v[188:191], v[52:55]
	v_mfma_f32_16x16x32_bf16 v[48:51], v[172:175], v[188:191], v[48:51]
	v_mfma_f32_16x16x32_bf16 v[44:47], v[168:171], v[196:199], v[44:47]
	v_mfma_f32_16x16x32_bf16 v[40:43], v[172:175], v[196:199], v[40:43]
	v_mfma_f32_16x16x32_bf16 v[36:39], v[168:171], v[204:207], v[36:39]
	v_mfma_f32_16x16x32_bf16 v[32:35], v[172:175], v[204:207], v[32:35]
	s_setprio 0
	s_setprio 1
	v_mfma_f32_16x16x32_bf16 v[28:31], v[208:211], v[176:179], v[28:31]
	v_mfma_f32_16x16x32_bf16 v[24:27], v[212:215], v[176:179], v[24:27]
	v_mfma_f32_16x16x32_bf16 v[20:23], v[208:211], v[184:187], v[20:23]
	v_mfma_f32_16x16x32_bf16 v[16:19], v[212:215], v[184:187], v[16:19]
	v_mfma_f32_16x16x32_bf16 v[12:15], v[208:211], v[192:195], v[12:15]
	v_mfma_f32_16x16x32_bf16 v[8:11], v[212:215], v[192:195], v[8:11]
	v_mfma_f32_16x16x32_bf16 v[4:7], v[208:211], v[200:203], v[4:7]
	v_mfma_f32_16x16x32_bf16 v[0:3], v[212:215], v[200:203], v[0:3]
	v_mfma_f32_16x16x32_bf16 v[28:31], v[216:219], v[180:183], v[28:31]
	v_mfma_f32_16x16x32_bf16 v[24:27], v[220:223], v[180:183], v[24:27]
	v_mfma_f32_16x16x32_bf16 v[20:23], v[216:219], v[188:191], v[20:23]
	v_mfma_f32_16x16x32_bf16 v[16:19], v[220:223], v[188:191], v[16:19]
	v_mfma_f32_16x16x32_bf16 v[12:15], v[216:219], v[196:199], v[12:15]
	v_mfma_f32_16x16x32_bf16 v[8:11], v[220:223], v[196:199], v[8:11]
	v_mfma_f32_16x16x32_bf16 v[4:7], v[216:219], v[204:207], v[4:7]
	v_mfma_f32_16x16x32_bf16 v[0:3], v[220:223], v[204:207], v[0:3]
	s_setprio 0
	s_add_i32 s74, s74, 2
	s_add_u32 s60, s60, 0x100
	s_addc_u32 s61, s61, 0
	s_add_u32 s62, s62, 0x100
	s_addc_u32 s63, s63, 0
	s_add_u32 s64, s64, 0x100
	s_addc_u32 s65, s65, 0
	s_cmpk_lt_u32 s74, 0x54
	s_barrier
	s_cbranch_scc1 .LBB0_1152
	s_add_u32 s60, s68, s73
	s_addc_u32 s61, s69, s72
	v_lshl_add_u64 v[208:209], s[60:61], 0, v[128:129]
	v_readfirstlane_b32 s60, v150
	s_mov_b32 m0, s60
	v_readfirstlane_b32 s60, v151
	ds_read_b128 v[160:163], v152
	ds_read_b128 v[164:167], v152 offset:256
	ds_read_b128 v[168:171], v153
	ds_read_b128 v[172:175], v153 offset:256
	ds_read_b128 v[176:179], v149
	ds_read_b128 v[180:183], v149 offset:1024
	ds_read_b128 v[184:187], v149 offset:2048
	ds_read_b128 v[188:191], v149 offset:3072
	ds_read_b128 v[192:195], v149 offset:4096
	ds_read_b128 v[196:199], v149 offset:5120
	ds_read_b128 v[200:203], v149 offset:6144
	ds_read_b128 v[204:207], v149 offset:7168
	global_load_lds_dwordx4 v[208:209], off
	v_lshl_add_u64 v[208:209], v[208:209], 0, s[8:9]
	s_mov_b32 m0, s60
	s_nop 0
	global_load_lds_dwordx4 v[208:209], off
	s_barrier
	s_waitcnt lgkmcnt(0)
	s_setprio 1
	s_waitcnt lgkmcnt(0)
	v_mfma_f32_16x16x32_bf16 v[124:127], v[160:163], v[176:179], v[124:127]
	v_mfma_f32_16x16x32_bf16 v[116:119], v[160:163], v[184:187], v[116:119]
	v_mfma_f32_16x16x32_bf16 v[108:111], v[160:163], v[192:195], v[108:111]
	v_mfma_f32_16x16x32_bf16 v[100:103], v[160:163], v[200:203], v[100:103]
	v_mfma_f32_16x16x32_bf16 v[96:99], v[164:167], v[200:203], v[96:99]
	v_mfma_f32_16x16x32_bf16 v[124:127], v[168:171], v[180:183], v[124:127]
	v_mfma_f32_16x16x32_bf16 v[120:123], v[164:167], v[176:179], v[120:123]
	v_mfma_f32_16x16x32_bf16 v[116:119], v[168:171], v[188:191], v[116:119]
	v_mfma_f32_16x16x32_bf16 v[112:115], v[164:167], v[184:187], v[112:115]
	v_mfma_f32_16x16x32_bf16 v[108:111], v[168:171], v[196:199], v[108:111]
	v_mfma_f32_16x16x32_bf16 v[104:107], v[164:167], v[192:195], v[104:107]
	v_mfma_f32_16x16x32_bf16 v[100:103], v[168:171], v[204:207], v[100:103]
	v_mfma_f32_16x16x32_bf16 v[96:99], v[172:175], v[204:207], v[96:99]
	v_mfma_f32_16x16x32_bf16 v[208:211], v[172:175], v[180:183], v[120:123]
	v_mfma_f32_16x16x32_bf16 v[212:215], v[172:175], v[188:191], v[112:115]
	v_mfma_f32_16x16x32_bf16 v[216:219], v[172:175], v[196:199], v[104:107]
	s_setprio 0
	s_barrier
; #define LDA(dst, b, h) for (int m = 0; m < 4; ++m) { \
;     dst[m][0] = *reinterpret_cast<const bf16x8*>((char*)SA(b, h) + aoff0 + m * 2048); \
;     dst[m][1] = *reinterpret_cast<const bf16x8*>((char*)SA(b, h) + aoff1 + m * 2048); }
; #define LDB(dst, b, h) for (int n = 0; n < 2; ++n) { \
;     dst[n][0] = *reinterpret_cast<const bf16x8*>((char*)SB(b, h) + boff0 + n * 256); \
;     dst[n][1] = *reinterpret_cast<const bf16x8*>((char*)SB(b, h) + boff1 + n * 256); }
; #define MMA(ai, bj, At, Btf) do { __builtin_amdgcn_s_setprio(1); \
;     for (int m = 0; m < 4; ++m) for (int n = 0; n < 2; ++n) for (int k = 0; k < 2; ++k) \
;       acc[ai][bj][m][n] = __builtin_amdgcn_mfma_f32_16x16x32_bf16(Btf[n][k], At[m][k], acc[ai][bj][m][n], 0, 0, 0); \
;     __builtin_amdgcn_s_setprio(0); } while (0)
; #define WAIT_V(n) asm volatile("s_waitcnt vmcnt(" #n ")" ::: "memory")
; #define WAIT_L(n) asm volatile("s_waitcnt lgkmcnt(" #n ")" ::: "memory")
; #define BAR __builtin_amdgcn_s_barrier()
; template <int EPI> ...
;     ...
;     BAR; WAIT_L(0); MMA(0, 0, At, B0); BAR;
;     LDB(B1, 0, 1); BAR; WAIT_L(0); MMA(0, 1, At, B1); BAR;
;     LDA(At, 0, 1); WAIT_V(4); BAR; WAIT_L(0); MMA(1, 0, At, B0); MMA(1, 1, At, B1); BAR; }
;   { LDB(B0, 1, 0); LDA(At, 1, 0); WAIT_V(2); BAR; WAIT_L(0); MMA(0, 0, At, B0); BAR;
	s_nop 0
	ds_read_b128 v[104:107], v154
	ds_read_b128 v[112:115], v154 offset:256
	ds_read_b128 v[120:123], v155
	ds_read_b128 v[220:223], v155 offset:256
	s_barrier
	s_waitcnt lgkmcnt(0)
	s_setprio 1
	s_waitcnt lgkmcnt(0)
	v_mfma_f32_16x16x32_bf16 v[84:87], v[104:107], v[184:187], v[84:87]
	v_mfma_f32_16x16x32_bf16 v[76:79], v[104:107], v[192:195], v[76:79]
	v_mfma_f32_16x16x32_bf16 v[72:75], v[112:115], v[192:195], v[72:75]
	v_mfma_f32_16x16x32_bf16 v[92:95], v[104:107], v[176:179], v[92:95]
	v_mfma_f32_16x16x32_bf16 v[88:91], v[112:115], v[176:179], v[88:91]
	v_mfma_f32_16x16x32_bf16 v[84:87], v[120:123], v[188:191], v[84:87]
	v_mfma_f32_16x16x32_bf16 v[80:83], v[112:115], v[184:187], v[80:83]
	v_mfma_f32_16x16x32_bf16 v[76:79], v[120:123], v[196:199], v[76:79]
	v_mfma_f32_16x16x32_bf16 v[72:75], v[220:223], v[196:199], v[72:75]
	v_mfma_f32_16x16x32_bf16 v[68:71], v[104:107], v[200:203], v[68:71]
	v_mfma_f32_16x16x32_bf16 v[64:67], v[112:115], v[200:203], v[64:67]
	v_mfma_f32_16x16x32_bf16 v[224:227], v[120:123], v[180:183], v[92:95]
	v_mfma_f32_16x16x32_bf16 v[176:179], v[220:223], v[180:183], v[88:91]
	v_mfma_f32_16x16x32_bf16 v[180:183], v[220:223], v[188:191], v[80:83]
	v_mfma_f32_16x16x32_bf16 v[184:187], v[120:123], v[204:207], v[68:71]
	v_mfma_f32_16x16x32_bf16 v[188:191], v[220:223], v[204:207], v[64:67]
	s_setprio 0
	s_barrier
	s_nop 0
	ds_read_b128 v[64:67], v149 offset:16384
	ds_read_b128 v[68:71], v149 offset:17408
	ds_read_b128 v[80:83], v149 offset:18432
	ds_read_b128 v[88:91], v149 offset:19456
	ds_read_b128 v[92:95], v149 offset:20480
	ds_read_b128 v[192:195], v149 offset:21504
	ds_read_b128 v[196:199], v149 offset:22528
	ds_read_b128 v[200:203], v149 offset:23552
	s_waitcnt vmcnt(4)
	s_barrier
	s_waitcnt lgkmcnt(0)
	s_setprio 1
	s_waitcnt lgkmcnt(0)
	v_mfma_f32_16x16x32_bf16 v[52:55], v[160:163], v[80:83], v[52:55]
	v_mfma_f32_16x16x32_bf16 v[44:47], v[160:163], v[92:95], v[44:47]
	v_mfma_f32_16x16x32_bf16 v[36:39], v[160:163], v[196:199], v[36:39]
	v_mfma_f32_16x16x32_bf16 v[60:63], v[160:163], v[64:67], v[60:63]
	v_mfma_f32_16x16x32_bf16 v[56:59], v[164:167], v[64:67], v[56:59]
	v_mfma_f32_16x16x32_bf16 v[52:55], v[168:171], v[88:91], v[52:55]
	v_mfma_f32_16x16x32_bf16 v[48:51], v[164:167], v[80:83], v[48:51]
	v_mfma_f32_16x16x32_bf16 v[44:47], v[168:171], v[192:195], v[44:47]
	v_mfma_f32_16x16x32_bf16 v[40:43], v[164:167], v[92:95], v[40:43]
	v_mfma_f32_16x16x32_bf16 v[36:39], v[168:171], v[200:203], v[36:39]
	v_mfma_f32_16x16x32_bf16 v[32:35], v[164:167], v[196:199], v[32:35]
	v_mfma_f32_16x16x32_bf16 v[204:207], v[168:171], v[68:71], v[60:63]
	v_mfma_f32_16x16x32_bf16 v[228:231], v[172:175], v[68:71], v[56:59]
	v_mfma_f32_16x16x32_bf16 v[232:235], v[172:175], v[88:91], v[48:51]
	v_mfma_f32_16x16x32_bf16 v[236:239], v[172:175], v[192:195], v[40:43]
	v_mfma_f32_16x16x32_bf16 v[160:163], v[172:175], v[200:203], v[32:35]
	s_setprio 0
	s_setprio 1
	v_mfma_f32_16x16x32_bf16 v[28:31], v[104:107], v[64:67], v[28:31]
	v_mfma_f32_16x16x32_bf16 v[20:23], v[104:107], v[80:83], v[20:23]
	v_mfma_f32_16x16x32_bf16 v[12:15], v[104:107], v[92:95], v[12:15]
	v_mfma_f32_16x16x32_bf16 v[4:7], v[104:107], v[196:199], v[4:7]
	v_mfma_f32_16x16x32_bf16 v[28:31], v[120:123], v[68:71], v[28:31]
	v_mfma_f32_16x16x32_bf16 v[24:27], v[112:115], v[64:67], v[24:27]
	v_mfma_f32_16x16x32_bf16 v[20:23], v[120:123], v[88:91], v[20:23]
	v_mfma_f32_16x16x32_bf16 v[16:19], v[112:115], v[80:83], v[16:19]
	v_mfma_f32_16x16x32_bf16 v[12:15], v[120:123], v[192:195], v[12:15]
	v_mfma_f32_16x16x32_bf16 v[8:11], v[112:115], v[92:95], v[8:11]
	v_mfma_f32_16x16x32_bf16 v[4:7], v[120:123], v[200:203], v[4:7]
	v_mfma_f32_16x16x32_bf16 v[0:3], v[112:115], v[196:199], v[0:3]
	v_mfma_f32_16x16x32_bf16 v[164:167], v[220:223], v[68:71], v[24:27]
	v_mfma_f32_16x16x32_bf16 v[168:171], v[220:223], v[88:91], v[16:19]
	v_mfma_f32_16x16x32_bf16 v[172:175], v[220:223], v[192:195], v[8:11]
	v_mfma_f32_16x16x32_bf16 v[192:195], v[220:223], v[200:203], v[0:3]
	s_setprio 0
	s_barrier
	s_nop 1
	ds_read_b128 v[0:3], v156
	ds_read_b128 v[8:11], v156 offset:256
	ds_read_b128 v[16:19], v157
	ds_read_b128 v[24:27], v157 offset:256
	ds_read_b128 v[32:35], v149 offset:32768
	ds_read_b128 v[40:43], v149 offset:33792
	ds_read_b128 v[48:51], v149 offset:34816
	ds_read_b128 v[56:59], v149 offset:35840
	ds_read_b128 v[60:63], v149 offset:36864
	ds_read_b128 v[68:71], v149 offset:37888
	ds_read_b128 v[196:199], v149 offset:38912
	ds_read_b128 v[200:203], v149 offset:39936
	s_waitcnt vmcnt(2)
	s_barrier
; #define LDA(dst, b, h) for (int m = 0; m < 4; ++m) { \
;     dst[m][0] = *reinterpret_cast<const bf16x8*>((char*)SA(b, h) + aoff0 + m * 2048); \
;     dst[m][1] = *reinterpret_cast<const bf16x8*>((char*)SA(b, h) + aoff1 + m * 2048); }
; #define LDB(dst, b, h) for (int n = 0; n < 2; ++n) { \
;     dst[n][0] = *reinterpret_cast<const bf16x8*>((char*)SB(b, h) + boff0 + n * 256); \
;     dst[n][1] = *reinterpret_cast<const bf16x8*>((char*)SB(b, h) + boff1 + n * 256); }
; #define MMA(ai, bj, At, Btf) do { __builtin_amdgcn_s_setprio(1); \
;     for (int m = 0; m < 4; ++m) for (int n = 0; n < 2; ++n) for (int k = 0; k < 2; ++k) \
;       acc[ai][bj][m][n] = __builtin_amdgcn_mfma_f32_16x16x32_bf16(Btf[n][k], At[m][k], acc[ai][bj][m][n], 0, 0, 0); \
;     __builtin_amdgcn_s_setprio(0); } while (0)
; #define WAIT_V(n) asm volatile("s_waitcnt vmcnt(" #n ")" ::: "memory")
; #define WAIT_L(n) asm volatile("s_waitcnt lgkmcnt(" #n ")" ::: "memory")
; #define BAR __builtin_amdgcn_s_barrier()
; template <int EPI> ...
;     ...
;   { LDB(B0, 1, 0); LDA(At, 1, 0); WAIT_V(2); BAR; WAIT_L(0); MMA(0, 0, At, B0); BAR;
;     LDB(B1, 1, 1); WAIT_V(0); BAR; WAIT_L(0); MMA(0, 1, At, B1); BAR;
;     LDA(At, 1, 1); BAR; WAIT_L(0); MMA(1, 0, At, B0); MMA(1, 1, At, B1); BAR; }
;   if (wr == 0) BAR;
	s_waitcnt lgkmcnt(0)
	s_setprio 1
	s_waitcnt lgkmcnt(0)
	v_mfma_f32_16x16x32_bf16 v[64:67], v[0:3], v[32:35], v[124:127]
	v_mfma_f32_16x16x32_bf16 v[120:123], v[16:19], v[40:43], v[64:67]
	v_mfma_f32_16x16x32_bf16 v[64:67], v[8:11], v[32:35], v[208:211]
	v_mfma_f32_16x16x32_bf16 v[124:127], v[24:27], v[40:43], v[64:67]
	v_mfma_f32_16x16x32_bf16 v[64:67], v[0:3], v[48:51], v[116:119]
	v_mfma_f32_16x16x32_bf16 v[112:115], v[16:19], v[56:59], v[64:67]
	v_mfma_f32_16x16x32_bf16 v[64:67], v[8:11], v[48:51], v[212:215]
	v_mfma_f32_16x16x32_bf16 v[116:119], v[24:27], v[56:59], v[64:67]
	v_mfma_f32_16x16x32_bf16 v[64:67], v[0:3], v[60:63], v[108:111]
	v_mfma_f32_16x16x32_bf16 v[104:107], v[16:19], v[68:71], v[64:67]
	v_mfma_f32_16x16x32_bf16 v[64:67], v[8:11], v[60:63], v[216:219]
	v_mfma_f32_16x16x32_bf16 v[108:111], v[24:27], v[68:71], v[64:67]
	v_mfma_f32_16x16x32_bf16 v[64:67], v[0:3], v[196:199], v[100:103]
	v_mfma_f32_16x16x32_bf16 v[88:91], v[16:19], v[200:203], v[64:67]
	v_mfma_f32_16x16x32_bf16 v[64:67], v[8:11], v[196:199], v[96:99]
	v_mfma_f32_16x16x32_bf16 v[92:95], v[24:27], v[200:203], v[64:67]
	s_setprio 0
	s_barrier
	ds_read_b128 v[208:211], v158
	ds_read_b128 v[212:215], v158 offset:256
	ds_read_b128 v[216:219], v159
	ds_read_b128 v[220:223], v159 offset:256
	s_waitcnt vmcnt(0)
	s_barrier
	s_waitcnt lgkmcnt(0)
	s_setprio 1
	s_waitcnt lgkmcnt(0)
	v_mfma_f32_16x16x32_bf16 v[64:67], v[208:211], v[32:35], v[224:227]
	v_mfma_f32_16x16x32_bf16 v[32:35], v[212:215], v[32:35], v[176:179]
	v_mfma_f32_16x16x32_bf16 v[100:103], v[220:223], v[40:43], v[32:35]
	v_mfma_f32_16x16x32_bf16 v[32:35], v[208:211], v[48:51], v[84:87]
	v_mfma_f32_16x16x32_bf16 v[80:83], v[216:219], v[56:59], v[32:35]
	v_mfma_f32_16x16x32_bf16 v[32:35], v[212:215], v[48:51], v[180:183]
	v_mfma_f32_16x16x32_bf16 v[84:87], v[220:223], v[56:59], v[32:35]
	v_mfma_f32_16x16x32_bf16 v[32:35], v[208:211], v[60:63], v[76:79]
	v_mfma_f32_16x16x32_bf16 v[96:99], v[216:219], v[40:43], v[64:67]
	v_mfma_f32_16x16x32_bf16 v[64:67], v[216:219], v[68:71], v[32:35]
	v_mfma_f32_16x16x32_bf16 v[32:35], v[212:215], v[60:63], v[72:75]
	v_mfma_f32_16x16x32_bf16 v[68:71], v[220:223], v[68:71], v[32:35]
	v_mfma_f32_16x16x32_bf16 v[32:35], v[208:211], v[196:199], v[184:187]
	v_mfma_f32_16x16x32_bf16 v[56:59], v[216:219], v[200:203], v[32:35]
	v_mfma_f32_16x16x32_bf16 v[32:35], v[212:215], v[196:199], v[188:191]
	v_mfma_f32_16x16x32_bf16 v[60:63], v[220:223], v[200:203], v[32:35]
	s_setprio 0
	s_barrier
	ds_read_b128 v[176:179], v149 offset:49152
	ds_read_b128 v[180:183], v149 offset:50176
	ds_read_b128 v[184:187], v149 offset:51200
	ds_read_b128 v[188:191], v149 offset:52224
	ds_read_b128 v[196:199], v149 offset:53248
	ds_read_b128 v[200:203], v149 offset:54272
	ds_read_b128 v[224:227], v149 offset:55296
	ds_read_b128 v[240:243], v149 offset:56320
	s_barrier
	s_waitcnt lgkmcnt(0)
	s_setprio 1
	s_waitcnt lgkmcnt(0)
	v_mfma_f32_16x16x32_bf16 v[32:35], v[0:3], v[176:179], v[204:207]
	v_mfma_f32_16x16x32_bf16 v[72:75], v[16:19], v[180:183], v[32:35]
	v_mfma_f32_16x16x32_bf16 v[32:35], v[8:11], v[176:179], v[228:231]
	v_mfma_f32_16x16x32_bf16 v[76:79], v[24:27], v[180:183], v[32:35]
	v_mfma_f32_16x16x32_bf16 v[32:35], v[0:3], v[184:187], v[52:55]
	v_mfma_f32_16x16x32_bf16 v[48:51], v[16:19], v[188:191], v[32:35]
	v_mfma_f32_16x16x32_bf16 v[32:35], v[8:11], v[184:187], v[232:235]
	v_mfma_f32_16x16x32_bf16 v[52:55], v[24:27], v[188:191], v[32:35]
	v_mfma_f32_16x16x32_bf16 v[32:35], v[0:3], v[196:199], v[44:47]
	v_mfma_f32_16x16x32_bf16 v[40:43], v[16:19], v[200:203], v[32:35]
	v_mfma_f32_16x16x32_bf16 v[32:35], v[8:11], v[196:199], v[236:239]
	v_mfma_f32_16x16x32_bf16 v[0:3], v[0:3], v[224:227], v[36:39]
	v_mfma_f32_16x16x32_bf16 v[44:47], v[24:27], v[200:203], v[32:35]
	v_mfma_f32_16x16x32_bf16 v[32:35], v[16:19], v[240:243], v[0:3]
	v_mfma_f32_16x16x32_bf16 v[0:3], v[8:11], v[224:227], v[160:163]
	v_mfma_f32_16x16x32_bf16 v[36:39], v[24:27], v[240:243], v[0:3]
	s_setprio 0
	s_setprio 1
	v_mfma_f32_16x16x32_bf16 v[0:3], v[208:211], v[176:179], v[28:31]
	v_mfma_f32_16x16x32_bf16 v[24:27], v[216:219], v[180:183], v[0:3]
	v_mfma_f32_16x16x32_bf16 v[0:3], v[212:215], v[176:179], v[164:167]
	v_mfma_f32_16x16x32_bf16 v[28:31], v[220:223], v[180:183], v[0:3]
	v_mfma_f32_16x16x32_bf16 v[0:3], v[208:211], v[184:187], v[20:23]
	v_mfma_f32_16x16x32_bf16 v[16:19], v[216:219], v[188:191], v[0:3]
	v_mfma_f32_16x16x32_bf16 v[0:3], v[212:215], v[184:187], v[168:171]
	v_mfma_f32_16x16x32_bf16 v[20:23], v[220:223], v[188:191], v[0:3]
	v_mfma_f32_16x16x32_bf16 v[0:3], v[208:211], v[196:199], v[12:15]
	v_mfma_f32_16x16x32_bf16 v[8:11], v[216:219], v[200:203], v[0:3]
	v_mfma_f32_16x16x32_bf16 v[0:3], v[212:215], v[196:199], v[172:175]
	v_mfma_f32_16x16x32_bf16 v[12:15], v[220:223], v[200:203], v[0:3]
	v_mfma_f32_16x16x32_bf16 v[0:3], v[208:211], v[224:227], v[4:7]
	v_mfma_f32_16x16x32_bf16 v[4:7], v[212:215], v[224:227], v[192:195]
	v_mfma_f32_16x16x32_bf16 v[0:3], v[216:219], v[240:243], v[0:3]
	v_mfma_f32_16x16x32_bf16 v[4:7], v[220:223], v[240:243], v[4:7]
	s_setprio 0
	s_barrier
	s_and_saveexec_b64 s[60:61], s[2:3]
	s_cbranch_execz .LBB0_1146
	s_barrier
	s_branch .LBB0_1146
